# GEMM K loops (in-proj, ff1, ff2): fragment reads issue right after the barrier, prefetch loads spread into the gaps of the first eight MFMAs
# speedup vs baseline: 1.0298x; 1.0035x over previous
; template <class Epi, class ColV>
; DI void gemm_tile(const bf16_t* __restrict__ A, int lda, const bf16_t* __restrict__ Bt, int ldb, int K, int m0, int n0, unsigned char* smem, Epi epi, ColV colv, const bf16_t* __restrict__ HYT = nullptr) {
;     ...
;     auto step = [&](int kt, u32x4 (&ldset)[8], const u32x4 (&stset)[8]) {
;         const int buf = kt & 1;
;         if (kt + 2 < nk) gload(ldset, kt + 2);
;         const bf16_t* Ab = As + (buf * 128 + 64 * wr + li) * LS + 8 * lh;
;         const bf16_t* Bb = Bs + (buf * 128 + 64 * wc + li) * LS + 8 * lh;
;         bf16x8 fa[2][2], fb[2][2], ga[2][2], gb[2][2];
; #pragma unroll
;         for (int k2 = 0; k2 < 2; ++k2) { fa[k2][0] = ld8(Ab + 16 * k2); fa[k2][1] = ld8(Ab + 32 * LS + 16 * k2); fb[k2][0] = ld8(Bb + 16 * k2); fb[k2][1] = ld8(Bb + 32 * LS + 16 * k2); }
;         __builtin_amdgcn_sched_barrier(0);
; #pragma unroll
;         for (int k2 = 0; k2 < 2; ++k2) {
;             acc[0][0] = MFMA(fa[k2][0], fb[k2][0], acc[0][0]); acc[0][1] = MFMA(fa[k2][0], fb[k2][1], acc[0][1]);
;             acc[1][0] = MFMA(fa[k2][1], fb[k2][0], acc[1][0]); acc[1][1] = MFMA(fa[k2][1], fb[k2][1], acc[1][1]);
;         }
; #pragma unroll
;         for (int k2 = 0; k2 < 2; ++k2) { const int ks = 2 + k2; ga[k2][0] = ld8(Ab + 16 * ks); ga[k2][1] = ld8(Ab + 32 * LS + 16 * ks); gb[k2][0] = ld8(Bb + 16 * ks); gb[k2][1] = ld8(Bb + 32 * LS + 16 * ks); }
; #pragma unroll
;         for (int k2 = 0; k2 < 2; ++k2) {
;             acc[0][0] = MFMA(ga[k2][0], gb[k2][0], acc[0][0]); acc[0][1] = MFMA(ga[k2][0], gb[k2][1], acc[0][1]);
;             acc[1][0] = MFMA(ga[k2][1], gb[k2][0], acc[1][0]); acc[1][1] = MFMA(ga[k2][1], gb[k2][1], acc[1][1]);
;         }
;         if (kt + 1 < nk) sstore(stset, buf ^ 1, kt + 1);
; #pragma unroll
;         for (int i = 0; i < 8; ++i) { __builtin_amdgcn_sched_group_barrier(0x008, 1, 0); __builtin_amdgcn_sched_group_barrier(0x100, 1, 0); }
; #pragma unroll
;         for (int i = 0; i < 8; ++i) { __builtin_amdgcn_sched_group_barrier(0x008, 1, 0); __builtin_amdgcn_sched_group_barrier(0x200, 1, 0); }
;         __builtin_amdgcn_sched_barrier(0);
;         __syncthreads();
;     ...
;         XCD_TILE_LOOP(NL / 128, 8, tm, tn) gemm_tile((const bf16_t*)(p.ws + WS_HID), 4096, (const bf16_t*)(p.ws + wbase(layer) + W_FF2), 4096, 4096, tm * 128, tn * 128, smem, epi, gate);
.Lg3_phase11:
	ds_read_b128 v[174:177], v194
	ds_read_b128 v[178:181], v194 offset:32
	ds_read_b128 v[202:205], v194 offset:4608
	ds_read_b128 v[206:209], v194 offset:4640
	ds_read_b128 v[210:213], v195 offset:36864
	ds_read_b128 v[214:217], v195 offset:36896
	ds_read_b128 v[218:221], v195 offset:41472
	ds_read_b128 v[222:225], v195 offset:41504
	s_waitcnt lgkmcnt(3)
	v_mfma_f32_32x32x16_bf16 v[52:67], v[174:177], v[210:213], v[52:67]
	global_load_dwordx4 v[68:71], v[164:165], off offset:384
	s_waitcnt lgkmcnt(1)
	v_mfma_f32_32x32x16_bf16 v[36:51], v[174:177], v[218:221], v[36:51]
	global_load_dwordx4 v[72:75], v[162:163], off offset:384
	v_mfma_f32_32x32x16_bf16 v[4:19], v[202:205], v[218:221], v[4:19]
	global_load_dwordx4 v[76:79], v[160:161], off offset:384
	s_waitcnt lgkmcnt(0)
	v_mfma_f32_32x32x16_bf16 v[36:51], v[178:181], v[222:225], v[36:51]
	global_load_dwordx4 v[80:83], v[158:159], off offset:384
	v_mfma_f32_32x32x16_bf16 v[4:19], v[206:209], v[222:225], v[4:19]
	global_load_dwordx4 v[84:87], v[156:157], off offset:384
	ds_read_b128 v[222:225], v195 offset:41568
	ds_read_b128 v[174:177], v194 offset:4672
	v_mfma_f32_32x32x16_bf16 v[20:35], v[202:205], v[210:213], v[20:35]
	global_load_dwordx4 v[92:95], v[154:155], off offset:384
	ds_read_b128 v[210:213], v194 offset:4704
	ds_read_b128 v[202:205], v194 offset:64
	v_mfma_f32_32x32x16_bf16 v[52:67], v[178:181], v[214:217], v[52:67]
	global_load_dwordx4 v[104:107], v[152:153], off offset:384
	ds_read_b128 v[218:221], v195 offset:36960
	ds_read_b128 v[178:181], v195 offset:41536
	v_mfma_f32_32x32x16_bf16 v[20:35], v[206:209], v[214:217], v[20:35]
	global_load_dwordx4 v[112:115], v[146:147], off offset:384
	ds_read_b128 v[214:217], v195 offset:36928
	ds_read_b128 v[206:209], v194 offset:96
	s_waitcnt lgkmcnt(1)
	v_mfma_f32_32x32x16_bf16 v[52:67], v[202:205], v[214:217], v[52:67]
	s_waitcnt vmcnt(23)
	ds_write_b128 v190, v[88:91] offset:18432
	v_mfma_f32_32x32x16_bf16 v[36:51], v[202:205], v[178:181], v[36:51]
	s_waitcnt vmcnt(22)
	ds_write_b128 v190, v[96:99] offset:55296
	v_mfma_f32_32x32x16_bf16 v[20:35], v[174:177], v[214:217], v[20:35]
	s_waitcnt vmcnt(21)
	ds_write_b128 v191, v[100:103] offset:18432
	v_mfma_f32_32x32x16_bf16 v[4:19], v[174:177], v[178:181], v[4:19]
	s_waitcnt vmcnt(20)
	ds_write_b128 v191, v[108:111] offset:55296
	s_waitcnt lgkmcnt(4)
	v_mfma_f32_32x32x16_bf16 v[52:67], v[206:209], v[218:221], v[52:67]
	s_waitcnt vmcnt(19)
	ds_write_b128 v192, v[116:119] offset:18432
	v_mfma_f32_32x32x16_bf16 v[36:51], v[206:209], v[222:225], v[36:51]
	s_waitcnt vmcnt(18)
	ds_write_b128 v192, v[120:123] offset:55296
	v_mfma_f32_32x32x16_bf16 v[20:35], v[210:213], v[218:221], v[20:35]
	s_waitcnt vmcnt(17)
	ds_write_b128 v193, v[124:127] offset:18432
	v_mfma_f32_32x32x16_bf16 v[4:19], v[210:213], v[222:225], v[4:19]
	s_waitcnt vmcnt(16)
	ds_write_b128 v193, v[128:131] offset:55296
	s_waitcnt lgkmcnt(0)
	s_barrier
	ds_read_b128 v[174:177], v196
	ds_read_b128 v[178:181], v196 offset:32
	ds_read_b128 v[202:205], v196 offset:4608
	ds_read_b128 v[206:209], v196 offset:4640
	ds_read_b128 v[210:213], v197 offset:36864
	ds_read_b128 v[214:217], v197 offset:36896
	ds_read_b128 v[218:221], v197 offset:41472
	ds_read_b128 v[222:225], v197 offset:41504
	s_waitcnt lgkmcnt(3)
	v_mfma_f32_32x32x16_bf16 v[52:67], v[174:177], v[210:213], v[52:67]
	global_load_dwordx4 v[88:91], v[164:165], off offset:512
	s_waitcnt lgkmcnt(1)
	v_mfma_f32_32x32x16_bf16 v[36:51], v[174:177], v[218:221], v[36:51]
	global_load_dwordx4 v[96:99], v[162:163], off offset:512
	v_mfma_f32_32x32x16_bf16 v[4:19], v[202:205], v[218:221], v[4:19]
	global_load_dwordx4 v[100:103], v[160:161], off offset:512
	s_waitcnt lgkmcnt(0)
	v_mfma_f32_32x32x16_bf16 v[36:51], v[178:181], v[222:225], v[36:51]
	global_load_dwordx4 v[108:111], v[158:159], off offset:512
	v_mfma_f32_32x32x16_bf16 v[4:19], v[206:209], v[222:225], v[4:19]
	global_load_dwordx4 v[116:119], v[156:157], off offset:512
	ds_read_b128 v[222:225], v197 offset:41568
	ds_read_b128 v[174:177], v196 offset:4672
	v_mfma_f32_32x32x16_bf16 v[20:35], v[202:205], v[210:213], v[20:35]
	global_load_dwordx4 v[120:123], v[154:155], off offset:512
	ds_read_b128 v[210:213], v196 offset:4704
	ds_read_b128 v[202:205], v196 offset:64
	v_mfma_f32_32x32x16_bf16 v[52:67], v[178:181], v[214:217], v[52:67]
	global_load_dwordx4 v[124:127], v[152:153], off offset:512
	ds_read_b128 v[218:221], v197 offset:36960
	ds_read_b128 v[178:181], v197 offset:41536
	v_mfma_f32_32x32x16_bf16 v[20:35], v[206:209], v[214:217], v[20:35]
	global_load_dwordx4 v[128:131], v[146:147], off offset:512
	ds_read_b128 v[214:217], v197 offset:36928
	ds_read_b128 v[206:209], v196 offset:96
	s_waitcnt lgkmcnt(1)
	v_mfma_f32_32x32x16_bf16 v[52:67], v[202:205], v[214:217], v[52:67]
	s_waitcnt vmcnt(23)
	ds_write_b128 v190, v[132:135]
	v_mfma_f32_32x32x16_bf16 v[36:51], v[202:205], v[178:181], v[36:51]
	s_waitcnt vmcnt(22)
	ds_write_b128 v190, v[136:139] offset:36864
	v_mfma_f32_32x32x16_bf16 v[20:35], v[174:177], v[214:217], v[20:35]
	s_waitcnt vmcnt(21)
	ds_write_b128 v191, v[140:143]
	v_mfma_f32_32x32x16_bf16 v[4:19], v[174:177], v[178:181], v[4:19]
	s_waitcnt vmcnt(20)
	ds_write_b128 v191, v[198:201] offset:36864
	s_waitcnt lgkmcnt(4)
	v_mfma_f32_32x32x16_bf16 v[52:67], v[206:209], v[218:221], v[52:67]
	s_waitcnt vmcnt(19)
	ds_write_b128 v192, v[226:229]
	v_mfma_f32_32x32x16_bf16 v[36:51], v[206:209], v[222:225], v[36:51]
	s_waitcnt vmcnt(18)
	ds_write_b128 v192, v[230:233] offset:36864
	v_mfma_f32_32x32x16_bf16 v[20:35], v[210:213], v[218:221], v[20:35]
	s_waitcnt vmcnt(17)
	ds_write_b128 v193, v[242:245]
	v_mfma_f32_32x32x16_bf16 v[4:19], v[210:213], v[222:225], v[4:19]
	s_waitcnt vmcnt(16)
	ds_write_b128 v193, v[246:249] offset:36864
	s_waitcnt lgkmcnt(0)
	s_barrier
; #define MFMA(a, b, c) __builtin_amdgcn_mfma_f32_32x32x16_bf16((a), (b), (c), 0, 0, 0)
; template <class Epi, class ColV>
; DI void gemm_tile(const bf16_t* __restrict__ A, int lda, const bf16_t* __restrict__ Bt, int ldb, int K, int m0, int n0, unsigned char* smem, Epi epi, ColV colv, const bf16_t* __restrict__ HYT = nullptr) {
;     ...
;     auto gload = [&](u32x4 (&r)[8], int kt) {
; #pragma unroll
;         for (int i = 0; i < 4; ++i) { int id = tid + 256 * i, row = id >> 3, kc = id & 7;
;             if (HYT && kt >= 12) r[i] = *(const u32x4*)(HYT + (size_t)((kt - 12) * 64 + (id >> 4)) * NT + m0 + (id & 15) * 8);
;             else r[i] = *(const u32x4*)(A + (size_t)(m0 + row) * lda + kt * 64 + kc * 8);
;             r[4 + i] = *(const u32x4*)(Bt + (size_t)(n0 + row) * ldb + kt * 64 + kc * 8); }
;     };
;     auto sstore = [&](const u32x4 (&r)[8], int buf, int kt) {
; #pragma unroll
;         for (int i = 0; i < 4; ++i) { int id = tid + 256 * i, row = id >> 3, kc = id & 7;
;             if (HYT && kt >= 12) { const int kk = id >> 4, rr = (id & 15) * 8; bf16_t* d = As + (buf * 128 + rr) * LS + kk; const bf16x8 v = __builtin_bit_cast(bf16x8, r[i]);
; #pragma unroll
;                 for (int e = 0; e < 8; ++e) d[e * LS] = (bf16_t)v[e]; }
;             else *(u32x4*)(As + (buf * 128 + row) * LS + kc * 8) = r[i];
;             *(u32x4*)(Bs + (buf * 128 + row) * LS + kc * 8) = r[4 + i]; }
;     };
;     auto step = [&](int kt, u32x4 (&ldset)[8], const u32x4 (&stset)[8]) {
;         const int buf = kt & 1;
;         if (kt + 2 < nk) gload(ldset, kt + 2);
;         const bf16_t* Ab = As + (buf * 128 + 64 * wr + li) * LS + 8 * lh;
;         const bf16_t* Bb = Bs + (buf * 128 + 64 * wc + li) * LS + 8 * lh;
;         bf16x8 fa[2][2], fb[2][2], ga[2][2], gb[2][2];
; #pragma unroll
;         for (int k2 = 0; k2 < 2; ++k2) { fa[k2][0] = ld8(Ab + 16 * k2); fa[k2][1] = ld8(Ab + 32 * LS + 16 * k2); fb[k2][0] = ld8(Bb + 16 * k2); fb[k2][1] = ld8(Bb + 32 * LS + 16 * k2); }
;         __builtin_amdgcn_sched_barrier(0);
; #pragma unroll
;         for (int k2 = 0; k2 < 2; ++k2) {
;             acc[0][0] = MFMA(fa[k2][0], fb[k2][0], acc[0][0]); acc[0][1] = MFMA(fa[k2][0], fb[k2][1], acc[0][1]);
;             acc[1][0] = MFMA(fa[k2][1], fb[k2][0], acc[1][0]); acc[1][1] = MFMA(fa[k2][1], fb[k2][1], acc[1][1]);
;         }
; #pragma unroll
	ds_read_b128 v[174:177], v194
	ds_read_b128 v[178:181], v194 offset:32
	ds_read_b128 v[202:205], v194 offset:4608
	ds_read_b128 v[206:209], v194 offset:4640
	ds_read_b128 v[210:213], v195 offset:36864
	ds_read_b128 v[214:217], v195 offset:36896
	ds_read_b128 v[218:221], v195 offset:41472
	ds_read_b128 v[222:225], v195 offset:41504
	s_waitcnt lgkmcnt(3)
	v_mfma_f32_32x32x16_bf16 v[52:67], v[174:177], v[210:213], v[52:67]
	global_load_dwordx4 v[132:135], v[164:165], off offset:640
	s_waitcnt lgkmcnt(1)
	v_mfma_f32_32x32x16_bf16 v[36:51], v[174:177], v[218:221], v[36:51]
	global_load_dwordx4 v[136:139], v[162:163], off offset:640
	v_mfma_f32_32x32x16_bf16 v[4:19], v[202:205], v[218:221], v[4:19]
	global_load_dwordx4 v[140:143], v[160:161], off offset:640
	s_waitcnt lgkmcnt(0)
	v_mfma_f32_32x32x16_bf16 v[36:51], v[178:181], v[222:225], v[36:51]
	global_load_dwordx4 v[198:201], v[158:159], off offset:640
	v_mfma_f32_32x32x16_bf16 v[4:19], v[206:209], v[222:225], v[4:19]
	global_load_dwordx4 v[226:229], v[156:157], off offset:640
	ds_read_b128 v[222:225], v195 offset:41568
	ds_read_b128 v[174:177], v194 offset:4672
	v_mfma_f32_32x32x16_bf16 v[20:35], v[202:205], v[210:213], v[20:35]
	global_load_dwordx4 v[230:233], v[154:155], off offset:640
	ds_read_b128 v[210:213], v194 offset:4704
	ds_read_b128 v[202:205], v194 offset:64
	v_mfma_f32_32x32x16_bf16 v[52:67], v[178:181], v[214:217], v[52:67]
	global_load_dwordx4 v[242:245], v[152:153], off offset:640
	ds_read_b128 v[218:221], v195 offset:36960
	ds_read_b128 v[178:181], v195 offset:41536
	v_mfma_f32_32x32x16_bf16 v[20:35], v[206:209], v[214:217], v[20:35]
	global_load_dwordx4 v[246:249], v[146:147], off offset:640
	ds_read_b128 v[214:217], v195 offset:36928
	ds_read_b128 v[206:209], v194 offset:96
	s_waitcnt lgkmcnt(1)
	v_mfma_f32_32x32x16_bf16 v[52:67], v[202:205], v[214:217], v[52:67]
	s_waitcnt vmcnt(23)
	ds_write_b128 v190, v[68:71] offset:18432
	v_mfma_f32_32x32x16_bf16 v[36:51], v[202:205], v[178:181], v[36:51]
	s_waitcnt vmcnt(22)
	ds_write_b128 v190, v[72:75] offset:55296
	v_mfma_f32_32x32x16_bf16 v[20:35], v[174:177], v[214:217], v[20:35]
	s_waitcnt vmcnt(21)
	ds_write_b128 v191, v[76:79] offset:18432
	v_mfma_f32_32x32x16_bf16 v[4:19], v[174:177], v[178:181], v[4:19]
	s_waitcnt vmcnt(20)
	ds_write_b128 v191, v[80:83] offset:55296
	s_waitcnt lgkmcnt(4)
	v_mfma_f32_32x32x16_bf16 v[52:67], v[206:209], v[218:221], v[52:67]
	s_waitcnt vmcnt(19)
	ds_write_b128 v192, v[84:87] offset:18432
	v_mfma_f32_32x32x16_bf16 v[36:51], v[206:209], v[222:225], v[36:51]
	s_waitcnt vmcnt(18)
	ds_write_b128 v192, v[92:95] offset:55296
	v_mfma_f32_32x32x16_bf16 v[20:35], v[210:213], v[218:221], v[20:35]
	s_waitcnt vmcnt(17)
	ds_write_b128 v193, v[104:107] offset:18432
	v_mfma_f32_32x32x16_bf16 v[4:19], v[210:213], v[222:225], v[4:19]
	s_waitcnt vmcnt(16)
	ds_write_b128 v193, v[112:115] offset:55296
	s_waitcnt lgkmcnt(0)
	s_barrier
	ds_read_b128 v[174:177], v196
	ds_read_b128 v[178:181], v196 offset:32
	ds_read_b128 v[202:205], v196 offset:4608
	ds_read_b128 v[206:209], v196 offset:4640
	ds_read_b128 v[210:213], v197 offset:36864
	ds_read_b128 v[214:217], v197 offset:36896
	ds_read_b128 v[218:221], v197 offset:41472
	ds_read_b128 v[222:225], v197 offset:41504
	s_waitcnt lgkmcnt(3)
	v_mfma_f32_32x32x16_bf16 v[52:67], v[174:177], v[210:213], v[52:67]
	global_load_dwordx4 v[68:71], v[164:165], off offset:768
	s_waitcnt lgkmcnt(1)
	v_mfma_f32_32x32x16_bf16 v[36:51], v[174:177], v[218:221], v[36:51]
	global_load_dwordx4 v[72:75], v[162:163], off offset:768
	v_mfma_f32_32x32x16_bf16 v[4:19], v[202:205], v[218:221], v[4:19]
	global_load_dwordx4 v[76:79], v[160:161], off offset:768
	s_waitcnt lgkmcnt(0)
	v_mfma_f32_32x32x16_bf16 v[36:51], v[178:181], v[222:225], v[36:51]
	global_load_dwordx4 v[80:83], v[158:159], off offset:768
	v_mfma_f32_32x32x16_bf16 v[4:19], v[206:209], v[222:225], v[4:19]
	global_load_dwordx4 v[84:87], v[156:157], off offset:768
	ds_read_b128 v[222:225], v197 offset:41568
	ds_read_b128 v[174:177], v196 offset:4672
	v_mfma_f32_32x32x16_bf16 v[20:35], v[202:205], v[210:213], v[20:35]
	global_load_dwordx4 v[92:95], v[154:155], off offset:768
	ds_read_b128 v[210:213], v196 offset:4704
	ds_read_b128 v[202:205], v196 offset:64
	v_mfma_f32_32x32x16_bf16 v[52:67], v[178:181], v[214:217], v[52:67]
	global_load_dwordx4 v[104:107], v[152:153], off offset:768
	ds_read_b128 v[218:221], v197 offset:36960
	ds_read_b128 v[178:181], v197 offset:41536
	v_mfma_f32_32x32x16_bf16 v[20:35], v[206:209], v[214:217], v[20:35]
	global_load_dwordx4 v[112:115], v[146:147], off offset:768
	ds_read_b128 v[214:217], v197 offset:36928
	ds_read_b128 v[206:209], v196 offset:96
	s_waitcnt lgkmcnt(1)
	v_mfma_f32_32x32x16_bf16 v[52:67], v[202:205], v[214:217], v[52:67]
	s_waitcnt vmcnt(23)
	ds_write_b128 v190, v[88:91]
	v_mfma_f32_32x32x16_bf16 v[36:51], v[202:205], v[178:181], v[36:51]
	s_waitcnt vmcnt(22)
	ds_write_b128 v190, v[96:99] offset:36864
	v_mfma_f32_32x32x16_bf16 v[20:35], v[174:177], v[214:217], v[20:35]
	s_waitcnt vmcnt(21)
	ds_write_b128 v191, v[100:103]
	v_mfma_f32_32x32x16_bf16 v[4:19], v[174:177], v[178:181], v[4:19]
	s_waitcnt vmcnt(20)
	ds_write_b128 v191, v[108:111] offset:36864
	s_waitcnt lgkmcnt(4)
	v_mfma_f32_32x32x16_bf16 v[52:67], v[206:209], v[218:221], v[52:67]
	s_waitcnt vmcnt(19)
	ds_write_b128 v192, v[116:119]
	v_mfma_f32_32x32x16_bf16 v[36:51], v[206:209], v[222:225], v[36:51]
	s_waitcnt vmcnt(18)
	ds_write_b128 v192, v[120:123] offset:36864
	v_mfma_f32_32x32x16_bf16 v[20:35], v[210:213], v[218:221], v[20:35]
	s_waitcnt vmcnt(17)
	ds_write_b128 v193, v[124:127]
	v_mfma_f32_32x32x16_bf16 v[4:19], v[210:213], v[222:225], v[4:19]
	s_waitcnt vmcnt(16)
	ds_write_b128 v193, v[128:131] offset:36864
	s_waitcnt lgkmcnt(0)
	s_barrier
; #define MFMA(a, b, c) __builtin_amdgcn_mfma_f32_32x32x16_bf16((a), (b), (c), 0, 0, 0)
; template <class Epi, class ColV>
; DI void gemm_tile(const bf16_t* __restrict__ A, int lda, const bf16_t* __restrict__ Bt, int ldb, int K, int m0, int n0, unsigned char* smem, Epi epi, ColV colv, const bf16_t* __restrict__ HYT = nullptr) {
;     ...
;     auto gload = [&](u32x4 (&r)[8], int kt) {
; #pragma unroll
;         for (int i = 0; i < 4; ++i) { int id = tid + 256 * i, row = id >> 3, kc = id & 7;
;             if (HYT && kt >= 12) r[i] = *(const u32x4*)(HYT + (size_t)((kt - 12) * 64 + (id >> 4)) * NT + m0 + (id & 15) * 8);
;             else r[i] = *(const u32x4*)(A + (size_t)(m0 + row) * lda + kt * 64 + kc * 8);
;             r[4 + i] = *(const u32x4*)(Bt + (size_t)(n0 + row) * ldb + kt * 64 + kc * 8); }
;     };
;     auto sstore = [&](const u32x4 (&r)[8], int buf, int kt) {
; #pragma unroll
;         for (int i = 0; i < 4; ++i) { int id = tid + 256 * i, row = id >> 3, kc = id & 7;
;             if (HYT && kt >= 12) { const int kk = id >> 4, rr = (id & 15) * 8; bf16_t* d = As + (buf * 128 + rr) * LS + kk; const bf16x8 v = __builtin_bit_cast(bf16x8, r[i]);
; #pragma unroll
;                 for (int e = 0; e < 8; ++e) d[e * LS] = (bf16_t)v[e]; }
;             else *(u32x4*)(As + (buf * 128 + row) * LS + kc * 8) = r[i];
;             *(u32x4*)(Bs + (buf * 128 + row) * LS + kc * 8) = r[4 + i]; }
;     };
;     auto step = [&](int kt, u32x4 (&ldset)[8], const u32x4 (&stset)[8]) {
;         const int buf = kt & 1;
;         if (kt + 2 < nk) gload(ldset, kt + 2);
;         const bf16_t* Ab = As + (buf * 128 + 64 * wr + li) * LS + 8 * lh;
;         const bf16_t* Bb = Bs + (buf * 128 + 64 * wc + li) * LS + 8 * lh;
;         bf16x8 fa[2][2], fb[2][2], ga[2][2], gb[2][2];
; #pragma unroll
;         for (int k2 = 0; k2 < 2; ++k2) { fa[k2][0] = ld8(Ab + 16 * k2); fa[k2][1] = ld8(Ab + 32 * LS + 16 * k2); fb[k2][0] = ld8(Bb + 16 * k2); fb[k2][1] = ld8(Bb + 32 * LS + 16 * k2); }
;         __builtin_amdgcn_sched_barrier(0);
; #pragma unroll
;         for (int k2 = 0; k2 < 2; ++k2) {
;             acc[0][0] = MFMA(fa[k2][0], fb[k2][0], acc[0][0]); acc[0][1] = MFMA(fa[k2][0], fb[k2][1], acc[0][1]);
;             acc[1][0] = MFMA(fa[k2][1], fb[k2][0], acc[1][0]); acc[1][1] = MFMA(fa[k2][1], fb[k2][1], acc[1][1]);
;         }
; #pragma unroll
	ds_read_b128 v[174:177], v194
	ds_read_b128 v[178:181], v194 offset:32
	ds_read_b128 v[202:205], v194 offset:4608
	ds_read_b128 v[206:209], v194 offset:4640
	ds_read_b128 v[210:213], v195 offset:36864
	ds_read_b128 v[214:217], v195 offset:36896
	ds_read_b128 v[218:221], v195 offset:41472
	ds_read_b128 v[222:225], v195 offset:41504
	s_waitcnt lgkmcnt(3)
	v_mfma_f32_32x32x16_bf16 v[52:67], v[174:177], v[210:213], v[52:67]
	global_load_dwordx4 v[88:91], v[164:165], off offset:896
	s_waitcnt lgkmcnt(1)
	v_mfma_f32_32x32x16_bf16 v[36:51], v[174:177], v[218:221], v[36:51]
	global_load_dwordx4 v[96:99], v[162:163], off offset:896
	v_mfma_f32_32x32x16_bf16 v[4:19], v[202:205], v[218:221], v[4:19]
	global_load_dwordx4 v[100:103], v[160:161], off offset:896
	s_waitcnt lgkmcnt(0)
	v_mfma_f32_32x32x16_bf16 v[36:51], v[178:181], v[222:225], v[36:51]
	global_load_dwordx4 v[108:111], v[158:159], off offset:896
	v_mfma_f32_32x32x16_bf16 v[4:19], v[206:209], v[222:225], v[4:19]
	global_load_dwordx4 v[116:119], v[156:157], off offset:896
	ds_read_b128 v[222:225], v195 offset:41568
	ds_read_b128 v[174:177], v194 offset:4672
	v_mfma_f32_32x32x16_bf16 v[20:35], v[202:205], v[210:213], v[20:35]
	global_load_dwordx4 v[120:123], v[154:155], off offset:896
	ds_read_b128 v[210:213], v194 offset:4704
	ds_read_b128 v[202:205], v194 offset:64
	v_mfma_f32_32x32x16_bf16 v[52:67], v[178:181], v[214:217], v[52:67]
	global_load_dwordx4 v[124:127], v[152:153], off offset:896
	ds_read_b128 v[218:221], v195 offset:36960
	ds_read_b128 v[178:181], v195 offset:41536
	v_mfma_f32_32x32x16_bf16 v[20:35], v[206:209], v[214:217], v[20:35]
	global_load_dwordx4 v[128:131], v[146:147], off offset:896
	ds_read_b128 v[214:217], v195 offset:36928
	ds_read_b128 v[206:209], v194 offset:96
	s_waitcnt lgkmcnt(1)
	v_mfma_f32_32x32x16_bf16 v[52:67], v[202:205], v[214:217], v[52:67]
	s_waitcnt vmcnt(23)
	ds_write_b128 v190, v[132:135] offset:18432
	v_mfma_f32_32x32x16_bf16 v[36:51], v[202:205], v[178:181], v[36:51]
	s_waitcnt vmcnt(22)
	ds_write_b128 v190, v[136:139] offset:55296
	v_mfma_f32_32x32x16_bf16 v[20:35], v[174:177], v[214:217], v[20:35]
	s_waitcnt vmcnt(21)
	ds_write_b128 v191, v[140:143] offset:18432
	v_mfma_f32_32x32x16_bf16 v[4:19], v[174:177], v[178:181], v[4:19]
	s_waitcnt vmcnt(20)
	ds_write_b128 v191, v[198:201] offset:55296
	s_waitcnt lgkmcnt(4)
	v_mfma_f32_32x32x16_bf16 v[52:67], v[206:209], v[218:221], v[52:67]
	s_waitcnt vmcnt(19)
	ds_write_b128 v192, v[226:229] offset:18432
	v_mfma_f32_32x32x16_bf16 v[36:51], v[206:209], v[222:225], v[36:51]
	s_waitcnt vmcnt(18)
	ds_write_b128 v192, v[230:233] offset:55296
	v_mfma_f32_32x32x16_bf16 v[20:35], v[210:213], v[218:221], v[20:35]
	s_waitcnt vmcnt(17)
	ds_write_b128 v193, v[242:245] offset:18432
	v_mfma_f32_32x32x16_bf16 v[4:19], v[210:213], v[222:225], v[4:19]
	s_waitcnt vmcnt(16)
	ds_write_b128 v193, v[246:249] offset:55296
	s_waitcnt lgkmcnt(0)
	s_barrier
	ds_read_b128 v[174:177], v196
	ds_read_b128 v[178:181], v196 offset:32
	ds_read_b128 v[202:205], v196 offset:4608
	ds_read_b128 v[206:209], v196 offset:4640
	ds_read_b128 v[210:213], v197 offset:36864
	ds_read_b128 v[214:217], v197 offset:36896
	ds_read_b128 v[218:221], v197 offset:41472
	ds_read_b128 v[222:225], v197 offset:41504
	s_waitcnt lgkmcnt(3)
	v_mfma_f32_32x32x16_bf16 v[52:67], v[174:177], v[210:213], v[52:67]
	global_load_dwordx4 v[132:135], v[164:165], off offset:1024
	s_waitcnt lgkmcnt(1)
	v_mfma_f32_32x32x16_bf16 v[36:51], v[174:177], v[218:221], v[36:51]
	global_load_dwordx4 v[136:139], v[162:163], off offset:1024
	v_mfma_f32_32x32x16_bf16 v[4:19], v[202:205], v[218:221], v[4:19]
	global_load_dwordx4 v[140:143], v[160:161], off offset:1024
	s_waitcnt lgkmcnt(0)
	v_mfma_f32_32x32x16_bf16 v[36:51], v[178:181], v[222:225], v[36:51]
	global_load_dwordx4 v[198:201], v[158:159], off offset:1024
	v_mfma_f32_32x32x16_bf16 v[4:19], v[206:209], v[222:225], v[4:19]
	global_load_dwordx4 v[226:229], v[156:157], off offset:1024
	ds_read_b128 v[222:225], v197 offset:41568
	ds_read_b128 v[174:177], v196 offset:4672
	v_mfma_f32_32x32x16_bf16 v[20:35], v[202:205], v[210:213], v[20:35]
	global_load_dwordx4 v[230:233], v[154:155], off offset:1024
	ds_read_b128 v[210:213], v196 offset:4704
	ds_read_b128 v[202:205], v196 offset:64
	v_mfma_f32_32x32x16_bf16 v[52:67], v[178:181], v[214:217], v[52:67]
	global_load_dwordx4 v[242:245], v[152:153], off offset:1024
	ds_read_b128 v[218:221], v197 offset:36960
	ds_read_b128 v[178:181], v197 offset:41536
	v_mfma_f32_32x32x16_bf16 v[20:35], v[206:209], v[214:217], v[20:35]
	global_load_dwordx4 v[246:249], v[146:147], off offset:1024
	ds_read_b128 v[214:217], v197 offset:36928
	ds_read_b128 v[206:209], v196 offset:96
	s_waitcnt lgkmcnt(1)
	v_mfma_f32_32x32x16_bf16 v[52:67], v[202:205], v[214:217], v[52:67]
	s_waitcnt vmcnt(23)
	ds_write_b128 v190, v[68:71]
	v_mfma_f32_32x32x16_bf16 v[36:51], v[202:205], v[178:181], v[36:51]
	s_waitcnt vmcnt(22)
	ds_write_b128 v190, v[72:75] offset:36864
	v_mfma_f32_32x32x16_bf16 v[20:35], v[174:177], v[214:217], v[20:35]
	s_waitcnt vmcnt(21)
	ds_write_b128 v191, v[76:79]
	v_mfma_f32_32x32x16_bf16 v[4:19], v[174:177], v[178:181], v[4:19]
	s_waitcnt vmcnt(20)
	ds_write_b128 v191, v[80:83] offset:36864
	s_waitcnt lgkmcnt(4)
	v_mfma_f32_32x32x16_bf16 v[52:67], v[206:209], v[218:221], v[52:67]
	s_waitcnt vmcnt(19)
	ds_write_b128 v192, v[84:87]
	v_mfma_f32_32x32x16_bf16 v[36:51], v[206:209], v[222:225], v[36:51]
	s_waitcnt vmcnt(18)
	ds_write_b128 v192, v[92:95] offset:36864
	v_mfma_f32_32x32x16_bf16 v[20:35], v[210:213], v[218:221], v[20:35]
	s_waitcnt vmcnt(17)
	ds_write_b128 v193, v[104:107]
	v_mfma_f32_32x32x16_bf16 v[4:19], v[210:213], v[222:225], v[4:19]
	s_waitcnt vmcnt(16)
	ds_write_b128 v193, v[112:115] offset:36864
	s_waitcnt lgkmcnt(0)
	s_barrier
; template <class Epi, class ColV>
; DI void gemm_tile(const bf16_t* __restrict__ A, int lda, const bf16_t* __restrict__ Bt, int ldb, int K, int m0, int n0, unsigned char* smem, Epi epi, ColV colv, const bf16_t* __restrict__ HYT = nullptr) {
;     ...
;     auto step = [&](int kt, u32x4 (&ldset)[8], const u32x4 (&stset)[8]) {
;         const int buf = kt & 1;
;         if (kt + 2 < nk) gload(ldset, kt + 2);
;         const bf16_t* Ab = As + (buf * 128 + 64 * wr + li) * LS + 8 * lh;
;         const bf16_t* Bb = Bs + (buf * 128 + 64 * wc + li) * LS + 8 * lh;
;         bf16x8 fa[2][2], fb[2][2], ga[2][2], gb[2][2];
; #pragma unroll
;         for (int k2 = 0; k2 < 2; ++k2) { fa[k2][0] = ld8(Ab + 16 * k2); fa[k2][1] = ld8(Ab + 32 * LS + 16 * k2); fb[k2][0] = ld8(Bb + 16 * k2); fb[k2][1] = ld8(Bb + 32 * LS + 16 * k2); }
;         __builtin_amdgcn_sched_barrier(0);
; #pragma unroll
;         for (int k2 = 0; k2 < 2; ++k2) {
;             acc[0][0] = MFMA(fa[k2][0], fb[k2][0], acc[0][0]); acc[0][1] = MFMA(fa[k2][0], fb[k2][1], acc[0][1]);
;             acc[1][0] = MFMA(fa[k2][1], fb[k2][0], acc[1][0]); acc[1][1] = MFMA(fa[k2][1], fb[k2][1], acc[1][1]);
;         }
; #pragma unroll
;         for (int k2 = 0; k2 < 2; ++k2) { const int ks = 2 + k2; ga[k2][0] = ld8(Ab + 16 * ks); ga[k2][1] = ld8(Ab + 32 * LS + 16 * ks); gb[k2][0] = ld8(Bb + 16 * ks); gb[k2][1] = ld8(Bb + 32 * LS + 16 * ks); }
; #pragma unroll
;         for (int k2 = 0; k2 < 2; ++k2) {
;             acc[0][0] = MFMA(ga[k2][0], gb[k2][0], acc[0][0]); acc[0][1] = MFMA(ga[k2][0], gb[k2][1], acc[0][1]);
;             acc[1][0] = MFMA(ga[k2][1], gb[k2][0], acc[1][0]); acc[1][1] = MFMA(ga[k2][1], gb[k2][1], acc[1][1]);
;         }
;         if (kt + 1 < nk) sstore(stset, buf ^ 1, kt + 1);
; #pragma unroll
;         for (int i = 0; i < 8; ++i) { __builtin_amdgcn_sched_group_barrier(0x008, 1, 0); __builtin_amdgcn_sched_group_barrier(0x100, 1, 0); }
; #pragma unroll
;         for (int i = 0; i < 8; ++i) { __builtin_amdgcn_sched_group_barrier(0x008, 1, 0); __builtin_amdgcn_sched_group_barrier(0x200, 1, 0); }
;         __builtin_amdgcn_sched_barrier(0);
;         __syncthreads();
;     };
;     gload(R0, 0); gload(R1, 1);
;     sstore(R0, 0, 0); __syncthreads();
;     for (int kt = 0; kt < nk; kt += 2) {
;         step(kt, R0, R1);
;         if (kt + 1 < nk) step(kt + 1, R1, R0);
;     }
	v_lshl_add_u64 v[164:165], v[164:165], 0, s[100:101]
	v_lshl_add_u64 v[162:163], v[162:163], 0, s[100:101]
	v_lshl_add_u64 v[160:161], v[160:161], 0, s[100:101]
	v_lshl_add_u64 v[158:159], v[158:159], 0, s[100:101]
	v_lshl_add_u64 v[156:157], v[156:157], 0, s[100:101]
	v_lshl_add_u64 v[154:155], v[154:155], 0, s[100:101]
	v_lshl_add_u64 v[152:153], v[152:153], 0, s[100:101]
	v_lshl_add_u64 v[146:147], v[146:147], 0, s[100:101]
	s_sub_u32 s41, s41, 1
	s_cmp_lg_u32 s41, 0
	s_cbranch_scc1 .Lg3_phase11
	ds_read_b128 v[174:177], v194
	ds_read_b128 v[178:181], v194 offset:32
	ds_read_b128 v[202:205], v194 offset:4608
	ds_read_b128 v[206:209], v194 offset:4640
	ds_read_b128 v[210:213], v195 offset:36864
	ds_read_b128 v[214:217], v195 offset:36896
	ds_read_b128 v[218:221], v195 offset:41472
	ds_read_b128 v[222:225], v195 offset:41504
	s_waitcnt lgkmcnt(3)
	v_mfma_f32_32x32x16_bf16 v[52:67], v[174:177], v[210:213], v[52:67]
	global_load_dwordx4 v[68:71], v[164:165], off offset:384
	s_waitcnt lgkmcnt(1)
	v_mfma_f32_32x32x16_bf16 v[36:51], v[174:177], v[218:221], v[36:51]
	global_load_dwordx4 v[72:75], v[162:163], off offset:384
	v_mfma_f32_32x32x16_bf16 v[4:19], v[202:205], v[218:221], v[4:19]
	global_load_dwordx4 v[76:79], v[160:161], off offset:384
	s_waitcnt lgkmcnt(0)
	v_mfma_f32_32x32x16_bf16 v[36:51], v[178:181], v[222:225], v[36:51]
	global_load_dwordx4 v[80:83], v[158:159], off offset:384
	v_mfma_f32_32x32x16_bf16 v[4:19], v[206:209], v[222:225], v[4:19]
	global_load_dwordx4 v[84:87], v[156:157], off offset:384
	ds_read_b128 v[222:225], v195 offset:41568
	ds_read_b128 v[174:177], v194 offset:4672
	v_mfma_f32_32x32x16_bf16 v[20:35], v[202:205], v[210:213], v[20:35]
	global_load_dwordx4 v[92:95], v[154:155], off offset:384
	ds_read_b128 v[210:213], v194 offset:4704
	ds_read_b128 v[202:205], v194 offset:64
	v_mfma_f32_32x32x16_bf16 v[52:67], v[178:181], v[214:217], v[52:67]
	global_load_dwordx4 v[104:107], v[152:153], off offset:384
	ds_read_b128 v[218:221], v195 offset:36960
	ds_read_b128 v[178:181], v195 offset:41536
	v_mfma_f32_32x32x16_bf16 v[20:35], v[206:209], v[214:217], v[20:35]
	global_load_dwordx4 v[112:115], v[146:147], off offset:384
	ds_read_b128 v[214:217], v195 offset:36928
	ds_read_b128 v[206:209], v194 offset:96
	s_waitcnt lgkmcnt(1)
	v_mfma_f32_32x32x16_bf16 v[52:67], v[202:205], v[214:217], v[52:67]
	s_waitcnt vmcnt(23)
	ds_write_b128 v190, v[88:91] offset:18432
	v_mfma_f32_32x32x16_bf16 v[36:51], v[202:205], v[178:181], v[36:51]
	s_waitcnt vmcnt(22)
	ds_write_b128 v190, v[96:99] offset:55296
	v_mfma_f32_32x32x16_bf16 v[20:35], v[174:177], v[214:217], v[20:35]
	s_waitcnt vmcnt(21)
	ds_write_b128 v191, v[100:103] offset:18432
	v_mfma_f32_32x32x16_bf16 v[4:19], v[174:177], v[178:181], v[4:19]
	s_waitcnt vmcnt(20)
	ds_write_b128 v191, v[108:111] offset:55296
	s_waitcnt lgkmcnt(4)
	v_mfma_f32_32x32x16_bf16 v[52:67], v[206:209], v[218:221], v[52:67]
	s_waitcnt vmcnt(19)
	ds_write_b128 v192, v[116:119] offset:18432
	v_mfma_f32_32x32x16_bf16 v[36:51], v[206:209], v[222:225], v[36:51]
	s_waitcnt vmcnt(18)
	ds_write_b128 v192, v[120:123] offset:55296
	v_mfma_f32_32x32x16_bf16 v[20:35], v[210:213], v[218:221], v[20:35]
	s_waitcnt vmcnt(17)
	ds_write_b128 v193, v[124:127] offset:18432
	v_mfma_f32_32x32x16_bf16 v[4:19], v[210:213], v[222:225], v[4:19]
	s_waitcnt vmcnt(16)
	ds_write_b128 v193, v[128:131] offset:55296
	s_waitcnt lgkmcnt(0)
	s_barrier
	ds_read_b128 v[174:177], v196
	ds_read_b128 v[178:181], v196 offset:32
	ds_read_b128 v[202:205], v196 offset:4608
	ds_read_b128 v[206:209], v196 offset:4640
	ds_read_b128 v[210:213], v197 offset:36864
	ds_read_b128 v[214:217], v197 offset:36896
	ds_read_b128 v[218:221], v197 offset:41472
	ds_read_b128 v[222:225], v197 offset:41504
	s_waitcnt lgkmcnt(3)
	v_mfma_f32_32x32x16_bf16 v[52:67], v[174:177], v[210:213], v[52:67]
	s_waitcnt lgkmcnt(1)
	v_mfma_f32_32x32x16_bf16 v[36:51], v[174:177], v[218:221], v[36:51]
	v_mfma_f32_32x32x16_bf16 v[4:19], v[202:205], v[218:221], v[4:19]
	s_waitcnt lgkmcnt(0)
	v_mfma_f32_32x32x16_bf16 v[36:51], v[178:181], v[222:225], v[36:51]
	v_mfma_f32_32x32x16_bf16 v[4:19], v[206:209], v[222:225], v[4:19]
	ds_read_b128 v[222:225], v197 offset:41568
	ds_read_b128 v[174:177], v196 offset:4672
	v_mfma_f32_32x32x16_bf16 v[20:35], v[202:205], v[210:213], v[20:35]
	ds_read_b128 v[210:213], v196 offset:4704
	ds_read_b128 v[202:205], v196 offset:64
	v_mfma_f32_32x32x16_bf16 v[52:67], v[178:181], v[214:217], v[52:67]
	ds_read_b128 v[218:221], v197 offset:36960
	ds_read_b128 v[178:181], v197 offset:41536
	v_mfma_f32_32x32x16_bf16 v[20:35], v[206:209], v[214:217], v[20:35]
	ds_read_b128 v[214:217], v197 offset:36928
	ds_read_b128 v[206:209], v196 offset:96
	s_waitcnt lgkmcnt(1)
	v_mfma_f32_32x32x16_bf16 v[52:67], v[202:205], v[214:217], v[52:67]
	s_waitcnt vmcnt(15)
	ds_write_b128 v190, v[132:135]
	v_mfma_f32_32x32x16_bf16 v[36:51], v[202:205], v[178:181], v[36:51]
	s_waitcnt vmcnt(14)
	ds_write_b128 v190, v[136:139] offset:36864
	v_mfma_f32_32x32x16_bf16 v[20:35], v[174:177], v[214:217], v[20:35]
	s_waitcnt vmcnt(13)
	ds_write_b128 v191, v[140:143]
	v_mfma_f32_32x32x16_bf16 v[4:19], v[174:177], v[178:181], v[4:19]
	s_waitcnt vmcnt(12)
	ds_write_b128 v191, v[198:201] offset:36864
	s_waitcnt lgkmcnt(4)
	v_mfma_f32_32x32x16_bf16 v[52:67], v[206:209], v[218:221], v[52:67]
	s_waitcnt vmcnt(11)
	ds_write_b128 v192, v[226:229]
	v_mfma_f32_32x32x16_bf16 v[36:51], v[206:209], v[222:225], v[36:51]
	s_waitcnt vmcnt(10)
	ds_write_b128 v192, v[230:233] offset:36864
	v_mfma_f32_32x32x16_bf16 v[20:35], v[210:213], v[218:221], v[20:35]
	s_waitcnt vmcnt(9)
	ds_write_b128 v193, v[242:245]
	v_mfma_f32_32x32x16_bf16 v[4:19], v[210:213], v[222:225], v[4:19]
	s_waitcnt vmcnt(8)
	ds_write_b128 v193, v[246:249] offset:36864
	s_waitcnt lgkmcnt(0)
	s_barrier
; template <class Epi, class ColV>
; DI void gemm_tile(const bf16_t* __restrict__ A, int lda, const bf16_t* __restrict__ Bt, int ldb, int K, int m0, int n0, unsigned char* smem, Epi epi, ColV colv, const bf16_t* __restrict__ HYT = nullptr) {
;     ...
;     auto step = [&](int kt, u32x4 (&ldset)[8], const u32x4 (&stset)[8]) {
;         const int buf = kt & 1;
;         if (kt + 2 < nk) gload(ldset, kt + 2);
;         const bf16_t* Ab = As + (buf * 128 + 64 * wr + li) * LS + 8 * lh;
;         const bf16_t* Bb = Bs + (buf * 128 + 64 * wc + li) * LS + 8 * lh;
;         bf16x8 fa[2][2], fb[2][2], ga[2][2], gb[2][2];
; #pragma unroll
;         for (int k2 = 0; k2 < 2; ++k2) { fa[k2][0] = ld8(Ab + 16 * k2); fa[k2][1] = ld8(Ab + 32 * LS + 16 * k2); fb[k2][0] = ld8(Bb + 16 * k2); fb[k2][1] = ld8(Bb + 32 * LS + 16 * k2); }
;         __builtin_amdgcn_sched_barrier(0);
; #pragma unroll
;         for (int k2 = 0; k2 < 2; ++k2) {
;             acc[0][0] = MFMA(fa[k2][0], fb[k2][0], acc[0][0]); acc[0][1] = MFMA(fa[k2][0], fb[k2][1], acc[0][1]);
;             acc[1][0] = MFMA(fa[k2][1], fb[k2][0], acc[1][0]); acc[1][1] = MFMA(fa[k2][1], fb[k2][1], acc[1][1]);
;         }
; #pragma unroll
;         for (int k2 = 0; k2 < 2; ++k2) { const int ks = 2 + k2; ga[k2][0] = ld8(Ab + 16 * ks); ga[k2][1] = ld8(Ab + 32 * LS + 16 * ks); gb[k2][0] = ld8(Bb + 16 * ks); gb[k2][1] = ld8(Bb + 32 * LS + 16 * ks); }
; #pragma unroll
;         for (int k2 = 0; k2 < 2; ++k2) {
;             acc[0][0] = MFMA(ga[k2][0], gb[k2][0], acc[0][0]); acc[0][1] = MFMA(ga[k2][0], gb[k2][1], acc[0][1]);
;             acc[1][0] = MFMA(ga[k2][1], gb[k2][0], acc[1][0]); acc[1][1] = MFMA(ga[k2][1], gb[k2][1], acc[1][1]);
;         }
;         if (kt + 1 < nk) sstore(stset, buf ^ 1, kt + 1);
; #pragma unroll
;         for (int i = 0; i < 8; ++i) { __builtin_amdgcn_sched_group_barrier(0x008, 1, 0); __builtin_amdgcn_sched_group_barrier(0x100, 1, 0); }
; #pragma unroll
;         for (int i = 0; i < 8; ++i) { __builtin_amdgcn_sched_group_barrier(0x008, 1, 0); __builtin_amdgcn_sched_group_barrier(0x200, 1, 0); }
;         __builtin_amdgcn_sched_barrier(0);
;         __syncthreads();
;     };
;     gload(R0, 0); gload(R1, 1);
;     sstore(R0, 0, 0); __syncthreads();
;     for (int kt = 0; kt < nk; kt += 2) {
;         step(kt, R0, R1);
;         if (kt + 1 < nk) step(kt + 1, R1, R0);
;     }
	ds_read_b128 v[174:177], v194
	ds_read_b128 v[178:181], v194 offset:32
	ds_read_b128 v[202:205], v194 offset:4608
	ds_read_b128 v[206:209], v194 offset:4640
	ds_read_b128 v[210:213], v195 offset:36864
	ds_read_b128 v[214:217], v195 offset:36896
	ds_read_b128 v[218:221], v195 offset:41472
	ds_read_b128 v[222:225], v195 offset:41504
	s_waitcnt lgkmcnt(3)
	v_mfma_f32_32x32x16_bf16 v[52:67], v[174:177], v[210:213], v[52:67]
	s_waitcnt lgkmcnt(1)
	v_mfma_f32_32x32x16_bf16 v[36:51], v[174:177], v[218:221], v[36:51]
	v_mfma_f32_32x32x16_bf16 v[4:19], v[202:205], v[218:221], v[4:19]
	s_waitcnt lgkmcnt(0)
	v_mfma_f32_32x32x16_bf16 v[36:51], v[178:181], v[222:225], v[36:51]
	v_mfma_f32_32x32x16_bf16 v[4:19], v[206:209], v[222:225], v[4:19]
	ds_read_b128 v[222:225], v195 offset:41568
	ds_read_b128 v[174:177], v194 offset:4672
	v_mfma_f32_32x32x16_bf16 v[20:35], v[202:205], v[210:213], v[20:35]
	ds_read_b128 v[210:213], v194 offset:4704
	ds_read_b128 v[202:205], v194 offset:64
	v_mfma_f32_32x32x16_bf16 v[52:67], v[178:181], v[214:217], v[52:67]
	ds_read_b128 v[218:221], v195 offset:36960
	ds_read_b128 v[178:181], v195 offset:41536
	v_mfma_f32_32x32x16_bf16 v[20:35], v[206:209], v[214:217], v[20:35]
	ds_read_b128 v[214:217], v195 offset:36928
	ds_read_b128 v[206:209], v194 offset:96
	s_waitcnt lgkmcnt(1)
	v_mfma_f32_32x32x16_bf16 v[52:67], v[202:205], v[214:217], v[52:67]
	s_waitcnt vmcnt(7)
	ds_write_b128 v190, v[68:71] offset:18432
	v_mfma_f32_32x32x16_bf16 v[36:51], v[202:205], v[178:181], v[36:51]
	s_waitcnt vmcnt(6)
	ds_write_b128 v190, v[72:75] offset:55296
	v_mfma_f32_32x32x16_bf16 v[20:35], v[174:177], v[214:217], v[20:35]
	s_waitcnt vmcnt(5)
	ds_write_b128 v191, v[76:79] offset:18432
	v_mfma_f32_32x32x16_bf16 v[4:19], v[174:177], v[178:181], v[4:19]
	s_waitcnt vmcnt(4)
	ds_write_b128 v191, v[80:83] offset:55296
	s_waitcnt lgkmcnt(4)
	v_mfma_f32_32x32x16_bf16 v[52:67], v[206:209], v[218:221], v[52:67]
	s_waitcnt vmcnt(3)
	ds_write_b128 v192, v[84:87] offset:18432
	v_mfma_f32_32x32x16_bf16 v[36:51], v[206:209], v[222:225], v[36:51]
	s_waitcnt vmcnt(2)
	ds_write_b128 v192, v[92:95] offset:55296
	v_mfma_f32_32x32x16_bf16 v[20:35], v[210:213], v[218:221], v[20:35]
	s_waitcnt vmcnt(1)
	ds_write_b128 v193, v[104:107] offset:18432
	v_mfma_f32_32x32x16_bf16 v[4:19], v[210:213], v[222:225], v[4:19]
	s_waitcnt vmcnt(0)
	ds_write_b128 v193, v[112:115] offset:55296
	s_waitcnt lgkmcnt(0)
	s_barrier
	ds_read_b128 v[174:177], v196
	ds_read_b128 v[178:181], v196 offset:32
	ds_read_b128 v[202:205], v196 offset:4608
	ds_read_b128 v[206:209], v196 offset:4640
	ds_read_b128 v[210:213], v197 offset:36864
	ds_read_b128 v[214:217], v197 offset:36896
	ds_read_b128 v[218:221], v197 offset:41472
	ds_read_b128 v[222:225], v197 offset:41504
	s_waitcnt lgkmcnt(3)
	v_mfma_f32_32x32x16_bf16 v[52:67], v[174:177], v[210:213], v[52:67]
	s_waitcnt lgkmcnt(1)
	v_mfma_f32_32x32x16_bf16 v[36:51], v[174:177], v[218:221], v[36:51]
	v_mfma_f32_32x32x16_bf16 v[4:19], v[202:205], v[218:221], v[4:19]
	s_waitcnt lgkmcnt(0)
	v_mfma_f32_32x32x16_bf16 v[36:51], v[178:181], v[222:225], v[36:51]
	v_mfma_f32_32x32x16_bf16 v[4:19], v[206:209], v[222:225], v[4:19]
	ds_read_b128 v[222:225], v197 offset:41568
	ds_read_b128 v[174:177], v196 offset:4672
	v_mfma_f32_32x32x16_bf16 v[20:35], v[202:205], v[210:213], v[20:35]
	ds_read_b128 v[210:213], v196 offset:4704
	ds_read_b128 v[202:205], v196 offset:64
	v_mfma_f32_32x32x16_bf16 v[52:67], v[178:181], v[214:217], v[52:67]
	ds_read_b128 v[218:221], v197 offset:36960
	ds_read_b128 v[178:181], v197 offset:41536
	v_mfma_f32_32x32x16_bf16 v[20:35], v[206:209], v[214:217], v[20:35]
	ds_read_b128 v[214:217], v197 offset:36928
	ds_read_b128 v[206:209], v196 offset:96
	s_waitcnt lgkmcnt(1)
	v_mfma_f32_32x32x16_bf16 v[52:67], v[202:205], v[214:217], v[52:67]
	v_mfma_f32_32x32x16_bf16 v[36:51], v[202:205], v[178:181], v[36:51]
	v_mfma_f32_32x32x16_bf16 v[20:35], v[174:177], v[214:217], v[20:35]
	v_mfma_f32_32x32x16_bf16 v[4:19], v[174:177], v[178:181], v[4:19]
	s_waitcnt lgkmcnt(0)
	v_mfma_f32_32x32x16_bf16 v[52:67], v[206:209], v[218:221], v[52:67]
	v_mfma_f32_32x32x16_bf16 v[36:51], v[206:209], v[222:225], v[36:51]
	v_mfma_f32_32x32x16_bf16 v[20:35], v[210:213], v[218:221], v[20:35]
	v_mfma_f32_32x32x16_bf16 v[4:19], v[210:213], v[222:225], v[4:19]
	s_waitcnt lgkmcnt(0)
	s_barrier
	s_nop 7
	s_nop 3
	s_branch .LBB0_37

; #define MFMA(a, b, c) __builtin_amdgcn_mfma_f32_32x32x16_bf16((a), (b), (c), 0, 0, 0)
; template <class Epi, class ColV>
; DI void gemm_tile(const bf16_t* __restrict__ A, int lda, const bf16_t* __restrict__ Bt, int ldb, int K, int m0, int n0, unsigned char* smem, Epi epi, ColV colv, const bf16_t* __restrict__ HYT = nullptr) {
;     ...
;     auto gload = [&](u32x4 (&r)[8], int kt) {
; #pragma unroll
;         for (int i = 0; i < 4; ++i) { int id = tid + 256 * i, row = id >> 3, kc = id & 7;
;             if (HYT && kt >= 12) r[i] = *(const u32x4*)(HYT + (size_t)((kt - 12) * 64 + (id >> 4)) * NT + m0 + (id & 15) * 8);
;             else r[i] = *(const u32x4*)(A + (size_t)(m0 + row) * lda + kt * 64 + kc * 8);
;             r[4 + i] = *(const u32x4*)(Bt + (size_t)(n0 + row) * ldb + kt * 64 + kc * 8); }
;     };
;     auto sstore = [&](const u32x4 (&r)[8], int buf, int kt) {
; #pragma unroll
;         for (int i = 0; i < 4; ++i) { int id = tid + 256 * i, row = id >> 3, kc = id & 7;
;             if (HYT && kt >= 12) { const int kk = id >> 4, rr = (id & 15) * 8; bf16_t* d = As + (buf * 128 + rr) * LS + kk; const bf16x8 v = __builtin_bit_cast(bf16x8, r[i]);
; #pragma unroll
;                 for (int e = 0; e < 8; ++e) d[e * LS] = (bf16_t)v[e]; }
;             else *(u32x4*)(As + (buf * 128 + row) * LS + kc * 8) = r[i];
;             *(u32x4*)(Bs + (buf * 128 + row) * LS + kc * 8) = r[4 + i]; }
;     };
;     auto step = [&](int kt, u32x4 (&ldset)[8], const u32x4 (&stset)[8]) {
;         const int buf = kt & 1;
;         if (kt + 2 < nk) gload(ldset, kt + 2);
;         const bf16_t* Ab = As + (buf * 128 + 64 * wr + li) * LS + 8 * lh;
;         const bf16_t* Bb = Bs + (buf * 128 + 64 * wc + li) * LS + 8 * lh;
;         bf16x8 fa[2][2], fb[2][2], ga[2][2], gb[2][2];
; #pragma unroll
;         for (int k2 = 0; k2 < 2; ++k2) { fa[k2][0] = ld8(Ab + 16 * k2); fa[k2][1] = ld8(Ab + 32 * LS + 16 * k2); fb[k2][0] = ld8(Bb + 16 * k2); fb[k2][1] = ld8(Bb + 32 * LS + 16 * k2); }
;         __builtin_amdgcn_sched_barrier(0);
; #pragma unroll
;         for (int k2 = 0; k2 < 2; ++k2) {
;             acc[0][0] = MFMA(fa[k2][0], fb[k2][0], acc[0][0]); acc[0][1] = MFMA(fa[k2][0], fb[k2][1], acc[0][1]);
;             acc[1][0] = MFMA(fa[k2][1], fb[k2][0], acc[1][0]); acc[1][1] = MFMA(fa[k2][1], fb[k2][1], acc[1][1]);
;         }
; #pragma unroll
.LBB0_56:
	s_cmp_lt_u32 s40, 14
	s_cselect_b64 s[18:19], -1, 0
	s_cmp_gt_u32 s40, 13
	s_cselect_b64 s[12:13], -1, 0
	s_and_b64 vcc, exec, s[12:13]
	v_lshl_add_u64 v[164:165], v[144:145], 0, v[2:3]
	v_lshl_add_u64 v[162:163], v[142:143], 0, v[2:3]
	v_lshl_add_u64 v[160:161], v[140:141], 0, v[2:3]
	v_lshl_add_u64 v[158:159], v[138:139], 0, v[2:3]
	v_lshl_add_u64 v[156:157], v[136:137], 0, v[2:3]
	v_lshl_add_u64 v[154:155], v[134:135], 0, v[2:3]
	v_lshl_add_u64 v[152:153], v[132:133], 0, v[2:3]
	v_lshl_add_u64 v[146:147], v[0:1], 0, v[2:3]
	s_mov_b32 s100, 0x26ca000
	s_mov_b32 s101, 0
	v_lshl_add_u64 v[164:165], v[164:165], 0, s[100:101]
	v_lshl_add_u64 v[160:161], v[160:161], 0, s[100:101]
	v_lshl_add_u64 v[156:157], v[156:157], 0, s[100:101]
	v_lshl_add_u64 v[152:153], v[152:153], 0, s[100:101]
	s_mov_b32 s100, 0x680000
	s_mov_b32 s101, 0
	v_lshl_add_u64 v[162:163], v[162:163], 0, s[100:101]
	v_lshl_add_u64 v[158:159], v[158:159], 0, s[100:101]
	v_lshl_add_u64 v[154:155], v[154:155], 0, s[100:101]
	v_lshl_add_u64 v[146:147], v[146:147], 0, s[100:101]
	ds_read_b128 v[174:177], v194
	ds_read_b128 v[178:181], v194 offset:32
	ds_read_b128 v[202:205], v194 offset:4608
	ds_read_b128 v[206:209], v194 offset:4640
	ds_read_b128 v[210:213], v195 offset:36864
	ds_read_b128 v[214:217], v195 offset:36896
	ds_read_b128 v[218:221], v195 offset:41472
	ds_read_b128 v[222:225], v195 offset:41504
	s_waitcnt lgkmcnt(3)
	v_mfma_f32_32x32x16_bf16 v[52:67], v[174:177], v[210:213], v[52:67]
	global_load_dwordx4 v[132:135], v[164:165], off offset:256
	global_load_dwordx4 v[136:139], v[162:163], off offset:256
	s_waitcnt lgkmcnt(1)
	v_mfma_f32_32x32x16_bf16 v[36:51], v[174:177], v[218:221], v[36:51]
	global_load_dwordx4 v[140:143], v[160:161], off offset:256
	global_load_dwordx4 v[198:201], v[158:159], off offset:256
	v_mfma_f32_32x32x16_bf16 v[4:19], v[202:205], v[218:221], v[4:19]
	global_load_dwordx4 v[226:229], v[156:157], off offset:256
	global_load_dwordx4 v[230:233], v[154:155], off offset:256
	s_waitcnt lgkmcnt(0)
	v_mfma_f32_32x32x16_bf16 v[36:51], v[178:181], v[222:225], v[36:51]
	global_load_dwordx4 v[242:245], v[152:153], off offset:256
	global_load_dwordx4 v[246:249], v[146:147], off offset:256
	v_mfma_f32_32x32x16_bf16 v[4:19], v[206:209], v[222:225], v[4:19]
	global_load_dwordx4 v[68:71], v[164:165], off offset:384
	global_load_dwordx4 v[72:75], v[162:163], off offset:384
	ds_read_b128 v[222:225], v195 offset:41568
	ds_read_b128 v[174:177], v194 offset:4672
	v_mfma_f32_32x32x16_bf16 v[20:35], v[202:205], v[210:213], v[20:35]
	global_load_dwordx4 v[76:79], v[160:161], off offset:384
	global_load_dwordx4 v[80:83], v[158:159], off offset:384
	ds_read_b128 v[210:213], v194 offset:4704
	ds_read_b128 v[202:205], v194 offset:64
	v_mfma_f32_32x32x16_bf16 v[52:67], v[178:181], v[214:217], v[52:67]
	global_load_dwordx4 v[84:87], v[156:157], off offset:384
	global_load_dwordx4 v[92:95], v[154:155], off offset:384
	ds_read_b128 v[218:221], v195 offset:36960
	ds_read_b128 v[178:181], v195 offset:41536
	v_mfma_f32_32x32x16_bf16 v[20:35], v[206:209], v[214:217], v[20:35]
	global_load_dwordx4 v[104:107], v[152:153], off offset:384
	global_load_dwordx4 v[112:115], v[146:147], off offset:384
	ds_read_b128 v[214:217], v195 offset:36928
	ds_read_b128 v[206:209], v194 offset:96
	s_waitcnt lgkmcnt(1)
	v_mfma_f32_32x32x16_bf16 v[52:67], v[202:205], v[214:217], v[52:67]
	s_waitcnt vmcnt(16)
	ds_write_b128 v167, v[88:91] offset:18432
	v_mfma_f32_32x32x16_bf16 v[36:51], v[202:205], v[178:181], v[36:51]
	ds_write_b128 v167, v[96:99] offset:55296
	v_mfma_f32_32x32x16_bf16 v[20:35], v[174:177], v[214:217], v[20:35]
	ds_write_b128 v190, v[100:103] offset:18432
	v_mfma_f32_32x32x16_bf16 v[4:19], v[174:177], v[178:181], v[4:19]
	ds_write_b128 v190, v[108:111] offset:55296
	s_waitcnt lgkmcnt(4)
	v_mfma_f32_32x32x16_bf16 v[52:67], v[206:209], v[218:221], v[52:67]
	ds_write_b128 v191, v[116:119] offset:18432
	v_mfma_f32_32x32x16_bf16 v[36:51], v[206:209], v[222:225], v[36:51]
	ds_write_b128 v191, v[120:123] offset:55296
	v_mfma_f32_32x32x16_bf16 v[20:35], v[210:213], v[218:221], v[20:35]
	ds_write_b128 v192, v[124:127] offset:18432
	v_mfma_f32_32x32x16_bf16 v[4:19], v[210:213], v[222:225], v[4:19]
	ds_write_b128 v192, v[128:131] offset:55296
	s_waitcnt lgkmcnt(0)
	s_barrier
; #define MFMA(a, b, c) __builtin_amdgcn_mfma_f32_32x32x16_bf16((a), (b), (c), 0, 0, 0)
; template <class Epi, class ColV>
; DI void gemm_tile(const bf16_t* __restrict__ A, int lda, const bf16_t* __restrict__ Bt, int ldb, int K, int m0, int n0, unsigned char* smem, Epi epi, ColV colv, const bf16_t* __restrict__ HYT = nullptr) {
;     ...
;     auto gload = [&](u32x4 (&r)[8], int kt) {
; #pragma unroll
;         for (int i = 0; i < 4; ++i) { int id = tid + 256 * i, row = id >> 3, kc = id & 7;
;             if (HYT && kt >= 12) r[i] = *(const u32x4*)(HYT + (size_t)((kt - 12) * 64 + (id >> 4)) * NT + m0 + (id & 15) * 8);
;             else r[i] = *(const u32x4*)(A + (size_t)(m0 + row) * lda + kt * 64 + kc * 8);
;             r[4 + i] = *(const u32x4*)(Bt + (size_t)(n0 + row) * ldb + kt * 64 + kc * 8); }
;     };
;     auto sstore = [&](const u32x4 (&r)[8], int buf, int kt) {
; #pragma unroll
;         for (int i = 0; i < 4; ++i) { int id = tid + 256 * i, row = id >> 3, kc = id & 7;
;             if (HYT && kt >= 12) { const int kk = id >> 4, rr = (id & 15) * 8; bf16_t* d = As + (buf * 128 + rr) * LS + kk; const bf16x8 v = __builtin_bit_cast(bf16x8, r[i]);
; #pragma unroll
;                 for (int e = 0; e < 8; ++e) d[e * LS] = (bf16_t)v[e]; }
;             else *(u32x4*)(As + (buf * 128 + row) * LS + kc * 8) = r[i];
;             *(u32x4*)(Bs + (buf * 128 + row) * LS + kc * 8) = r[4 + i]; }
;     };
;     auto step = [&](int kt, u32x4 (&ldset)[8], const u32x4 (&stset)[8]) {
;         const int buf = kt & 1;
;         if (kt + 2 < nk) gload(ldset, kt + 2);
;         const bf16_t* Ab = As + (buf * 128 + 64 * wr + li) * LS + 8 * lh;
;         const bf16_t* Bb = Bs + (buf * 128 + 64 * wc + li) * LS + 8 * lh;
;         bf16x8 fa[2][2], fb[2][2], ga[2][2], gb[2][2];
; #pragma unroll
;         for (int k2 = 0; k2 < 2; ++k2) { fa[k2][0] = ld8(Ab + 16 * k2); fa[k2][1] = ld8(Ab + 32 * LS + 16 * k2); fb[k2][0] = ld8(Bb + 16 * k2); fb[k2][1] = ld8(Bb + 32 * LS + 16 * k2); }
;         __builtin_amdgcn_sched_barrier(0);
; #pragma unroll
;         for (int k2 = 0; k2 < 2; ++k2) {
;             acc[0][0] = MFMA(fa[k2][0], fb[k2][0], acc[0][0]); acc[0][1] = MFMA(fa[k2][0], fb[k2][1], acc[0][1]);
;             acc[1][0] = MFMA(fa[k2][1], fb[k2][0], acc[1][0]); acc[1][1] = MFMA(fa[k2][1], fb[k2][1], acc[1][1]);
;         }
; #pragma unroll
	ds_read_b128 v[174:177], v196
	ds_read_b128 v[178:181], v196 offset:32
	ds_read_b128 v[202:205], v196 offset:4608
	ds_read_b128 v[206:209], v196 offset:4640
	ds_read_b128 v[210:213], v197 offset:36864
	ds_read_b128 v[214:217], v197 offset:36896
	ds_read_b128 v[218:221], v197 offset:41472
	ds_read_b128 v[222:225], v197 offset:41504
	s_waitcnt lgkmcnt(3)
	v_mfma_f32_32x32x16_bf16 v[52:67], v[174:177], v[210:213], v[52:67]
	global_load_dwordx4 v[88:91], v[164:165], off offset:512
	s_waitcnt lgkmcnt(1)
	v_mfma_f32_32x32x16_bf16 v[36:51], v[174:177], v[218:221], v[36:51]
	global_load_dwordx4 v[96:99], v[162:163], off offset:512
	v_mfma_f32_32x32x16_bf16 v[4:19], v[202:205], v[218:221], v[4:19]
	global_load_dwordx4 v[100:103], v[160:161], off offset:512
	s_waitcnt lgkmcnt(0)
	v_mfma_f32_32x32x16_bf16 v[36:51], v[178:181], v[222:225], v[36:51]
	global_load_dwordx4 v[108:111], v[158:159], off offset:512
	v_mfma_f32_32x32x16_bf16 v[4:19], v[206:209], v[222:225], v[4:19]
	global_load_dwordx4 v[116:119], v[156:157], off offset:512
	ds_read_b128 v[222:225], v197 offset:41568
	ds_read_b128 v[174:177], v196 offset:4672
	v_mfma_f32_32x32x16_bf16 v[20:35], v[202:205], v[210:213], v[20:35]
	global_load_dwordx4 v[120:123], v[154:155], off offset:512
	ds_read_b128 v[210:213], v196 offset:4704
	ds_read_b128 v[202:205], v196 offset:64
	v_mfma_f32_32x32x16_bf16 v[52:67], v[178:181], v[214:217], v[52:67]
	global_load_dwordx4 v[124:127], v[152:153], off offset:512
	ds_read_b128 v[218:221], v197 offset:36960
	ds_read_b128 v[178:181], v197 offset:41536
	v_mfma_f32_32x32x16_bf16 v[20:35], v[206:209], v[214:217], v[20:35]
	global_load_dwordx4 v[128:131], v[146:147], off offset:512
	ds_read_b128 v[214:217], v197 offset:36928
	ds_read_b128 v[206:209], v196 offset:96
	s_waitcnt lgkmcnt(1)
	v_mfma_f32_32x32x16_bf16 v[52:67], v[202:205], v[214:217], v[52:67]
	s_waitcnt vmcnt(23)
	ds_write_b128 v167, v[132:135]
	v_mfma_f32_32x32x16_bf16 v[36:51], v[202:205], v[178:181], v[36:51]
	s_waitcnt vmcnt(22)
	ds_write_b128 v167, v[136:139] offset:36864
	v_mfma_f32_32x32x16_bf16 v[20:35], v[174:177], v[214:217], v[20:35]
	s_waitcnt vmcnt(21)
	ds_write_b128 v190, v[140:143]
	v_mfma_f32_32x32x16_bf16 v[4:19], v[174:177], v[178:181], v[4:19]
	s_waitcnt vmcnt(20)
	ds_write_b128 v190, v[198:201] offset:36864
	s_waitcnt lgkmcnt(4)
	v_mfma_f32_32x32x16_bf16 v[52:67], v[206:209], v[218:221], v[52:67]
	s_waitcnt vmcnt(19)
	ds_write_b128 v191, v[226:229]
	v_mfma_f32_32x32x16_bf16 v[36:51], v[206:209], v[222:225], v[36:51]
	s_waitcnt vmcnt(18)
	ds_write_b128 v191, v[230:233] offset:36864
	v_mfma_f32_32x32x16_bf16 v[20:35], v[210:213], v[218:221], v[20:35]
	s_waitcnt vmcnt(17)
	ds_write_b128 v192, v[242:245]
	v_mfma_f32_32x32x16_bf16 v[4:19], v[210:213], v[222:225], v[4:19]
	s_waitcnt vmcnt(16)
	ds_write_b128 v192, v[246:249] offset:36864
	s_waitcnt lgkmcnt(0)
	s_barrier
	ds_read_b128 v[174:177], v194
	ds_read_b128 v[178:181], v194 offset:32
	ds_read_b128 v[202:205], v194 offset:4608
	ds_read_b128 v[206:209], v194 offset:4640
	ds_read_b128 v[210:213], v195 offset:36864
	ds_read_b128 v[214:217], v195 offset:36896
	ds_read_b128 v[218:221], v195 offset:41472
	ds_read_b128 v[222:225], v195 offset:41504
	s_waitcnt lgkmcnt(3)
	v_mfma_f32_32x32x16_bf16 v[52:67], v[174:177], v[210:213], v[52:67]
	global_load_dwordx4 v[132:135], v[164:165], off offset:640
	s_waitcnt lgkmcnt(1)
	v_mfma_f32_32x32x16_bf16 v[36:51], v[174:177], v[218:221], v[36:51]
	global_load_dwordx4 v[136:139], v[162:163], off offset:640
	v_mfma_f32_32x32x16_bf16 v[4:19], v[202:205], v[218:221], v[4:19]
	global_load_dwordx4 v[140:143], v[160:161], off offset:640
	s_waitcnt lgkmcnt(0)
	v_mfma_f32_32x32x16_bf16 v[36:51], v[178:181], v[222:225], v[36:51]
	global_load_dwordx4 v[198:201], v[158:159], off offset:640
	v_mfma_f32_32x32x16_bf16 v[4:19], v[206:209], v[222:225], v[4:19]
	global_load_dwordx4 v[226:229], v[156:157], off offset:640
	ds_read_b128 v[222:225], v195 offset:41568
	ds_read_b128 v[174:177], v194 offset:4672
	v_mfma_f32_32x32x16_bf16 v[20:35], v[202:205], v[210:213], v[20:35]
	global_load_dwordx4 v[230:233], v[154:155], off offset:640
	ds_read_b128 v[210:213], v194 offset:4704
	ds_read_b128 v[202:205], v194 offset:64
	v_mfma_f32_32x32x16_bf16 v[52:67], v[178:181], v[214:217], v[52:67]
	global_load_dwordx4 v[242:245], v[152:153], off offset:640
	ds_read_b128 v[218:221], v195 offset:36960
	ds_read_b128 v[178:181], v195 offset:41536
	v_mfma_f32_32x32x16_bf16 v[20:35], v[206:209], v[214:217], v[20:35]
	global_load_dwordx4 v[246:249], v[146:147], off offset:640
	ds_read_b128 v[214:217], v195 offset:36928
	ds_read_b128 v[206:209], v194 offset:96
	s_waitcnt lgkmcnt(1)
	v_mfma_f32_32x32x16_bf16 v[52:67], v[202:205], v[214:217], v[52:67]
	s_waitcnt vmcnt(23)
	ds_write_b128 v167, v[68:71] offset:18432
	v_mfma_f32_32x32x16_bf16 v[36:51], v[202:205], v[178:181], v[36:51]
	s_waitcnt vmcnt(22)
	ds_write_b128 v167, v[72:75] offset:55296
	v_mfma_f32_32x32x16_bf16 v[20:35], v[174:177], v[214:217], v[20:35]
	s_waitcnt vmcnt(21)
	ds_write_b128 v190, v[76:79] offset:18432
	v_mfma_f32_32x32x16_bf16 v[4:19], v[174:177], v[178:181], v[4:19]
	s_waitcnt vmcnt(20)
	ds_write_b128 v190, v[80:83] offset:55296
	s_waitcnt lgkmcnt(4)
	v_mfma_f32_32x32x16_bf16 v[52:67], v[206:209], v[218:221], v[52:67]
	s_waitcnt vmcnt(19)
	ds_write_b128 v191, v[84:87] offset:18432
	v_mfma_f32_32x32x16_bf16 v[36:51], v[206:209], v[222:225], v[36:51]
	s_waitcnt vmcnt(18)
	ds_write_b128 v191, v[92:95] offset:55296
	v_mfma_f32_32x32x16_bf16 v[20:35], v[210:213], v[218:221], v[20:35]
	s_waitcnt vmcnt(17)
	ds_write_b128 v192, v[104:107] offset:18432
	v_mfma_f32_32x32x16_bf16 v[4:19], v[210:213], v[222:225], v[4:19]
	s_waitcnt vmcnt(16)
	ds_write_b128 v192, v[112:115] offset:55296
	s_waitcnt lgkmcnt(0)
	s_barrier
; #define MFMA(a, b, c) __builtin_amdgcn_mfma_f32_32x32x16_bf16((a), (b), (c), 0, 0, 0)
; template <class Epi, class ColV>
; DI void gemm_tile(const bf16_t* __restrict__ A, int lda, const bf16_t* __restrict__ Bt, int ldb, int K, int m0, int n0, unsigned char* smem, Epi epi, ColV colv, const bf16_t* __restrict__ HYT = nullptr) {
;     ...
;     auto gload = [&](u32x4 (&r)[8], int kt) {
; #pragma unroll
;         for (int i = 0; i < 4; ++i) { int id = tid + 256 * i, row = id >> 3, kc = id & 7;
;             if (HYT && kt >= 12) r[i] = *(const u32x4*)(HYT + (size_t)((kt - 12) * 64 + (id >> 4)) * NT + m0 + (id & 15) * 8);
;             else r[i] = *(const u32x4*)(A + (size_t)(m0 + row) * lda + kt * 64 + kc * 8);
;             r[4 + i] = *(const u32x4*)(Bt + (size_t)(n0 + row) * ldb + kt * 64 + kc * 8); }
;     };
;     auto sstore = [&](const u32x4 (&r)[8], int buf, int kt) {
; #pragma unroll
;         for (int i = 0; i < 4; ++i) { int id = tid + 256 * i, row = id >> 3, kc = id & 7;
;             if (HYT && kt >= 12) { const int kk = id >> 4, rr = (id & 15) * 8; bf16_t* d = As + (buf * 128 + rr) * LS + kk; const bf16x8 v = __builtin_bit_cast(bf16x8, r[i]);
; #pragma unroll
;                 for (int e = 0; e < 8; ++e) d[e * LS] = (bf16_t)v[e]; }
;             else *(u32x4*)(As + (buf * 128 + row) * LS + kc * 8) = r[i];
;             *(u32x4*)(Bs + (buf * 128 + row) * LS + kc * 8) = r[4 + i]; }
;     };
;     auto step = [&](int kt, u32x4 (&ldset)[8], const u32x4 (&stset)[8]) {
;         const int buf = kt & 1;
;         if (kt + 2 < nk) gload(ldset, kt + 2);
;         const bf16_t* Ab = As + (buf * 128 + 64 * wr + li) * LS + 8 * lh;
;         const bf16_t* Bb = Bs + (buf * 128 + 64 * wc + li) * LS + 8 * lh;
;         bf16x8 fa[2][2], fb[2][2], ga[2][2], gb[2][2];
; #pragma unroll
;         for (int k2 = 0; k2 < 2; ++k2) { fa[k2][0] = ld8(Ab + 16 * k2); fa[k2][1] = ld8(Ab + 32 * LS + 16 * k2); fb[k2][0] = ld8(Bb + 16 * k2); fb[k2][1] = ld8(Bb + 32 * LS + 16 * k2); }
;         __builtin_amdgcn_sched_barrier(0);
; #pragma unroll
;         for (int k2 = 0; k2 < 2; ++k2) {
;             acc[0][0] = MFMA(fa[k2][0], fb[k2][0], acc[0][0]); acc[0][1] = MFMA(fa[k2][0], fb[k2][1], acc[0][1]);
;             acc[1][0] = MFMA(fa[k2][1], fb[k2][0], acc[1][0]); acc[1][1] = MFMA(fa[k2][1], fb[k2][1], acc[1][1]);
;         }
; #pragma unroll
	ds_read_b128 v[174:177], v196
	ds_read_b128 v[178:181], v196 offset:32
	ds_read_b128 v[202:205], v196 offset:4608
	ds_read_b128 v[206:209], v196 offset:4640
	ds_read_b128 v[210:213], v197 offset:36864
	ds_read_b128 v[214:217], v197 offset:36896
	ds_read_b128 v[218:221], v197 offset:41472
	ds_read_b128 v[222:225], v197 offset:41504
	s_waitcnt lgkmcnt(3)
	v_mfma_f32_32x32x16_bf16 v[52:67], v[174:177], v[210:213], v[52:67]
	global_load_dwordx4 v[68:71], v[164:165], off offset:768
	s_waitcnt lgkmcnt(1)
	v_mfma_f32_32x32x16_bf16 v[36:51], v[174:177], v[218:221], v[36:51]
	global_load_dwordx4 v[72:75], v[162:163], off offset:768
	v_mfma_f32_32x32x16_bf16 v[4:19], v[202:205], v[218:221], v[4:19]
	global_load_dwordx4 v[76:79], v[160:161], off offset:768
	s_waitcnt lgkmcnt(0)
	v_mfma_f32_32x32x16_bf16 v[36:51], v[178:181], v[222:225], v[36:51]
	global_load_dwordx4 v[80:83], v[158:159], off offset:768
	v_mfma_f32_32x32x16_bf16 v[4:19], v[206:209], v[222:225], v[4:19]
	global_load_dwordx4 v[84:87], v[156:157], off offset:768
	ds_read_b128 v[222:225], v197 offset:41568
	ds_read_b128 v[174:177], v196 offset:4672
	v_mfma_f32_32x32x16_bf16 v[20:35], v[202:205], v[210:213], v[20:35]
	global_load_dwordx4 v[92:95], v[154:155], off offset:768
	ds_read_b128 v[210:213], v196 offset:4704
	ds_read_b128 v[202:205], v196 offset:64
	v_mfma_f32_32x32x16_bf16 v[52:67], v[178:181], v[214:217], v[52:67]
	global_load_dwordx4 v[104:107], v[152:153], off offset:768
	ds_read_b128 v[218:221], v197 offset:36960
	ds_read_b128 v[178:181], v197 offset:41536
	v_mfma_f32_32x32x16_bf16 v[20:35], v[206:209], v[214:217], v[20:35]
	global_load_dwordx4 v[112:115], v[146:147], off offset:768
	ds_read_b128 v[214:217], v197 offset:36928
	ds_read_b128 v[206:209], v196 offset:96
	s_waitcnt lgkmcnt(1)
	v_mfma_f32_32x32x16_bf16 v[52:67], v[202:205], v[214:217], v[52:67]
	s_waitcnt vmcnt(23)
	ds_write_b128 v167, v[88:91]
	v_mfma_f32_32x32x16_bf16 v[36:51], v[202:205], v[178:181], v[36:51]
	s_waitcnt vmcnt(22)
	ds_write_b128 v167, v[96:99] offset:36864
	v_mfma_f32_32x32x16_bf16 v[20:35], v[174:177], v[214:217], v[20:35]
	s_waitcnt vmcnt(21)
	ds_write_b128 v190, v[100:103]
	v_mfma_f32_32x32x16_bf16 v[4:19], v[174:177], v[178:181], v[4:19]
	s_waitcnt vmcnt(20)
	ds_write_b128 v190, v[108:111] offset:36864
	s_waitcnt lgkmcnt(4)
	v_mfma_f32_32x32x16_bf16 v[52:67], v[206:209], v[218:221], v[52:67]
	s_waitcnt vmcnt(19)
	ds_write_b128 v191, v[116:119]
	v_mfma_f32_32x32x16_bf16 v[36:51], v[206:209], v[222:225], v[36:51]
	s_waitcnt vmcnt(18)
	ds_write_b128 v191, v[120:123] offset:36864
	v_mfma_f32_32x32x16_bf16 v[20:35], v[210:213], v[218:221], v[20:35]
	s_waitcnt vmcnt(17)
	ds_write_b128 v192, v[124:127]
	v_mfma_f32_32x32x16_bf16 v[4:19], v[210:213], v[222:225], v[4:19]
	s_waitcnt vmcnt(16)
	ds_write_b128 v192, v[128:131] offset:36864
	s_waitcnt lgkmcnt(0)
	s_barrier
	ds_read_b128 v[174:177], v194
	ds_read_b128 v[178:181], v194 offset:32
	ds_read_b128 v[202:205], v194 offset:4608
	ds_read_b128 v[206:209], v194 offset:4640
	ds_read_b128 v[210:213], v195 offset:36864
	ds_read_b128 v[214:217], v195 offset:36896
	ds_read_b128 v[218:221], v195 offset:41472
	ds_read_b128 v[222:225], v195 offset:41504
	s_waitcnt lgkmcnt(3)
	v_mfma_f32_32x32x16_bf16 v[52:67], v[174:177], v[210:213], v[52:67]
	global_load_dwordx4 v[88:91], v[164:165], off offset:896
	s_waitcnt lgkmcnt(1)
	v_mfma_f32_32x32x16_bf16 v[36:51], v[174:177], v[218:221], v[36:51]
	global_load_dwordx4 v[96:99], v[162:163], off offset:896
	v_mfma_f32_32x32x16_bf16 v[4:19], v[202:205], v[218:221], v[4:19]
	global_load_dwordx4 v[100:103], v[160:161], off offset:896
	s_waitcnt lgkmcnt(0)
	v_mfma_f32_32x32x16_bf16 v[36:51], v[178:181], v[222:225], v[36:51]
	global_load_dwordx4 v[108:111], v[158:159], off offset:896
	v_mfma_f32_32x32x16_bf16 v[4:19], v[206:209], v[222:225], v[4:19]
	global_load_dwordx4 v[116:119], v[156:157], off offset:896
	ds_read_b128 v[222:225], v195 offset:41568
	ds_read_b128 v[174:177], v194 offset:4672
	v_mfma_f32_32x32x16_bf16 v[20:35], v[202:205], v[210:213], v[20:35]
	global_load_dwordx4 v[120:123], v[154:155], off offset:896
	ds_read_b128 v[210:213], v194 offset:4704
	ds_read_b128 v[202:205], v194 offset:64
	v_mfma_f32_32x32x16_bf16 v[52:67], v[178:181], v[214:217], v[52:67]
	global_load_dwordx4 v[124:127], v[152:153], off offset:896
	ds_read_b128 v[218:221], v195 offset:36960
	ds_read_b128 v[178:181], v195 offset:41536
	v_mfma_f32_32x32x16_bf16 v[20:35], v[206:209], v[214:217], v[20:35]
	global_load_dwordx4 v[128:131], v[146:147], off offset:896
	ds_read_b128 v[214:217], v195 offset:36928
	ds_read_b128 v[206:209], v194 offset:96
	s_waitcnt lgkmcnt(1)
	v_mfma_f32_32x32x16_bf16 v[52:67], v[202:205], v[214:217], v[52:67]
	s_waitcnt vmcnt(23)
	ds_write_b128 v167, v[132:135] offset:18432
	v_mfma_f32_32x32x16_bf16 v[36:51], v[202:205], v[178:181], v[36:51]
	s_waitcnt vmcnt(22)
	ds_write_b128 v167, v[136:139] offset:55296
	v_mfma_f32_32x32x16_bf16 v[20:35], v[174:177], v[214:217], v[20:35]
	s_waitcnt vmcnt(21)
	ds_write_b128 v190, v[140:143] offset:18432
	v_mfma_f32_32x32x16_bf16 v[4:19], v[174:177], v[178:181], v[4:19]
	s_waitcnt vmcnt(20)
	ds_write_b128 v190, v[198:201] offset:55296
	s_waitcnt lgkmcnt(4)
	v_mfma_f32_32x32x16_bf16 v[52:67], v[206:209], v[218:221], v[52:67]
	s_waitcnt vmcnt(19)
	ds_write_b128 v191, v[226:229] offset:18432
	v_mfma_f32_32x32x16_bf16 v[36:51], v[206:209], v[222:225], v[36:51]
	s_waitcnt vmcnt(18)
	ds_write_b128 v191, v[230:233] offset:55296
	v_mfma_f32_32x32x16_bf16 v[20:35], v[210:213], v[218:221], v[20:35]
	s_waitcnt vmcnt(17)
	ds_write_b128 v192, v[242:245] offset:18432
	v_mfma_f32_32x32x16_bf16 v[4:19], v[210:213], v[222:225], v[4:19]
	s_waitcnt vmcnt(16)
	ds_write_b128 v192, v[246:249] offset:55296
	s_waitcnt lgkmcnt(0)
	s_barrier
; #define MFMA(a, b, c) __builtin_amdgcn_mfma_f32_32x32x16_bf16((a), (b), (c), 0, 0, 0)
; template <class Epi, class ColV>
; DI void gemm_tile(const bf16_t* __restrict__ A, int lda, const bf16_t* __restrict__ Bt, int ldb, int K, int m0, int n0, unsigned char* smem, Epi epi, ColV colv, const bf16_t* __restrict__ HYT = nullptr) {
;     ...
;     auto gload = [&](u32x4 (&r)[8], int kt) {
; #pragma unroll
;         for (int i = 0; i < 4; ++i) { int id = tid + 256 * i, row = id >> 3, kc = id & 7;
;             if (HYT && kt >= 12) r[i] = *(const u32x4*)(HYT + (size_t)((kt - 12) * 64 + (id >> 4)) * NT + m0 + (id & 15) * 8);
;             else r[i] = *(const u32x4*)(A + (size_t)(m0 + row) * lda + kt * 64 + kc * 8);
;             r[4 + i] = *(const u32x4*)(Bt + (size_t)(n0 + row) * ldb + kt * 64 + kc * 8); }
;     };
;     auto sstore = [&](const u32x4 (&r)[8], int buf, int kt) {
; #pragma unroll
;         for (int i = 0; i < 4; ++i) { int id = tid + 256 * i, row = id >> 3, kc = id & 7;
;             if (HYT && kt >= 12) { const int kk = id >> 4, rr = (id & 15) * 8; bf16_t* d = As + (buf * 128 + rr) * LS + kk; const bf16x8 v = __builtin_bit_cast(bf16x8, r[i]);
; #pragma unroll
;                 for (int e = 0; e < 8; ++e) d[e * LS] = (bf16_t)v[e]; }
;             else *(u32x4*)(As + (buf * 128 + row) * LS + kc * 8) = r[i];
;             *(u32x4*)(Bs + (buf * 128 + row) * LS + kc * 8) = r[4 + i]; }
;     };
;     auto step = [&](int kt, u32x4 (&ldset)[8], const u32x4 (&stset)[8]) {
;         const int buf = kt & 1;
;         if (kt + 2 < nk) gload(ldset, kt + 2);
;         const bf16_t* Ab = As + (buf * 128 + 64 * wr + li) * LS + 8 * lh;
;         const bf16_t* Bb = Bs + (buf * 128 + 64 * wc + li) * LS + 8 * lh;
;         bf16x8 fa[2][2], fb[2][2], ga[2][2], gb[2][2];
; #pragma unroll
;         for (int k2 = 0; k2 < 2; ++k2) { fa[k2][0] = ld8(Ab + 16 * k2); fa[k2][1] = ld8(Ab + 32 * LS + 16 * k2); fb[k2][0] = ld8(Bb + 16 * k2); fb[k2][1] = ld8(Bb + 32 * LS + 16 * k2); }
;         __builtin_amdgcn_sched_barrier(0);
; #pragma unroll
;         for (int k2 = 0; k2 < 2; ++k2) {
;             acc[0][0] = MFMA(fa[k2][0], fb[k2][0], acc[0][0]); acc[0][1] = MFMA(fa[k2][0], fb[k2][1], acc[0][1]);
;             acc[1][0] = MFMA(fa[k2][1], fb[k2][0], acc[1][0]); acc[1][1] = MFMA(fa[k2][1], fb[k2][1], acc[1][1]);
;         }
; #pragma unroll
	ds_read_b128 v[174:177], v196
	ds_read_b128 v[178:181], v196 offset:32
	ds_read_b128 v[202:205], v196 offset:4608
	ds_read_b128 v[206:209], v196 offset:4640
	ds_read_b128 v[210:213], v197 offset:36864
	ds_read_b128 v[214:217], v197 offset:36896
	ds_read_b128 v[218:221], v197 offset:41472
	ds_read_b128 v[222:225], v197 offset:41504
	s_waitcnt lgkmcnt(3)
	v_mfma_f32_32x32x16_bf16 v[52:67], v[174:177], v[210:213], v[52:67]
	global_load_dwordx4 v[132:135], v[164:165], off offset:1024
	s_waitcnt lgkmcnt(1)
	v_mfma_f32_32x32x16_bf16 v[36:51], v[174:177], v[218:221], v[36:51]
	global_load_dwordx4 v[136:139], v[162:163], off offset:1024
	v_mfma_f32_32x32x16_bf16 v[4:19], v[202:205], v[218:221], v[4:19]
	global_load_dwordx4 v[140:143], v[160:161], off offset:1024
	s_waitcnt lgkmcnt(0)
	v_mfma_f32_32x32x16_bf16 v[36:51], v[178:181], v[222:225], v[36:51]
	global_load_dwordx4 v[198:201], v[158:159], off offset:1024
	v_mfma_f32_32x32x16_bf16 v[4:19], v[206:209], v[222:225], v[4:19]
	global_load_dwordx4 v[226:229], v[156:157], off offset:1024
	ds_read_b128 v[222:225], v197 offset:41568
	ds_read_b128 v[174:177], v196 offset:4672
	v_mfma_f32_32x32x16_bf16 v[20:35], v[202:205], v[210:213], v[20:35]
	global_load_dwordx4 v[230:233], v[154:155], off offset:1024
	ds_read_b128 v[210:213], v196 offset:4704
	ds_read_b128 v[202:205], v196 offset:64
	v_mfma_f32_32x32x16_bf16 v[52:67], v[178:181], v[214:217], v[52:67]
	global_load_dwordx4 v[242:245], v[152:153], off offset:1024
	ds_read_b128 v[218:221], v197 offset:36960
	ds_read_b128 v[178:181], v197 offset:41536
	v_mfma_f32_32x32x16_bf16 v[20:35], v[206:209], v[214:217], v[20:35]
	global_load_dwordx4 v[246:249], v[146:147], off offset:1024
	ds_read_b128 v[214:217], v197 offset:36928
	ds_read_b128 v[206:209], v196 offset:96
	s_waitcnt lgkmcnt(1)
	v_mfma_f32_32x32x16_bf16 v[52:67], v[202:205], v[214:217], v[52:67]
	s_waitcnt vmcnt(23)
	ds_write_b128 v167, v[68:71]
	v_mfma_f32_32x32x16_bf16 v[36:51], v[202:205], v[178:181], v[36:51]
	s_waitcnt vmcnt(22)
	ds_write_b128 v167, v[72:75] offset:36864
	v_mfma_f32_32x32x16_bf16 v[20:35], v[174:177], v[214:217], v[20:35]
	s_waitcnt vmcnt(21)
	ds_write_b128 v190, v[76:79]
	v_mfma_f32_32x32x16_bf16 v[4:19], v[174:177], v[178:181], v[4:19]
	s_waitcnt vmcnt(20)
	ds_write_b128 v190, v[80:83] offset:36864
	s_waitcnt lgkmcnt(4)
	v_mfma_f32_32x32x16_bf16 v[52:67], v[206:209], v[218:221], v[52:67]
	s_waitcnt vmcnt(19)
	ds_write_b128 v191, v[84:87]
	v_mfma_f32_32x32x16_bf16 v[36:51], v[206:209], v[222:225], v[36:51]
	s_waitcnt vmcnt(18)
	ds_write_b128 v191, v[92:95] offset:36864
	v_mfma_f32_32x32x16_bf16 v[20:35], v[210:213], v[218:221], v[20:35]
	s_waitcnt vmcnt(17)
	ds_write_b128 v192, v[104:107]
	v_mfma_f32_32x32x16_bf16 v[4:19], v[210:213], v[222:225], v[4:19]
	s_waitcnt vmcnt(16)
	ds_write_b128 v192, v[112:115] offset:36864
	s_waitcnt lgkmcnt(0)
	s_barrier
	ds_read_b128 v[174:177], v194
	ds_read_b128 v[178:181], v194 offset:32
	ds_read_b128 v[202:205], v194 offset:4608
	ds_read_b128 v[206:209], v194 offset:4640
	ds_read_b128 v[210:213], v195 offset:36864
	ds_read_b128 v[214:217], v195 offset:36896
	ds_read_b128 v[218:221], v195 offset:41472
	ds_read_b128 v[222:225], v195 offset:41504
	s_waitcnt lgkmcnt(3)
	v_mfma_f32_32x32x16_bf16 v[52:67], v[174:177], v[210:213], v[52:67]
	global_load_dwordx4 v[68:71], v[164:165], off offset:1152
	s_waitcnt lgkmcnt(1)
	v_mfma_f32_32x32x16_bf16 v[36:51], v[174:177], v[218:221], v[36:51]
	global_load_dwordx4 v[72:75], v[162:163], off offset:1152
	v_mfma_f32_32x32x16_bf16 v[4:19], v[202:205], v[218:221], v[4:19]
	global_load_dwordx4 v[76:79], v[160:161], off offset:1152
	s_waitcnt lgkmcnt(0)
	v_mfma_f32_32x32x16_bf16 v[36:51], v[178:181], v[222:225], v[36:51]
	global_load_dwordx4 v[80:83], v[158:159], off offset:1152
	v_mfma_f32_32x32x16_bf16 v[4:19], v[206:209], v[222:225], v[4:19]
	global_load_dwordx4 v[84:87], v[156:157], off offset:1152
	ds_read_b128 v[222:225], v195 offset:41568
	ds_read_b128 v[174:177], v194 offset:4672
	v_mfma_f32_32x32x16_bf16 v[20:35], v[202:205], v[210:213], v[20:35]
	global_load_dwordx4 v[92:95], v[154:155], off offset:1152
	ds_read_b128 v[210:213], v194 offset:4704
	ds_read_b128 v[202:205], v194 offset:64
	v_mfma_f32_32x32x16_bf16 v[52:67], v[178:181], v[214:217], v[52:67]
	global_load_dwordx4 v[104:107], v[152:153], off offset:1152
	ds_read_b128 v[218:221], v195 offset:36960
	ds_read_b128 v[178:181], v195 offset:41536
	v_mfma_f32_32x32x16_bf16 v[20:35], v[206:209], v[214:217], v[20:35]
	global_load_dwordx4 v[112:115], v[146:147], off offset:1152
	ds_read_b128 v[214:217], v195 offset:36928
	ds_read_b128 v[206:209], v194 offset:96
	s_waitcnt lgkmcnt(1)
	v_mfma_f32_32x32x16_bf16 v[52:67], v[202:205], v[214:217], v[52:67]
	s_waitcnt vmcnt(23)
	ds_write_b128 v167, v[88:91] offset:18432
	v_mfma_f32_32x32x16_bf16 v[36:51], v[202:205], v[178:181], v[36:51]
	s_waitcnt vmcnt(22)
	ds_write_b128 v167, v[96:99] offset:55296
	v_mfma_f32_32x32x16_bf16 v[20:35], v[174:177], v[214:217], v[20:35]
	s_waitcnt vmcnt(21)
	ds_write_b128 v190, v[100:103] offset:18432
	v_mfma_f32_32x32x16_bf16 v[4:19], v[174:177], v[178:181], v[4:19]
	s_waitcnt vmcnt(20)
	ds_write_b128 v190, v[108:111] offset:55296
	s_waitcnt lgkmcnt(4)
	v_mfma_f32_32x32x16_bf16 v[52:67], v[206:209], v[218:221], v[52:67]
	s_waitcnt vmcnt(19)
	ds_write_b128 v191, v[116:119] offset:18432
	v_mfma_f32_32x32x16_bf16 v[36:51], v[206:209], v[222:225], v[36:51]
	s_waitcnt vmcnt(18)
	ds_write_b128 v191, v[120:123] offset:55296
	v_mfma_f32_32x32x16_bf16 v[20:35], v[210:213], v[218:221], v[20:35]
	s_waitcnt vmcnt(17)
	ds_write_b128 v192, v[124:127] offset:18432
	v_mfma_f32_32x32x16_bf16 v[4:19], v[210:213], v[222:225], v[4:19]
	s_waitcnt vmcnt(16)
	ds_write_b128 v192, v[128:131] offset:55296
	s_waitcnt lgkmcnt(0)
	s_barrier
; #define MFMA(a, b, c) __builtin_amdgcn_mfma_f32_32x32x16_bf16((a), (b), (c), 0, 0, 0)
; template <class Epi, class ColV>
; DI void gemm_tile(const bf16_t* __restrict__ A, int lda, const bf16_t* __restrict__ Bt, int ldb, int K, int m0, int n0, unsigned char* smem, Epi epi, ColV colv, const bf16_t* __restrict__ HYT = nullptr) {
;     ...
;     auto gload = [&](u32x4 (&r)[8], int kt) {
; #pragma unroll
;         for (int i = 0; i < 4; ++i) { int id = tid + 256 * i, row = id >> 3, kc = id & 7;
;             if (HYT && kt >= 12) r[i] = *(const u32x4*)(HYT + (size_t)((kt - 12) * 64 + (id >> 4)) * NT + m0 + (id & 15) * 8);
;             else r[i] = *(const u32x4*)(A + (size_t)(m0 + row) * lda + kt * 64 + kc * 8);
;             r[4 + i] = *(const u32x4*)(Bt + (size_t)(n0 + row) * ldb + kt * 64 + kc * 8); }
;     };
;     auto sstore = [&](const u32x4 (&r)[8], int buf, int kt) {
; #pragma unroll
;         for (int i = 0; i < 4; ++i) { int id = tid + 256 * i, row = id >> 3, kc = id & 7;
;             if (HYT && kt >= 12) { const int kk = id >> 4, rr = (id & 15) * 8; bf16_t* d = As + (buf * 128 + rr) * LS + kk; const bf16x8 v = __builtin_bit_cast(bf16x8, r[i]);
; #pragma unroll
;                 for (int e = 0; e < 8; ++e) d[e * LS] = (bf16_t)v[e]; }
;             else *(u32x4*)(As + (buf * 128 + row) * LS + kc * 8) = r[i];
;             *(u32x4*)(Bs + (buf * 128 + row) * LS + kc * 8) = r[4 + i]; }
;     };
;     auto step = [&](int kt, u32x4 (&ldset)[8], const u32x4 (&stset)[8]) {
;         const int buf = kt & 1;
;         if (kt + 2 < nk) gload(ldset, kt + 2);
;         const bf16_t* Ab = As + (buf * 128 + 64 * wr + li) * LS + 8 * lh;
;         const bf16_t* Bb = Bs + (buf * 128 + 64 * wc + li) * LS + 8 * lh;
;         bf16x8 fa[2][2], fb[2][2], ga[2][2], gb[2][2];
; #pragma unroll
;         for (int k2 = 0; k2 < 2; ++k2) { fa[k2][0] = ld8(Ab + 16 * k2); fa[k2][1] = ld8(Ab + 32 * LS + 16 * k2); fb[k2][0] = ld8(Bb + 16 * k2); fb[k2][1] = ld8(Bb + 32 * LS + 16 * k2); }
;         __builtin_amdgcn_sched_barrier(0);
; #pragma unroll
;         for (int k2 = 0; k2 < 2; ++k2) {
;             acc[0][0] = MFMA(fa[k2][0], fb[k2][0], acc[0][0]); acc[0][1] = MFMA(fa[k2][0], fb[k2][1], acc[0][1]);
;             acc[1][0] = MFMA(fa[k2][1], fb[k2][0], acc[1][0]); acc[1][1] = MFMA(fa[k2][1], fb[k2][1], acc[1][1]);
;         }
; #pragma unroll
	ds_read_b128 v[174:177], v196
	ds_read_b128 v[178:181], v196 offset:32
	ds_read_b128 v[202:205], v196 offset:4608
	ds_read_b128 v[206:209], v196 offset:4640
	ds_read_b128 v[210:213], v197 offset:36864
	ds_read_b128 v[214:217], v197 offset:36896
	ds_read_b128 v[218:221], v197 offset:41472
	ds_read_b128 v[222:225], v197 offset:41504
	s_waitcnt lgkmcnt(3)
	v_mfma_f32_32x32x16_bf16 v[52:67], v[174:177], v[210:213], v[52:67]
	global_load_dwordx4 v[88:91], v[164:165], off offset:1280
	s_waitcnt lgkmcnt(1)
	v_mfma_f32_32x32x16_bf16 v[36:51], v[174:177], v[218:221], v[36:51]
	global_load_dwordx4 v[96:99], v[162:163], off offset:1280
	v_mfma_f32_32x32x16_bf16 v[4:19], v[202:205], v[218:221], v[4:19]
	global_load_dwordx4 v[100:103], v[160:161], off offset:1280
	s_waitcnt lgkmcnt(0)
	v_mfma_f32_32x32x16_bf16 v[36:51], v[178:181], v[222:225], v[36:51]
	global_load_dwordx4 v[108:111], v[158:159], off offset:1280
	v_mfma_f32_32x32x16_bf16 v[4:19], v[206:209], v[222:225], v[4:19]
	global_load_dwordx4 v[116:119], v[156:157], off offset:1280
	ds_read_b128 v[222:225], v197 offset:41568
	ds_read_b128 v[174:177], v196 offset:4672
	v_mfma_f32_32x32x16_bf16 v[20:35], v[202:205], v[210:213], v[20:35]
	global_load_dwordx4 v[120:123], v[154:155], off offset:1280
	ds_read_b128 v[210:213], v196 offset:4704
	ds_read_b128 v[202:205], v196 offset:64
	v_mfma_f32_32x32x16_bf16 v[52:67], v[178:181], v[214:217], v[52:67]
	global_load_dwordx4 v[124:127], v[152:153], off offset:1280
	ds_read_b128 v[218:221], v197 offset:36960
	ds_read_b128 v[178:181], v197 offset:41536
	v_mfma_f32_32x32x16_bf16 v[20:35], v[206:209], v[214:217], v[20:35]
	global_load_dwordx4 v[128:131], v[146:147], off offset:1280
	ds_read_b128 v[214:217], v197 offset:36928
	ds_read_b128 v[206:209], v196 offset:96
	s_waitcnt lgkmcnt(1)
	v_mfma_f32_32x32x16_bf16 v[52:67], v[202:205], v[214:217], v[52:67]
	s_waitcnt vmcnt(23)
	ds_write_b128 v167, v[132:135]
	v_mfma_f32_32x32x16_bf16 v[36:51], v[202:205], v[178:181], v[36:51]
	s_waitcnt vmcnt(22)
	ds_write_b128 v167, v[136:139] offset:36864
	v_mfma_f32_32x32x16_bf16 v[20:35], v[174:177], v[214:217], v[20:35]
	s_waitcnt vmcnt(21)
	ds_write_b128 v190, v[140:143]
	v_mfma_f32_32x32x16_bf16 v[4:19], v[174:177], v[178:181], v[4:19]
	s_waitcnt vmcnt(20)
	ds_write_b128 v190, v[198:201] offset:36864
	s_waitcnt lgkmcnt(4)
	v_mfma_f32_32x32x16_bf16 v[52:67], v[206:209], v[218:221], v[52:67]
	s_waitcnt vmcnt(19)
	ds_write_b128 v191, v[226:229]
	v_mfma_f32_32x32x16_bf16 v[36:51], v[206:209], v[222:225], v[36:51]
	s_waitcnt vmcnt(18)
	ds_write_b128 v191, v[230:233] offset:36864
	v_mfma_f32_32x32x16_bf16 v[20:35], v[210:213], v[218:221], v[20:35]
	s_waitcnt vmcnt(17)
	ds_write_b128 v192, v[242:245]
	v_mfma_f32_32x32x16_bf16 v[4:19], v[210:213], v[222:225], v[4:19]
	s_waitcnt vmcnt(16)
	ds_write_b128 v192, v[246:249] offset:36864
	s_waitcnt lgkmcnt(0)
	s_barrier
	ds_read_b128 v[174:177], v194
	ds_read_b128 v[178:181], v194 offset:32
	ds_read_b128 v[202:205], v194 offset:4608
	ds_read_b128 v[206:209], v194 offset:4640
	ds_read_b128 v[210:213], v195 offset:36864
	ds_read_b128 v[214:217], v195 offset:36896
	ds_read_b128 v[218:221], v195 offset:41472
	ds_read_b128 v[222:225], v195 offset:41504
	s_waitcnt lgkmcnt(3)
	v_mfma_f32_32x32x16_bf16 v[52:67], v[174:177], v[210:213], v[52:67]
	global_load_dwordx4 v[132:135], v[164:165], off offset:1408
	s_waitcnt lgkmcnt(1)
	v_mfma_f32_32x32x16_bf16 v[36:51], v[174:177], v[218:221], v[36:51]
	global_load_dwordx4 v[136:139], v[162:163], off offset:1408
	v_mfma_f32_32x32x16_bf16 v[4:19], v[202:205], v[218:221], v[4:19]
	global_load_dwordx4 v[140:143], v[160:161], off offset:1408
	s_waitcnt lgkmcnt(0)
	v_mfma_f32_32x32x16_bf16 v[36:51], v[178:181], v[222:225], v[36:51]
	global_load_dwordx4 v[198:201], v[158:159], off offset:1408
	v_mfma_f32_32x32x16_bf16 v[4:19], v[206:209], v[222:225], v[4:19]
	global_load_dwordx4 v[226:229], v[156:157], off offset:1408
	ds_read_b128 v[222:225], v195 offset:41568
	ds_read_b128 v[174:177], v194 offset:4672
	v_mfma_f32_32x32x16_bf16 v[20:35], v[202:205], v[210:213], v[20:35]
	global_load_dwordx4 v[230:233], v[154:155], off offset:1408
	ds_read_b128 v[210:213], v194 offset:4704
	ds_read_b128 v[202:205], v194 offset:64
	v_mfma_f32_32x32x16_bf16 v[52:67], v[178:181], v[214:217], v[52:67]
	global_load_dwordx4 v[242:245], v[152:153], off offset:1408
	ds_read_b128 v[218:221], v195 offset:36960
	ds_read_b128 v[178:181], v195 offset:41536
	v_mfma_f32_32x32x16_bf16 v[20:35], v[206:209], v[214:217], v[20:35]
	global_load_dwordx4 v[246:249], v[146:147], off offset:1408
	ds_read_b128 v[214:217], v195 offset:36928
	ds_read_b128 v[206:209], v194 offset:96
	s_waitcnt lgkmcnt(1)
	v_mfma_f32_32x32x16_bf16 v[52:67], v[202:205], v[214:217], v[52:67]
	s_waitcnt vmcnt(23)
	ds_write_b128 v167, v[68:71] offset:18432
	v_mfma_f32_32x32x16_bf16 v[36:51], v[202:205], v[178:181], v[36:51]
	s_waitcnt vmcnt(22)
	ds_write_b128 v167, v[72:75] offset:55296
	v_mfma_f32_32x32x16_bf16 v[20:35], v[174:177], v[214:217], v[20:35]
	s_waitcnt vmcnt(21)
	ds_write_b128 v190, v[76:79] offset:18432
	v_mfma_f32_32x32x16_bf16 v[4:19], v[174:177], v[178:181], v[4:19]
	s_waitcnt vmcnt(20)
	ds_write_b128 v190, v[80:83] offset:55296
	s_waitcnt lgkmcnt(4)
	v_mfma_f32_32x32x16_bf16 v[52:67], v[206:209], v[218:221], v[52:67]
	s_waitcnt vmcnt(19)
	ds_write_b128 v191, v[84:87] offset:18432
	v_mfma_f32_32x32x16_bf16 v[36:51], v[206:209], v[222:225], v[36:51]
	s_waitcnt vmcnt(18)
	ds_write_b128 v191, v[92:95] offset:55296
	v_mfma_f32_32x32x16_bf16 v[20:35], v[210:213], v[218:221], v[20:35]
	s_waitcnt vmcnt(17)
	ds_write_b128 v192, v[104:107] offset:18432
	v_mfma_f32_32x32x16_bf16 v[4:19], v[210:213], v[222:225], v[4:19]
	s_waitcnt vmcnt(16)
	ds_write_b128 v192, v[112:115] offset:55296
	s_waitcnt lgkmcnt(0)
	s_barrier
; #define MFMA(a, b, c) __builtin_amdgcn_mfma_f32_32x32x16_bf16((a), (b), (c), 0, 0, 0)
; template <class Epi, class ColV>
; DI void gemm_tile(const bf16_t* __restrict__ A, int lda, const bf16_t* __restrict__ Bt, int ldb, int K, int m0, int n0, unsigned char* smem, Epi epi, ColV colv, const bf16_t* __restrict__ HYT = nullptr) {
;     ...
;     auto gload = [&](u32x4 (&r)[8], int kt) {
; #pragma unroll
;         for (int i = 0; i < 4; ++i) { int id = tid + 256 * i, row = id >> 3, kc = id & 7;
;             if (HYT && kt >= 12) r[i] = *(const u32x4*)(HYT + (size_t)((kt - 12) * 64 + (id >> 4)) * NT + m0 + (id & 15) * 8);
;             else r[i] = *(const u32x4*)(A + (size_t)(m0 + row) * lda + kt * 64 + kc * 8);
;             r[4 + i] = *(const u32x4*)(Bt + (size_t)(n0 + row) * ldb + kt * 64 + kc * 8); }
;     };
;     auto sstore = [&](const u32x4 (&r)[8], int buf, int kt) {
; #pragma unroll
;         for (int i = 0; i < 4; ++i) { int id = tid + 256 * i, row = id >> 3, kc = id & 7;
;             if (HYT && kt >= 12) { const int kk = id >> 4, rr = (id & 15) * 8; bf16_t* d = As + (buf * 128 + rr) * LS + kk; const bf16x8 v = __builtin_bit_cast(bf16x8, r[i]);
; #pragma unroll
;                 for (int e = 0; e < 8; ++e) d[e * LS] = (bf16_t)v[e]; }
;             else *(u32x4*)(As + (buf * 128 + row) * LS + kc * 8) = r[i];
;             *(u32x4*)(Bs + (buf * 128 + row) * LS + kc * 8) = r[4 + i]; }
;     };
;     auto step = [&](int kt, u32x4 (&ldset)[8], const u32x4 (&stset)[8]) {
;         const int buf = kt & 1;
;         if (kt + 2 < nk) gload(ldset, kt + 2);
;         const bf16_t* Ab = As + (buf * 128 + 64 * wr + li) * LS + 8 * lh;
;         const bf16_t* Bb = Bs + (buf * 128 + 64 * wc + li) * LS + 8 * lh;
;         bf16x8 fa[2][2], fb[2][2], ga[2][2], gb[2][2];
; #pragma unroll
;         for (int k2 = 0; k2 < 2; ++k2) { fa[k2][0] = ld8(Ab + 16 * k2); fa[k2][1] = ld8(Ab + 32 * LS + 16 * k2); fb[k2][0] = ld8(Bb + 16 * k2); fb[k2][1] = ld8(Bb + 32 * LS + 16 * k2); }
;         __builtin_amdgcn_sched_barrier(0);
; #pragma unroll
;         for (int k2 = 0; k2 < 2; ++k2) {
;             acc[0][0] = MFMA(fa[k2][0], fb[k2][0], acc[0][0]); acc[0][1] = MFMA(fa[k2][0], fb[k2][1], acc[0][1]);
;             acc[1][0] = MFMA(fa[k2][1], fb[k2][0], acc[1][0]); acc[1][1] = MFMA(fa[k2][1], fb[k2][1], acc[1][1]);
;         }
; #pragma unroll
	ds_read_b128 v[174:177], v196
	ds_read_b128 v[178:181], v196 offset:32
	ds_read_b128 v[202:205], v196 offset:4608
	ds_read_b128 v[206:209], v196 offset:4640
	ds_read_b128 v[210:213], v197 offset:36864
	ds_read_b128 v[214:217], v197 offset:36896
	ds_read_b128 v[218:221], v197 offset:41472
	ds_read_b128 v[222:225], v197 offset:41504
	s_waitcnt lgkmcnt(3)
	v_mfma_f32_32x32x16_bf16 v[52:67], v[174:177], v[210:213], v[52:67]
	global_load_dwordx4 v[68:71], v[164:165], off offset:1536
	s_waitcnt lgkmcnt(1)
	v_mfma_f32_32x32x16_bf16 v[36:51], v[174:177], v[218:221], v[36:51]
	global_load_dwordx4 v[72:75], v[162:163], off offset:1536
	v_mfma_f32_32x32x16_bf16 v[4:19], v[202:205], v[218:221], v[4:19]
	global_load_dwordx4 v[76:79], v[160:161], off offset:1536
	s_waitcnt lgkmcnt(0)
	v_mfma_f32_32x32x16_bf16 v[36:51], v[178:181], v[222:225], v[36:51]
	global_load_dwordx4 v[80:83], v[158:159], off offset:1536
	v_mfma_f32_32x32x16_bf16 v[4:19], v[206:209], v[222:225], v[4:19]
	global_load_dwordx4 v[84:87], v[156:157], off offset:1536
	ds_read_b128 v[222:225], v197 offset:41568
	ds_read_b128 v[174:177], v196 offset:4672
	v_mfma_f32_32x32x16_bf16 v[20:35], v[202:205], v[210:213], v[20:35]
	global_load_dwordx4 v[92:95], v[154:155], off offset:1536
	ds_read_b128 v[210:213], v196 offset:4704
	ds_read_b128 v[202:205], v196 offset:64
	v_mfma_f32_32x32x16_bf16 v[52:67], v[178:181], v[214:217], v[52:67]
	global_load_dwordx4 v[104:107], v[152:153], off offset:1536
	ds_read_b128 v[218:221], v197 offset:36960
	ds_read_b128 v[178:181], v197 offset:41536
	v_mfma_f32_32x32x16_bf16 v[20:35], v[206:209], v[214:217], v[20:35]
	global_load_dwordx4 v[112:115], v[146:147], off offset:1536
	ds_read_b128 v[214:217], v197 offset:36928
	ds_read_b128 v[206:209], v196 offset:96
	s_waitcnt lgkmcnt(1)
	v_mfma_f32_32x32x16_bf16 v[52:67], v[202:205], v[214:217], v[52:67]
	s_waitcnt vmcnt(23)
	ds_write_b128 v167, v[88:91]
	v_mfma_f32_32x32x16_bf16 v[36:51], v[202:205], v[178:181], v[36:51]
	s_waitcnt vmcnt(22)
	ds_write_b128 v167, v[96:99] offset:36864
	v_mfma_f32_32x32x16_bf16 v[20:35], v[174:177], v[214:217], v[20:35]
	s_waitcnt vmcnt(21)
	ds_write_b128 v190, v[100:103]
	v_mfma_f32_32x32x16_bf16 v[4:19], v[174:177], v[178:181], v[4:19]
	s_waitcnt vmcnt(20)
	ds_write_b128 v190, v[108:111] offset:36864
	s_waitcnt lgkmcnt(4)
	v_mfma_f32_32x32x16_bf16 v[52:67], v[206:209], v[218:221], v[52:67]
	s_waitcnt vmcnt(19)
	ds_write_b128 v191, v[116:119]
	v_mfma_f32_32x32x16_bf16 v[36:51], v[206:209], v[222:225], v[36:51]
	s_waitcnt vmcnt(18)
	ds_write_b128 v191, v[120:123] offset:36864
	v_mfma_f32_32x32x16_bf16 v[20:35], v[210:213], v[218:221], v[20:35]
	s_waitcnt vmcnt(17)
	ds_write_b128 v192, v[124:127]
	v_mfma_f32_32x32x16_bf16 v[4:19], v[210:213], v[222:225], v[4:19]
	s_waitcnt vmcnt(16)
	ds_write_b128 v192, v[128:131] offset:36864
	s_waitcnt lgkmcnt(0)
	s_barrier
	ds_read_b128 v[174:177], v194
	ds_read_b128 v[178:181], v194 offset:32
	ds_read_b128 v[202:205], v194 offset:4608
	ds_read_b128 v[206:209], v194 offset:4640
	ds_read_b128 v[210:213], v195 offset:36864
	ds_read_b128 v[214:217], v195 offset:36896
	ds_read_b128 v[218:221], v195 offset:41472
	ds_read_b128 v[222:225], v195 offset:41504
	s_waitcnt lgkmcnt(3)
	v_mfma_f32_32x32x16_bf16 v[52:67], v[174:177], v[210:213], v[52:67]
	global_load_dwordx4 v[88:91], v[164:165], off offset:1664
	s_waitcnt lgkmcnt(1)
	v_mfma_f32_32x32x16_bf16 v[36:51], v[174:177], v[218:221], v[36:51]
	global_load_dwordx4 v[96:99], v[162:163], off offset:1664
	v_mfma_f32_32x32x16_bf16 v[4:19], v[202:205], v[218:221], v[4:19]
	global_load_dwordx4 v[100:103], v[160:161], off offset:1664
	s_waitcnt lgkmcnt(0)
	v_mfma_f32_32x32x16_bf16 v[36:51], v[178:181], v[222:225], v[36:51]
	global_load_dwordx4 v[108:111], v[158:159], off offset:1664
	v_mfma_f32_32x32x16_bf16 v[4:19], v[206:209], v[222:225], v[4:19]
	global_load_dwordx4 v[116:119], v[156:157], off offset:1664
	ds_read_b128 v[222:225], v195 offset:41568
	ds_read_b128 v[174:177], v194 offset:4672
	v_mfma_f32_32x32x16_bf16 v[20:35], v[202:205], v[210:213], v[20:35]
	global_load_dwordx4 v[120:123], v[154:155], off offset:1664
	ds_read_b128 v[210:213], v194 offset:4704
	ds_read_b128 v[202:205], v194 offset:64
	v_mfma_f32_32x32x16_bf16 v[52:67], v[178:181], v[214:217], v[52:67]
	global_load_dwordx4 v[124:127], v[152:153], off offset:1664
	ds_read_b128 v[218:221], v195 offset:36960
	ds_read_b128 v[178:181], v195 offset:41536
	v_mfma_f32_32x32x16_bf16 v[20:35], v[206:209], v[214:217], v[20:35]
	global_load_dwordx4 v[128:131], v[146:147], off offset:1664
	ds_read_b128 v[214:217], v195 offset:36928
	ds_read_b128 v[206:209], v194 offset:96
	s_waitcnt lgkmcnt(1)
	v_mfma_f32_32x32x16_bf16 v[52:67], v[202:205], v[214:217], v[52:67]
	s_waitcnt vmcnt(23)
	ds_write_b128 v167, v[132:135] offset:18432
	v_mfma_f32_32x32x16_bf16 v[36:51], v[202:205], v[178:181], v[36:51]
	s_waitcnt vmcnt(22)
	ds_write_b128 v167, v[136:139] offset:55296
	v_mfma_f32_32x32x16_bf16 v[20:35], v[174:177], v[214:217], v[20:35]
	s_waitcnt vmcnt(21)
	ds_write_b128 v190, v[140:143] offset:18432
	v_mfma_f32_32x32x16_bf16 v[4:19], v[174:177], v[178:181], v[4:19]
	s_waitcnt vmcnt(20)
	ds_write_b128 v190, v[198:201] offset:55296
	s_waitcnt lgkmcnt(4)
	v_mfma_f32_32x32x16_bf16 v[52:67], v[206:209], v[218:221], v[52:67]
	s_waitcnt vmcnt(19)
	ds_write_b128 v191, v[226:229] offset:18432
	v_mfma_f32_32x32x16_bf16 v[36:51], v[206:209], v[222:225], v[36:51]
	s_waitcnt vmcnt(18)
	ds_write_b128 v191, v[230:233] offset:55296
	v_mfma_f32_32x32x16_bf16 v[20:35], v[210:213], v[218:221], v[20:35]
	s_waitcnt vmcnt(17)
	ds_write_b128 v192, v[242:245] offset:18432
	v_mfma_f32_32x32x16_bf16 v[4:19], v[210:213], v[222:225], v[4:19]
	s_waitcnt vmcnt(16)
	ds_write_b128 v192, v[246:249] offset:55296
	s_waitcnt lgkmcnt(0)
	s_barrier
; #define MFMA(a, b, c) __builtin_amdgcn_mfma_f32_32x32x16_bf16((a), (b), (c), 0, 0, 0)
; template <class Epi, class ColV>
; DI void gemm_tile(const bf16_t* __restrict__ A, int lda, const bf16_t* __restrict__ Bt, int ldb, int K, int m0, int n0, unsigned char* smem, Epi epi, ColV colv, const bf16_t* __restrict__ HYT = nullptr) {
;     ...
;     auto gload = [&](u32x4 (&r)[8], int kt) {
; #pragma unroll
;         for (int i = 0; i < 4; ++i) { int id = tid + 256 * i, row = id >> 3, kc = id & 7;
;             if (HYT && kt >= 12) r[i] = *(const u32x4*)(HYT + (size_t)((kt - 12) * 64 + (id >> 4)) * NT + m0 + (id & 15) * 8);
;             else r[i] = *(const u32x4*)(A + (size_t)(m0 + row) * lda + kt * 64 + kc * 8);
;             r[4 + i] = *(const u32x4*)(Bt + (size_t)(n0 + row) * ldb + kt * 64 + kc * 8); }
;     };
;     auto sstore = [&](const u32x4 (&r)[8], int buf, int kt) {
; #pragma unroll
;         for (int i = 0; i < 4; ++i) { int id = tid + 256 * i, row = id >> 3, kc = id & 7;
;             if (HYT && kt >= 12) { const int kk = id >> 4, rr = (id & 15) * 8; bf16_t* d = As + (buf * 128 + rr) * LS + kk; const bf16x8 v = __builtin_bit_cast(bf16x8, r[i]);
; #pragma unroll
;                 for (int e = 0; e < 8; ++e) d[e * LS] = (bf16_t)v[e]; }
;             else *(u32x4*)(As + (buf * 128 + row) * LS + kc * 8) = r[i];
;             *(u32x4*)(Bs + (buf * 128 + row) * LS + kc * 8) = r[4 + i]; }
;     };
;     auto step = [&](int kt, u32x4 (&ldset)[8], const u32x4 (&stset)[8]) {
;         const int buf = kt & 1;
;         if (kt + 2 < nk) gload(ldset, kt + 2);
;         const bf16_t* Ab = As + (buf * 128 + 64 * wr + li) * LS + 8 * lh;
;         const bf16_t* Bb = Bs + (buf * 128 + 64 * wc + li) * LS + 8 * lh;
;         bf16x8 fa[2][2], fb[2][2], ga[2][2], gb[2][2];
; #pragma unroll
;         for (int k2 = 0; k2 < 2; ++k2) { fa[k2][0] = ld8(Ab + 16 * k2); fa[k2][1] = ld8(Ab + 32 * LS + 16 * k2); fb[k2][0] = ld8(Bb + 16 * k2); fb[k2][1] = ld8(Bb + 32 * LS + 16 * k2); }
;         __builtin_amdgcn_sched_barrier(0);
; #pragma unroll
;         for (int k2 = 0; k2 < 2; ++k2) {
;             acc[0][0] = MFMA(fa[k2][0], fb[k2][0], acc[0][0]); acc[0][1] = MFMA(fa[k2][0], fb[k2][1], acc[0][1]);
;             acc[1][0] = MFMA(fa[k2][1], fb[k2][0], acc[1][0]); acc[1][1] = MFMA(fa[k2][1], fb[k2][1], acc[1][1]);
;         }
; #pragma unroll
	ds_read_b128 v[174:177], v196
	ds_read_b128 v[178:181], v196 offset:32
	ds_read_b128 v[202:205], v196 offset:4608
	ds_read_b128 v[206:209], v196 offset:4640
	ds_read_b128 v[210:213], v197 offset:36864
	ds_read_b128 v[214:217], v197 offset:36896
	ds_read_b128 v[218:221], v197 offset:41472
	ds_read_b128 v[222:225], v197 offset:41504
	s_waitcnt lgkmcnt(3)
	v_mfma_f32_32x32x16_bf16 v[52:67], v[174:177], v[210:213], v[52:67]
	global_load_dwordx4 v[132:135], v[164:165], off offset:1792
	s_waitcnt lgkmcnt(1)
	v_mfma_f32_32x32x16_bf16 v[36:51], v[174:177], v[218:221], v[36:51]
	global_load_dwordx4 v[136:139], v[162:163], off offset:1792
	v_mfma_f32_32x32x16_bf16 v[4:19], v[202:205], v[218:221], v[4:19]
	global_load_dwordx4 v[140:143], v[160:161], off offset:1792
	s_waitcnt lgkmcnt(0)
	v_mfma_f32_32x32x16_bf16 v[36:51], v[178:181], v[222:225], v[36:51]
	global_load_dwordx4 v[198:201], v[158:159], off offset:1792
	v_mfma_f32_32x32x16_bf16 v[4:19], v[206:209], v[222:225], v[4:19]
	global_load_dwordx4 v[226:229], v[156:157], off offset:1792
	ds_read_b128 v[222:225], v197 offset:41568
	ds_read_b128 v[174:177], v196 offset:4672
	v_mfma_f32_32x32x16_bf16 v[20:35], v[202:205], v[210:213], v[20:35]
	global_load_dwordx4 v[230:233], v[154:155], off offset:1792
	ds_read_b128 v[210:213], v196 offset:4704
	ds_read_b128 v[202:205], v196 offset:64
	v_mfma_f32_32x32x16_bf16 v[52:67], v[178:181], v[214:217], v[52:67]
	global_load_dwordx4 v[242:245], v[152:153], off offset:1792
	ds_read_b128 v[218:221], v197 offset:36960
	ds_read_b128 v[178:181], v197 offset:41536
	v_mfma_f32_32x32x16_bf16 v[20:35], v[206:209], v[214:217], v[20:35]
	global_load_dwordx4 v[246:249], v[146:147], off offset:1792
	ds_read_b128 v[214:217], v197 offset:36928
	ds_read_b128 v[206:209], v196 offset:96
	s_waitcnt lgkmcnt(1)
	v_mfma_f32_32x32x16_bf16 v[52:67], v[202:205], v[214:217], v[52:67]
	s_waitcnt vmcnt(23)
	ds_write_b128 v167, v[68:71]
	v_mfma_f32_32x32x16_bf16 v[36:51], v[202:205], v[178:181], v[36:51]
	s_waitcnt vmcnt(22)
	ds_write_b128 v167, v[72:75] offset:36864
	v_mfma_f32_32x32x16_bf16 v[20:35], v[174:177], v[214:217], v[20:35]
	s_waitcnt vmcnt(21)
	ds_write_b128 v190, v[76:79]
	v_mfma_f32_32x32x16_bf16 v[4:19], v[174:177], v[178:181], v[4:19]
	s_waitcnt vmcnt(20)
	ds_write_b128 v190, v[80:83] offset:36864
	s_waitcnt lgkmcnt(4)
	v_mfma_f32_32x32x16_bf16 v[52:67], v[206:209], v[218:221], v[52:67]
	s_waitcnt vmcnt(19)
	ds_write_b128 v191, v[84:87]
	v_mfma_f32_32x32x16_bf16 v[36:51], v[206:209], v[222:225], v[36:51]
	s_waitcnt vmcnt(18)
	ds_write_b128 v191, v[92:95] offset:36864
	v_mfma_f32_32x32x16_bf16 v[20:35], v[210:213], v[218:221], v[20:35]
	s_waitcnt vmcnt(17)
	ds_write_b128 v192, v[104:107]
	v_mfma_f32_32x32x16_bf16 v[4:19], v[210:213], v[222:225], v[4:19]
	s_waitcnt vmcnt(16)
	ds_write_b128 v192, v[112:115] offset:36864
	s_waitcnt lgkmcnt(0)
	s_barrier
	ds_read_b128 v[174:177], v194
	ds_read_b128 v[178:181], v194 offset:32
	ds_read_b128 v[202:205], v194 offset:4608
	ds_read_b128 v[206:209], v194 offset:4640
	ds_read_b128 v[210:213], v195 offset:36864
	ds_read_b128 v[214:217], v195 offset:36896
	ds_read_b128 v[218:221], v195 offset:41472
	ds_read_b128 v[222:225], v195 offset:41504
	s_waitcnt lgkmcnt(3)
	v_mfma_f32_32x32x16_bf16 v[52:67], v[174:177], v[210:213], v[52:67]
	global_load_dwordx4 v[68:71], v[164:165], off offset:1920
	s_waitcnt lgkmcnt(1)
	v_mfma_f32_32x32x16_bf16 v[36:51], v[174:177], v[218:221], v[36:51]
	global_load_dwordx4 v[72:75], v[162:163], off offset:1920
	v_mfma_f32_32x32x16_bf16 v[4:19], v[202:205], v[218:221], v[4:19]
	global_load_dwordx4 v[76:79], v[160:161], off offset:1920
	s_waitcnt lgkmcnt(0)
	v_mfma_f32_32x32x16_bf16 v[36:51], v[178:181], v[222:225], v[36:51]
	global_load_dwordx4 v[80:83], v[158:159], off offset:1920
	v_mfma_f32_32x32x16_bf16 v[4:19], v[206:209], v[222:225], v[4:19]
	global_load_dwordx4 v[84:87], v[156:157], off offset:1920
	ds_read_b128 v[222:225], v195 offset:41568
	ds_read_b128 v[174:177], v194 offset:4672
	v_mfma_f32_32x32x16_bf16 v[20:35], v[202:205], v[210:213], v[20:35]
	global_load_dwordx4 v[92:95], v[154:155], off offset:1920
	ds_read_b128 v[210:213], v194 offset:4704
	ds_read_b128 v[202:205], v194 offset:64
	v_mfma_f32_32x32x16_bf16 v[52:67], v[178:181], v[214:217], v[52:67]
	global_load_dwordx4 v[104:107], v[152:153], off offset:1920
	ds_read_b128 v[218:221], v195 offset:36960
	ds_read_b128 v[178:181], v195 offset:41536
	v_mfma_f32_32x32x16_bf16 v[20:35], v[206:209], v[214:217], v[20:35]
	global_load_dwordx4 v[112:115], v[146:147], off offset:1920
	ds_read_b128 v[214:217], v195 offset:36928
	ds_read_b128 v[206:209], v194 offset:96
	s_waitcnt lgkmcnt(1)
	v_mfma_f32_32x32x16_bf16 v[52:67], v[202:205], v[214:217], v[52:67]
	s_waitcnt vmcnt(23)
	ds_write_b128 v167, v[88:91] offset:18432
	v_mfma_f32_32x32x16_bf16 v[36:51], v[202:205], v[178:181], v[36:51]
	s_waitcnt vmcnt(22)
	ds_write_b128 v167, v[96:99] offset:55296
	v_mfma_f32_32x32x16_bf16 v[20:35], v[174:177], v[214:217], v[20:35]
	s_waitcnt vmcnt(21)
	ds_write_b128 v190, v[100:103] offset:18432
	v_mfma_f32_32x32x16_bf16 v[4:19], v[174:177], v[178:181], v[4:19]
	s_waitcnt vmcnt(20)
	ds_write_b128 v190, v[108:111] offset:55296
	s_waitcnt lgkmcnt(4)
	v_mfma_f32_32x32x16_bf16 v[52:67], v[206:209], v[218:221], v[52:67]
	s_waitcnt vmcnt(19)
	ds_write_b128 v191, v[116:119] offset:18432
	v_mfma_f32_32x32x16_bf16 v[36:51], v[206:209], v[222:225], v[36:51]
	s_waitcnt vmcnt(18)
	ds_write_b128 v191, v[120:123] offset:55296
	v_mfma_f32_32x32x16_bf16 v[20:35], v[210:213], v[218:221], v[20:35]
	s_waitcnt vmcnt(17)
	ds_write_b128 v192, v[124:127] offset:18432
	v_mfma_f32_32x32x16_bf16 v[4:19], v[210:213], v[222:225], v[4:19]
	s_waitcnt vmcnt(16)
	ds_write_b128 v192, v[128:131] offset:55296
	s_waitcnt lgkmcnt(0)
	s_barrier
; template <class Epi, class ColV>
; DI void gemm_tile(const bf16_t* __restrict__ A, int lda, const bf16_t* __restrict__ Bt, int ldb, int K, int m0, int n0, unsigned char* smem, Epi epi, ColV colv, const bf16_t* __restrict__ HYT = nullptr) {
;     ...
;     auto step = [&](int kt, u32x4 (&ldset)[8], const u32x4 (&stset)[8]) {
;         const int buf = kt & 1;
;         if (kt + 2 < nk) gload(ldset, kt + 2);
;         const bf16_t* Ab = As + (buf * 128 + 64 * wr + li) * LS + 8 * lh;
;         const bf16_t* Bb = Bs + (buf * 128 + 64 * wc + li) * LS + 8 * lh;
;         bf16x8 fa[2][2], fb[2][2], ga[2][2], gb[2][2];
; #pragma unroll
;         for (int k2 = 0; k2 < 2; ++k2) { fa[k2][0] = ld8(Ab + 16 * k2); fa[k2][1] = ld8(Ab + 32 * LS + 16 * k2); fb[k2][0] = ld8(Bb + 16 * k2); fb[k2][1] = ld8(Bb + 32 * LS + 16 * k2); }
;         __builtin_amdgcn_sched_barrier(0);
; #pragma unroll
;         for (int k2 = 0; k2 < 2; ++k2) {
;             acc[0][0] = MFMA(fa[k2][0], fb[k2][0], acc[0][0]); acc[0][1] = MFMA(fa[k2][0], fb[k2][1], acc[0][1]);
;             acc[1][0] = MFMA(fa[k2][1], fb[k2][0], acc[1][0]); acc[1][1] = MFMA(fa[k2][1], fb[k2][1], acc[1][1]);
;         }
; #pragma unroll
;         for (int k2 = 0; k2 < 2; ++k2) { const int ks = 2 + k2; ga[k2][0] = ld8(Ab + 16 * ks); ga[k2][1] = ld8(Ab + 32 * LS + 16 * ks); gb[k2][0] = ld8(Bb + 16 * ks); gb[k2][1] = ld8(Bb + 32 * LS + 16 * ks); }
; #pragma unroll
;         for (int k2 = 0; k2 < 2; ++k2) {
;             acc[0][0] = MFMA(ga[k2][0], gb[k2][0], acc[0][0]); acc[0][1] = MFMA(ga[k2][0], gb[k2][1], acc[0][1]);
;             acc[1][0] = MFMA(ga[k2][1], gb[k2][0], acc[1][0]); acc[1][1] = MFMA(ga[k2][1], gb[k2][1], acc[1][1]);
;         }
;         if (kt + 1 < nk) sstore(stset, buf ^ 1, kt + 1);
; #pragma unroll
;         for (int i = 0; i < 8; ++i) { __builtin_amdgcn_sched_group_barrier(0x008, 1, 0); __builtin_amdgcn_sched_group_barrier(0x100, 1, 0); }
; #pragma unroll
;         for (int i = 0; i < 8; ++i) { __builtin_amdgcn_sched_group_barrier(0x008, 1, 0); __builtin_amdgcn_sched_group_barrier(0x200, 1, 0); }
;         __builtin_amdgcn_sched_barrier(0);
;         __syncthreads();
;     };
;     gload(R0, 0); gload(R1, 1);
;     sstore(R0, 0, 0); __syncthreads();
;     for (int kt = 0; kt < nk; kt += 2) {
;         step(kt, R0, R1);
;         if (kt + 1 < nk) step(kt + 1, R1, R0);
;     }
	ds_read_b128 v[174:177], v196
	ds_read_b128 v[178:181], v196 offset:32
	ds_read_b128 v[202:205], v196 offset:4608
	ds_read_b128 v[206:209], v196 offset:4640
	ds_read_b128 v[210:213], v197 offset:36864
	ds_read_b128 v[214:217], v197 offset:36896
	ds_read_b128 v[218:221], v197 offset:41472
	ds_read_b128 v[222:225], v197 offset:41504
	s_waitcnt lgkmcnt(3)
	v_mfma_f32_32x32x16_bf16 v[52:67], v[174:177], v[210:213], v[52:67]
	s_waitcnt lgkmcnt(1)
	v_mfma_f32_32x32x16_bf16 v[36:51], v[174:177], v[218:221], v[36:51]
	v_mfma_f32_32x32x16_bf16 v[4:19], v[202:205], v[218:221], v[4:19]
	s_waitcnt lgkmcnt(0)
	v_mfma_f32_32x32x16_bf16 v[36:51], v[178:181], v[222:225], v[36:51]
	v_mfma_f32_32x32x16_bf16 v[4:19], v[206:209], v[222:225], v[4:19]
	ds_read_b128 v[222:225], v197 offset:41568
	ds_read_b128 v[174:177], v196 offset:4672
	v_mfma_f32_32x32x16_bf16 v[20:35], v[202:205], v[210:213], v[20:35]
	ds_read_b128 v[210:213], v196 offset:4704
	ds_read_b128 v[202:205], v196 offset:64
	v_mfma_f32_32x32x16_bf16 v[52:67], v[178:181], v[214:217], v[52:67]
	ds_read_b128 v[218:221], v197 offset:36960
	ds_read_b128 v[178:181], v197 offset:41536
	v_mfma_f32_32x32x16_bf16 v[20:35], v[206:209], v[214:217], v[20:35]
	ds_read_b128 v[214:217], v197 offset:36928
	ds_read_b128 v[206:209], v196 offset:96
	s_waitcnt lgkmcnt(1)
	v_mfma_f32_32x32x16_bf16 v[52:67], v[202:205], v[214:217], v[52:67]
	s_waitcnt vmcnt(15)
	ds_write_b128 v167, v[132:135]
	v_mfma_f32_32x32x16_bf16 v[36:51], v[202:205], v[178:181], v[36:51]
	s_waitcnt vmcnt(14)
	ds_write_b128 v167, v[136:139] offset:36864
	v_mfma_f32_32x32x16_bf16 v[20:35], v[174:177], v[214:217], v[20:35]
	s_waitcnt vmcnt(13)
	ds_write_b128 v190, v[140:143]
	v_mfma_f32_32x32x16_bf16 v[4:19], v[174:177], v[178:181], v[4:19]
	s_waitcnt vmcnt(12)
	ds_write_b128 v190, v[198:201] offset:36864
	s_waitcnt lgkmcnt(4)
	v_mfma_f32_32x32x16_bf16 v[52:67], v[206:209], v[218:221], v[52:67]
	s_waitcnt vmcnt(11)
	ds_write_b128 v191, v[226:229]
	v_mfma_f32_32x32x16_bf16 v[36:51], v[206:209], v[222:225], v[36:51]
	s_waitcnt vmcnt(10)
	ds_write_b128 v191, v[230:233] offset:36864
	v_mfma_f32_32x32x16_bf16 v[20:35], v[210:213], v[218:221], v[20:35]
	s_waitcnt vmcnt(9)
	ds_write_b128 v192, v[242:245]
	v_mfma_f32_32x32x16_bf16 v[4:19], v[210:213], v[222:225], v[4:19]
	s_waitcnt vmcnt(8)
	ds_write_b128 v192, v[246:249] offset:36864
	s_waitcnt lgkmcnt(0)
	s_barrier
	ds_read_b128 v[174:177], v194
	ds_read_b128 v[178:181], v194 offset:32
	ds_read_b128 v[202:205], v194 offset:4608
	ds_read_b128 v[206:209], v194 offset:4640
	ds_read_b128 v[210:213], v195 offset:36864
	ds_read_b128 v[214:217], v195 offset:36896
	ds_read_b128 v[218:221], v195 offset:41472
	ds_read_b128 v[222:225], v195 offset:41504
	s_waitcnt lgkmcnt(3)
	v_mfma_f32_32x32x16_bf16 v[52:67], v[174:177], v[210:213], v[52:67]
	s_waitcnt lgkmcnt(1)
	v_mfma_f32_32x32x16_bf16 v[36:51], v[174:177], v[218:221], v[36:51]
	v_mfma_f32_32x32x16_bf16 v[4:19], v[202:205], v[218:221], v[4:19]
	s_waitcnt lgkmcnt(0)
	v_mfma_f32_32x32x16_bf16 v[36:51], v[178:181], v[222:225], v[36:51]
	v_mfma_f32_32x32x16_bf16 v[4:19], v[206:209], v[222:225], v[4:19]
	ds_read_b128 v[222:225], v195 offset:41568
	ds_read_b128 v[174:177], v194 offset:4672
	v_mfma_f32_32x32x16_bf16 v[20:35], v[202:205], v[210:213], v[20:35]
	ds_read_b128 v[210:213], v194 offset:4704
	ds_read_b128 v[202:205], v194 offset:64
	v_mfma_f32_32x32x16_bf16 v[52:67], v[178:181], v[214:217], v[52:67]
	ds_read_b128 v[218:221], v195 offset:36960
	ds_read_b128 v[178:181], v195 offset:41536
	v_mfma_f32_32x32x16_bf16 v[20:35], v[206:209], v[214:217], v[20:35]
	ds_read_b128 v[214:217], v195 offset:36928
	ds_read_b128 v[206:209], v194 offset:96
	s_waitcnt lgkmcnt(1)
	v_mfma_f32_32x32x16_bf16 v[52:67], v[202:205], v[214:217], v[52:67]
	s_waitcnt vmcnt(7)
	ds_write_b128 v167, v[68:71] offset:18432
	v_mfma_f32_32x32x16_bf16 v[36:51], v[202:205], v[178:181], v[36:51]
	s_waitcnt vmcnt(6)
	ds_write_b128 v167, v[72:75] offset:55296
	v_mfma_f32_32x32x16_bf16 v[20:35], v[174:177], v[214:217], v[20:35]
	s_waitcnt vmcnt(5)
	ds_write_b128 v190, v[76:79] offset:18432
	v_mfma_f32_32x32x16_bf16 v[4:19], v[174:177], v[178:181], v[4:19]
	s_waitcnt vmcnt(4)
	ds_write_b128 v190, v[80:83] offset:55296
	s_waitcnt lgkmcnt(4)
	v_mfma_f32_32x32x16_bf16 v[52:67], v[206:209], v[218:221], v[52:67]
	s_waitcnt vmcnt(3)
	ds_write_b128 v191, v[84:87] offset:18432
	v_mfma_f32_32x32x16_bf16 v[36:51], v[206:209], v[222:225], v[36:51]
	s_waitcnt vmcnt(2)
	ds_write_b128 v191, v[92:95] offset:55296
	v_mfma_f32_32x32x16_bf16 v[20:35], v[210:213], v[218:221], v[20:35]
	s_waitcnt vmcnt(1)
	ds_write_b128 v192, v[104:107] offset:18432
	v_mfma_f32_32x32x16_bf16 v[4:19], v[210:213], v[222:225], v[4:19]
	s_waitcnt vmcnt(0)
	ds_write_b128 v192, v[112:115] offset:55296
	s_waitcnt lgkmcnt(0)
	s_barrier
	ds_read_b128 v[174:177], v196
	ds_read_b128 v[178:181], v196 offset:32
	ds_read_b128 v[202:205], v196 offset:4608
	ds_read_b128 v[206:209], v196 offset:4640
	ds_read_b128 v[210:213], v197 offset:36864
	ds_read_b128 v[214:217], v197 offset:36896
	ds_read_b128 v[218:221], v197 offset:41472
	ds_read_b128 v[222:225], v197 offset:41504
	s_waitcnt lgkmcnt(3)
	v_mfma_f32_32x32x16_bf16 v[52:67], v[174:177], v[210:213], v[52:67]
	s_waitcnt lgkmcnt(1)
	v_mfma_f32_32x32x16_bf16 v[36:51], v[174:177], v[218:221], v[36:51]
	v_mfma_f32_32x32x16_bf16 v[4:19], v[202:205], v[218:221], v[4:19]
	s_waitcnt lgkmcnt(0)
	v_mfma_f32_32x32x16_bf16 v[36:51], v[178:181], v[222:225], v[36:51]
	v_mfma_f32_32x32x16_bf16 v[4:19], v[206:209], v[222:225], v[4:19]
	ds_read_b128 v[222:225], v197 offset:41568
	ds_read_b128 v[174:177], v196 offset:4672
	v_mfma_f32_32x32x16_bf16 v[20:35], v[202:205], v[210:213], v[20:35]
	ds_read_b128 v[210:213], v196 offset:4704
	ds_read_b128 v[202:205], v196 offset:64
	v_mfma_f32_32x32x16_bf16 v[52:67], v[178:181], v[214:217], v[52:67]
	ds_read_b128 v[218:221], v197 offset:36960
	ds_read_b128 v[178:181], v197 offset:41536
	v_mfma_f32_32x32x16_bf16 v[20:35], v[206:209], v[214:217], v[20:35]
	ds_read_b128 v[214:217], v197 offset:36928
	ds_read_b128 v[206:209], v196 offset:96
	s_waitcnt lgkmcnt(1)
	v_mfma_f32_32x32x16_bf16 v[52:67], v[202:205], v[214:217], v[52:67]
	v_mfma_f32_32x32x16_bf16 v[36:51], v[202:205], v[178:181], v[36:51]
	v_mfma_f32_32x32x16_bf16 v[20:35], v[174:177], v[214:217], v[20:35]
	v_mfma_f32_32x32x16_bf16 v[4:19], v[174:177], v[178:181], v[4:19]
	s_waitcnt lgkmcnt(0)
	v_mfma_f32_32x32x16_bf16 v[52:67], v[206:209], v[218:221], v[52:67]
	v_mfma_f32_32x32x16_bf16 v[36:51], v[206:209], v[222:225], v[36:51]
	v_mfma_f32_32x32x16_bf16 v[20:35], v[210:213], v[218:221], v[20:35]
	v_mfma_f32_32x32x16_bf16 v[4:19], v[210:213], v[222:225], v[4:19]
	s_waitcnt lgkmcnt(0)
	s_barrier
	s_nop 7
	s_nop 3
	s_branch .LBB0_53

; #define MFMA(a, b, c) __builtin_amdgcn_mfma_f32_32x32x16_bf16((a), (b), (c), 0, 0, 0)
; template <class Epi, class ColV>
; DI void gemm_tile(const bf16_t* __restrict__ A, int lda, const bf16_t* __restrict__ Bt, int ldb, int K, int m0, int n0, unsigned char* smem, Epi epi, ColV colv, const bf16_t* __restrict__ HYT = nullptr) {
;     ...
;     auto gload = [&](u32x4 (&r)[8], int kt) {
; #pragma unroll
;         for (int i = 0; i < 4; ++i) { int id = tid + 256 * i, row = id >> 3, kc = id & 7;
;             if (HYT && kt >= 12) r[i] = *(const u32x4*)(HYT + (size_t)((kt - 12) * 64 + (id >> 4)) * NT + m0 + (id & 15) * 8);
;             else r[i] = *(const u32x4*)(A + (size_t)(m0 + row) * lda + kt * 64 + kc * 8);
;             r[4 + i] = *(const u32x4*)(Bt + (size_t)(n0 + row) * ldb + kt * 64 + kc * 8); }
;     };
;     auto sstore = [&](const u32x4 (&r)[8], int buf, int kt) {
; #pragma unroll
;         for (int i = 0; i < 4; ++i) { int id = tid + 256 * i, row = id >> 3, kc = id & 7;
;             if (HYT && kt >= 12) { const int kk = id >> 4, rr = (id & 15) * 8; bf16_t* d = As + (buf * 128 + rr) * LS + kk; const bf16x8 v = __builtin_bit_cast(bf16x8, r[i]);
; #pragma unroll
;                 for (int e = 0; e < 8; ++e) d[e * LS] = (bf16_t)v[e]; }
;             else *(u32x4*)(As + (buf * 128 + row) * LS + kc * 8) = r[i];
;             *(u32x4*)(Bs + (buf * 128 + row) * LS + kc * 8) = r[4 + i]; }
;     };
;     auto step = [&](int kt, u32x4 (&ldset)[8], const u32x4 (&stset)[8]) {
;         const int buf = kt & 1;
;         if (kt + 2 < nk) gload(ldset, kt + 2);
;         const bf16_t* Ab = As + (buf * 128 + 64 * wr + li) * LS + 8 * lh;
;         const bf16_t* Bb = Bs + (buf * 128 + 64 * wc + li) * LS + 8 * lh;
;         bf16x8 fa[2][2], fb[2][2], ga[2][2], gb[2][2];
; #pragma unroll
;         for (int k2 = 0; k2 < 2; ++k2) { fa[k2][0] = ld8(Ab + 16 * k2); fa[k2][1] = ld8(Ab + 32 * LS + 16 * k2); fb[k2][0] = ld8(Bb + 16 * k2); fb[k2][1] = ld8(Bb + 32 * LS + 16 * k2); }
;         __builtin_amdgcn_sched_barrier(0);
; #pragma unroll
;         for (int k2 = 0; k2 < 2; ++k2) {
;             acc[0][0] = MFMA(fa[k2][0], fb[k2][0], acc[0][0]); acc[0][1] = MFMA(fa[k2][0], fb[k2][1], acc[0][1]);
;             acc[1][0] = MFMA(fa[k2][1], fb[k2][0], acc[1][0]); acc[1][1] = MFMA(fa[k2][1], fb[k2][1], acc[1][1]);
;         }
; #pragma unroll
.LBB0_1558:
	s_cmp_lt_u32 s19, 14
	s_cselect_b64 s[12:13], -1, 0
	s_cmp_gt_u32 s19, 13
	s_cselect_b64 s[10:11], -1, 0
	s_and_b64 vcc, exec, s[10:11]
	v_lshl_add_u64 v[164:165], v[144:145], 0, v[2:3]
	v_lshl_add_u64 v[162:163], v[0:1], 0, v[2:3]
	v_lshl_add_u64 v[160:161], v[142:143], 0, v[2:3]
	v_lshl_add_u64 v[158:159], v[132:133], 0, v[2:3]
	v_lshl_add_u64 v[156:157], v[140:141], 0, v[2:3]
	v_lshl_add_u64 v[154:155], v[134:135], 0, v[2:3]
	v_lshl_add_u64 v[152:153], v[138:139], 0, v[2:3]
	v_lshl_add_u64 v[146:147], v[136:137], 0, v[2:3]
	s_mov_b32 s100, 0x26ca000
	s_mov_b32 s101, 0
	v_lshl_add_u64 v[164:165], v[164:165], 0, s[100:101]
	v_lshl_add_u64 v[160:161], v[160:161], 0, s[100:101]
	v_lshl_add_u64 v[156:157], v[156:157], 0, s[100:101]
	v_lshl_add_u64 v[152:153], v[152:153], 0, s[100:101]
	ds_read_b128 v[202:205], v194
	ds_read_b128 v[206:209], v194 offset:32
	ds_read_b128 v[210:213], v194 offset:4608
	ds_read_b128 v[214:217], v194 offset:4640
	ds_read_b128 v[218:221], v195 offset:36864
	ds_read_b128 v[222:225], v195 offset:36896
	ds_read_b128 v[226:229], v195 offset:41472
	ds_read_b128 v[230:233], v195 offset:41504
	s_waitcnt lgkmcnt(3)
	v_mfma_f32_32x32x16_bf16 v[52:67], v[202:205], v[218:221], v[52:67]
	global_load_dwordx4 v[132:135], v[164:165], off offset:256
	global_load_dwordx4 v[136:139], v[162:163], off offset:256
	s_waitcnt lgkmcnt(1)
	v_mfma_f32_32x32x16_bf16 v[36:51], v[202:205], v[226:229], v[36:51]
	global_load_dwordx4 v[140:143], v[160:161], off offset:256
	global_load_dwordx4 v[198:201], v[158:159], off offset:256
	v_mfma_f32_32x32x16_bf16 v[4:19], v[210:213], v[226:229], v[4:19]
	global_load_dwordx4 v[174:177], v[156:157], off offset:256
	global_load_dwordx4 v[178:181], v[154:155], off offset:256
	s_waitcnt lgkmcnt(0)
	v_mfma_f32_32x32x16_bf16 v[36:51], v[206:209], v[230:233], v[36:51]
	global_load_dwordx4 v[242:245], v[152:153], off offset:256
	global_load_dwordx4 v[246:249], v[146:147], off offset:256
	v_mfma_f32_32x32x16_bf16 v[4:19], v[214:217], v[230:233], v[4:19]
	global_load_dwordx4 v[68:71], v[164:165], off offset:384
	global_load_dwordx4 v[72:75], v[162:163], off offset:384
	ds_read_b128 v[230:233], v195 offset:41568
	ds_read_b128 v[202:205], v194 offset:4672
	v_mfma_f32_32x32x16_bf16 v[20:35], v[210:213], v[218:221], v[20:35]
	global_load_dwordx4 v[76:79], v[160:161], off offset:384
	global_load_dwordx4 v[80:83], v[158:159], off offset:384
	ds_read_b128 v[218:221], v194 offset:4704
	ds_read_b128 v[210:213], v194 offset:64
	v_mfma_f32_32x32x16_bf16 v[52:67], v[206:209], v[222:225], v[52:67]
	global_load_dwordx4 v[84:87], v[156:157], off offset:384
	global_load_dwordx4 v[88:91], v[154:155], off offset:384
	ds_read_b128 v[226:229], v195 offset:36960
	ds_read_b128 v[206:209], v195 offset:41536
	v_mfma_f32_32x32x16_bf16 v[20:35], v[214:217], v[222:225], v[20:35]
	global_load_dwordx4 v[92:95], v[152:153], off offset:384
	global_load_dwordx4 v[104:107], v[146:147], off offset:384
	ds_read_b128 v[222:225], v195 offset:36928
	ds_read_b128 v[214:217], v194 offset:96
	s_waitcnt lgkmcnt(1)
	v_mfma_f32_32x32x16_bf16 v[52:67], v[210:213], v[222:225], v[52:67]
	s_waitcnt vmcnt(16)
	ds_write_b128 v167, v[96:99] offset:18432
	v_mfma_f32_32x32x16_bf16 v[36:51], v[210:213], v[206:209], v[36:51]
	ds_write_b128 v167, v[100:103] offset:55296
	v_mfma_f32_32x32x16_bf16 v[20:35], v[202:205], v[222:225], v[20:35]
	ds_write_b128 v190, v[108:111] offset:18432
	v_mfma_f32_32x32x16_bf16 v[4:19], v[202:205], v[206:209], v[4:19]
	ds_write_b128 v190, v[112:115] offset:55296
	s_waitcnt lgkmcnt(4)
	v_mfma_f32_32x32x16_bf16 v[52:67], v[214:217], v[226:229], v[52:67]
	ds_write_b128 v191, v[116:119] offset:18432
	v_mfma_f32_32x32x16_bf16 v[36:51], v[214:217], v[230:233], v[36:51]
	ds_write_b128 v191, v[120:123] offset:55296
	v_mfma_f32_32x32x16_bf16 v[20:35], v[218:221], v[226:229], v[20:35]
	ds_write_b128 v192, v[124:127] offset:18432
	v_mfma_f32_32x32x16_bf16 v[4:19], v[218:221], v[230:233], v[4:19]
	ds_write_b128 v192, v[128:131] offset:55296
	s_waitcnt lgkmcnt(0)
	s_barrier
	ds_read_b128 v[202:205], v196
	ds_read_b128 v[206:209], v196 offset:32
	ds_read_b128 v[210:213], v196 offset:4608
	ds_read_b128 v[214:217], v196 offset:4640
	ds_read_b128 v[218:221], v197 offset:36864
	ds_read_b128 v[222:225], v197 offset:36896
	ds_read_b128 v[226:229], v197 offset:41472
	ds_read_b128 v[230:233], v197 offset:41504
	s_waitcnt lgkmcnt(3)
	v_mfma_f32_32x32x16_bf16 v[52:67], v[202:205], v[218:221], v[52:67]
	global_load_dwordx4 v[96:99], v[164:165], off offset:512
	s_waitcnt lgkmcnt(1)
	v_mfma_f32_32x32x16_bf16 v[36:51], v[202:205], v[226:229], v[36:51]
	global_load_dwordx4 v[100:103], v[162:163], off offset:512
	v_mfma_f32_32x32x16_bf16 v[4:19], v[210:213], v[226:229], v[4:19]
	global_load_dwordx4 v[108:111], v[160:161], off offset:512
	s_waitcnt lgkmcnt(0)
	v_mfma_f32_32x32x16_bf16 v[36:51], v[206:209], v[230:233], v[36:51]
	global_load_dwordx4 v[112:115], v[158:159], off offset:512
	v_mfma_f32_32x32x16_bf16 v[4:19], v[214:217], v[230:233], v[4:19]
	global_load_dwordx4 v[116:119], v[156:157], off offset:512
	ds_read_b128 v[230:233], v197 offset:41568
	ds_read_b128 v[202:205], v196 offset:4672
	v_mfma_f32_32x32x16_bf16 v[20:35], v[210:213], v[218:221], v[20:35]
	global_load_dwordx4 v[120:123], v[154:155], off offset:512
	ds_read_b128 v[218:221], v196 offset:4704
	ds_read_b128 v[210:213], v196 offset:64
	v_mfma_f32_32x32x16_bf16 v[52:67], v[206:209], v[222:225], v[52:67]
	global_load_dwordx4 v[124:127], v[152:153], off offset:512
	ds_read_b128 v[226:229], v197 offset:36960
	ds_read_b128 v[206:209], v197 offset:41536
	v_mfma_f32_32x32x16_bf16 v[20:35], v[214:217], v[222:225], v[20:35]
	global_load_dwordx4 v[128:131], v[146:147], off offset:512
	ds_read_b128 v[222:225], v197 offset:36928
	ds_read_b128 v[214:217], v196 offset:96
	s_waitcnt lgkmcnt(1)
	v_mfma_f32_32x32x16_bf16 v[52:67], v[210:213], v[222:225], v[52:67]
	s_waitcnt vmcnt(23)
	ds_write_b128 v167, v[132:135]
	v_mfma_f32_32x32x16_bf16 v[36:51], v[210:213], v[206:209], v[36:51]
	s_waitcnt vmcnt(22)
	ds_write_b128 v167, v[136:139] offset:36864
	v_mfma_f32_32x32x16_bf16 v[20:35], v[202:205], v[222:225], v[20:35]
	s_waitcnt vmcnt(21)
	ds_write_b128 v190, v[140:143]
	v_mfma_f32_32x32x16_bf16 v[4:19], v[202:205], v[206:209], v[4:19]
	s_waitcnt vmcnt(20)
	ds_write_b128 v190, v[198:201] offset:36864
	s_waitcnt lgkmcnt(4)
	v_mfma_f32_32x32x16_bf16 v[52:67], v[214:217], v[226:229], v[52:67]
	s_waitcnt vmcnt(19)
	ds_write_b128 v191, v[174:177]
	v_mfma_f32_32x32x16_bf16 v[36:51], v[214:217], v[230:233], v[36:51]
	s_waitcnt vmcnt(18)
	ds_write_b128 v191, v[178:181] offset:36864
	v_mfma_f32_32x32x16_bf16 v[20:35], v[218:221], v[226:229], v[20:35]
	s_waitcnt vmcnt(17)
	ds_write_b128 v192, v[242:245]
	v_mfma_f32_32x32x16_bf16 v[4:19], v[218:221], v[230:233], v[4:19]
	s_waitcnt vmcnt(16)
	ds_write_b128 v192, v[246:249] offset:36864
	s_waitcnt lgkmcnt(0)
	s_barrier
; #define MFMA(a, b, c) __builtin_amdgcn_mfma_f32_32x32x16_bf16((a), (b), (c), 0, 0, 0)
; template <class Epi, class ColV>
; DI void gemm_tile(const bf16_t* __restrict__ A, int lda, const bf16_t* __restrict__ Bt, int ldb, int K, int m0, int n0, unsigned char* smem, Epi epi, ColV colv, const bf16_t* __restrict__ HYT = nullptr) {
;     ...
;     auto gload = [&](u32x4 (&r)[8], int kt) {
; #pragma unroll
;         for (int i = 0; i < 4; ++i) { int id = tid + 256 * i, row = id >> 3, kc = id & 7;
;             if (HYT && kt >= 12) r[i] = *(const u32x4*)(HYT + (size_t)((kt - 12) * 64 + (id >> 4)) * NT + m0 + (id & 15) * 8);
;             else r[i] = *(const u32x4*)(A + (size_t)(m0 + row) * lda + kt * 64 + kc * 8);
;             r[4 + i] = *(const u32x4*)(Bt + (size_t)(n0 + row) * ldb + kt * 64 + kc * 8); }
;     };
;     auto sstore = [&](const u32x4 (&r)[8], int buf, int kt) {
; #pragma unroll
;         for (int i = 0; i < 4; ++i) { int id = tid + 256 * i, row = id >> 3, kc = id & 7;
;             if (HYT && kt >= 12) { const int kk = id >> 4, rr = (id & 15) * 8; bf16_t* d = As + (buf * 128 + rr) * LS + kk; const bf16x8 v = __builtin_bit_cast(bf16x8, r[i]);
; #pragma unroll
;                 for (int e = 0; e < 8; ++e) d[e * LS] = (bf16_t)v[e]; }
;             else *(u32x4*)(As + (buf * 128 + row) * LS + kc * 8) = r[i];
;             *(u32x4*)(Bs + (buf * 128 + row) * LS + kc * 8) = r[4 + i]; }
;     };
;     auto step = [&](int kt, u32x4 (&ldset)[8], const u32x4 (&stset)[8]) {
;         const int buf = kt & 1;
;         if (kt + 2 < nk) gload(ldset, kt + 2);
;         const bf16_t* Ab = As + (buf * 128 + 64 * wr + li) * LS + 8 * lh;
;         const bf16_t* Bb = Bs + (buf * 128 + 64 * wc + li) * LS + 8 * lh;
;         bf16x8 fa[2][2], fb[2][2], ga[2][2], gb[2][2];
; #pragma unroll
;         for (int k2 = 0; k2 < 2; ++k2) { fa[k2][0] = ld8(Ab + 16 * k2); fa[k2][1] = ld8(Ab + 32 * LS + 16 * k2); fb[k2][0] = ld8(Bb + 16 * k2); fb[k2][1] = ld8(Bb + 32 * LS + 16 * k2); }
;         __builtin_amdgcn_sched_barrier(0);
; #pragma unroll
;         for (int k2 = 0; k2 < 2; ++k2) {
;             acc[0][0] = MFMA(fa[k2][0], fb[k2][0], acc[0][0]); acc[0][1] = MFMA(fa[k2][0], fb[k2][1], acc[0][1]);
;             acc[1][0] = MFMA(fa[k2][1], fb[k2][0], acc[1][0]); acc[1][1] = MFMA(fa[k2][1], fb[k2][1], acc[1][1]);
;         }
; #pragma unroll
	ds_read_b128 v[202:205], v194
	ds_read_b128 v[206:209], v194 offset:32
	ds_read_b128 v[210:213], v194 offset:4608
	ds_read_b128 v[214:217], v194 offset:4640
	ds_read_b128 v[218:221], v195 offset:36864
	ds_read_b128 v[222:225], v195 offset:36896
	ds_read_b128 v[226:229], v195 offset:41472
	ds_read_b128 v[230:233], v195 offset:41504
	s_waitcnt lgkmcnt(3)
	v_mfma_f32_32x32x16_bf16 v[52:67], v[202:205], v[218:221], v[52:67]
	global_load_dwordx4 v[132:135], v[164:165], off offset:640
	s_waitcnt lgkmcnt(1)
	v_mfma_f32_32x32x16_bf16 v[36:51], v[202:205], v[226:229], v[36:51]
	global_load_dwordx4 v[136:139], v[162:163], off offset:640
	v_mfma_f32_32x32x16_bf16 v[4:19], v[210:213], v[226:229], v[4:19]
	global_load_dwordx4 v[140:143], v[160:161], off offset:640
	s_waitcnt lgkmcnt(0)
	v_mfma_f32_32x32x16_bf16 v[36:51], v[206:209], v[230:233], v[36:51]
	global_load_dwordx4 v[198:201], v[158:159], off offset:640
	v_mfma_f32_32x32x16_bf16 v[4:19], v[214:217], v[230:233], v[4:19]
	global_load_dwordx4 v[174:177], v[156:157], off offset:640
	ds_read_b128 v[230:233], v195 offset:41568
	ds_read_b128 v[202:205], v194 offset:4672
	v_mfma_f32_32x32x16_bf16 v[20:35], v[210:213], v[218:221], v[20:35]
	global_load_dwordx4 v[178:181], v[154:155], off offset:640
	ds_read_b128 v[218:221], v194 offset:4704
	ds_read_b128 v[210:213], v194 offset:64
	v_mfma_f32_32x32x16_bf16 v[52:67], v[206:209], v[222:225], v[52:67]
	global_load_dwordx4 v[242:245], v[152:153], off offset:640
	ds_read_b128 v[226:229], v195 offset:36960
	ds_read_b128 v[206:209], v195 offset:41536
	v_mfma_f32_32x32x16_bf16 v[20:35], v[214:217], v[222:225], v[20:35]
	global_load_dwordx4 v[246:249], v[146:147], off offset:640
	ds_read_b128 v[222:225], v195 offset:36928
	ds_read_b128 v[214:217], v194 offset:96
	s_waitcnt lgkmcnt(1)
	v_mfma_f32_32x32x16_bf16 v[52:67], v[210:213], v[222:225], v[52:67]
	s_waitcnt vmcnt(23)
	ds_write_b128 v167, v[68:71] offset:18432
	v_mfma_f32_32x32x16_bf16 v[36:51], v[210:213], v[206:209], v[36:51]
	s_waitcnt vmcnt(22)
	ds_write_b128 v167, v[72:75] offset:55296
	v_mfma_f32_32x32x16_bf16 v[20:35], v[202:205], v[222:225], v[20:35]
	s_waitcnt vmcnt(21)
	ds_write_b128 v190, v[76:79] offset:18432
	v_mfma_f32_32x32x16_bf16 v[4:19], v[202:205], v[206:209], v[4:19]
	s_waitcnt vmcnt(20)
	ds_write_b128 v190, v[80:83] offset:55296
	s_waitcnt lgkmcnt(4)
	v_mfma_f32_32x32x16_bf16 v[52:67], v[214:217], v[226:229], v[52:67]
	s_waitcnt vmcnt(19)
	ds_write_b128 v191, v[84:87] offset:18432
	v_mfma_f32_32x32x16_bf16 v[36:51], v[214:217], v[230:233], v[36:51]
	s_waitcnt vmcnt(18)
	ds_write_b128 v191, v[88:91] offset:55296
	v_mfma_f32_32x32x16_bf16 v[20:35], v[218:221], v[226:229], v[20:35]
	s_waitcnt vmcnt(17)
	ds_write_b128 v192, v[92:95] offset:18432
	v_mfma_f32_32x32x16_bf16 v[4:19], v[218:221], v[230:233], v[4:19]
	s_waitcnt vmcnt(16)
	ds_write_b128 v192, v[104:107] offset:55296
	s_waitcnt lgkmcnt(0)
	s_barrier
	ds_read_b128 v[202:205], v196
	ds_read_b128 v[206:209], v196 offset:32
	ds_read_b128 v[210:213], v196 offset:4608
	ds_read_b128 v[214:217], v196 offset:4640
	ds_read_b128 v[218:221], v197 offset:36864
	ds_read_b128 v[222:225], v197 offset:36896
	ds_read_b128 v[226:229], v197 offset:41472
	ds_read_b128 v[230:233], v197 offset:41504
	s_waitcnt lgkmcnt(3)
	v_mfma_f32_32x32x16_bf16 v[52:67], v[202:205], v[218:221], v[52:67]
	global_load_dwordx4 v[68:71], v[164:165], off offset:768
	s_waitcnt lgkmcnt(1)
	v_mfma_f32_32x32x16_bf16 v[36:51], v[202:205], v[226:229], v[36:51]
	global_load_dwordx4 v[72:75], v[162:163], off offset:768
	v_mfma_f32_32x32x16_bf16 v[4:19], v[210:213], v[226:229], v[4:19]
	global_load_dwordx4 v[76:79], v[160:161], off offset:768
	s_waitcnt lgkmcnt(0)
	v_mfma_f32_32x32x16_bf16 v[36:51], v[206:209], v[230:233], v[36:51]
	global_load_dwordx4 v[80:83], v[158:159], off offset:768
	v_mfma_f32_32x32x16_bf16 v[4:19], v[214:217], v[230:233], v[4:19]
	global_load_dwordx4 v[84:87], v[156:157], off offset:768
	ds_read_b128 v[230:233], v197 offset:41568
	ds_read_b128 v[202:205], v196 offset:4672
	v_mfma_f32_32x32x16_bf16 v[20:35], v[210:213], v[218:221], v[20:35]
	global_load_dwordx4 v[88:91], v[154:155], off offset:768
	ds_read_b128 v[218:221], v196 offset:4704
	ds_read_b128 v[210:213], v196 offset:64
	v_mfma_f32_32x32x16_bf16 v[52:67], v[206:209], v[222:225], v[52:67]
	global_load_dwordx4 v[92:95], v[152:153], off offset:768
	ds_read_b128 v[226:229], v197 offset:36960
	ds_read_b128 v[206:209], v197 offset:41536
	v_mfma_f32_32x32x16_bf16 v[20:35], v[214:217], v[222:225], v[20:35]
	global_load_dwordx4 v[104:107], v[146:147], off offset:768
	ds_read_b128 v[222:225], v197 offset:36928
	ds_read_b128 v[214:217], v196 offset:96
	s_waitcnt lgkmcnt(1)
	v_mfma_f32_32x32x16_bf16 v[52:67], v[210:213], v[222:225], v[52:67]
	s_waitcnt vmcnt(23)
	ds_write_b128 v167, v[96:99]
	v_mfma_f32_32x32x16_bf16 v[36:51], v[210:213], v[206:209], v[36:51]
	s_waitcnt vmcnt(22)
	ds_write_b128 v167, v[100:103] offset:36864
	v_mfma_f32_32x32x16_bf16 v[20:35], v[202:205], v[222:225], v[20:35]
	s_waitcnt vmcnt(21)
	ds_write_b128 v190, v[108:111]
	v_mfma_f32_32x32x16_bf16 v[4:19], v[202:205], v[206:209], v[4:19]
	s_waitcnt vmcnt(20)
	ds_write_b128 v190, v[112:115] offset:36864
	s_waitcnt lgkmcnt(4)
	v_mfma_f32_32x32x16_bf16 v[52:67], v[214:217], v[226:229], v[52:67]
	s_waitcnt vmcnt(19)
	ds_write_b128 v191, v[116:119]
	v_mfma_f32_32x32x16_bf16 v[36:51], v[214:217], v[230:233], v[36:51]
	s_waitcnt vmcnt(18)
	ds_write_b128 v191, v[120:123] offset:36864
	v_mfma_f32_32x32x16_bf16 v[20:35], v[218:221], v[226:229], v[20:35]
	s_waitcnt vmcnt(17)
	ds_write_b128 v192, v[124:127]
	v_mfma_f32_32x32x16_bf16 v[4:19], v[218:221], v[230:233], v[4:19]
	s_waitcnt vmcnt(16)
	ds_write_b128 v192, v[128:131] offset:36864
	s_waitcnt lgkmcnt(0)
	s_barrier
; #define MFMA(a, b, c) __builtin_amdgcn_mfma_f32_32x32x16_bf16((a), (b), (c), 0, 0, 0)
; template <class Epi, class ColV>
; DI void gemm_tile(const bf16_t* __restrict__ A, int lda, const bf16_t* __restrict__ Bt, int ldb, int K, int m0, int n0, unsigned char* smem, Epi epi, ColV colv, const bf16_t* __restrict__ HYT = nullptr) {
;     ...
;     auto gload = [&](u32x4 (&r)[8], int kt) {
; #pragma unroll
;         for (int i = 0; i < 4; ++i) { int id = tid + 256 * i, row = id >> 3, kc = id & 7;
;             if (HYT && kt >= 12) r[i] = *(const u32x4*)(HYT + (size_t)((kt - 12) * 64 + (id >> 4)) * NT + m0 + (id & 15) * 8);
;             else r[i] = *(const u32x4*)(A + (size_t)(m0 + row) * lda + kt * 64 + kc * 8);
;             r[4 + i] = *(const u32x4*)(Bt + (size_t)(n0 + row) * ldb + kt * 64 + kc * 8); }
;     };
;     auto sstore = [&](const u32x4 (&r)[8], int buf, int kt) {
; #pragma unroll
;         for (int i = 0; i < 4; ++i) { int id = tid + 256 * i, row = id >> 3, kc = id & 7;
;             if (HYT && kt >= 12) { const int kk = id >> 4, rr = (id & 15) * 8; bf16_t* d = As + (buf * 128 + rr) * LS + kk; const bf16x8 v = __builtin_bit_cast(bf16x8, r[i]);
; #pragma unroll
;                 for (int e = 0; e < 8; ++e) d[e * LS] = (bf16_t)v[e]; }
;             else *(u32x4*)(As + (buf * 128 + row) * LS + kc * 8) = r[i];
;             *(u32x4*)(Bs + (buf * 128 + row) * LS + kc * 8) = r[4 + i]; }
;     };
;     auto step = [&](int kt, u32x4 (&ldset)[8], const u32x4 (&stset)[8]) {
;         const int buf = kt & 1;
;         if (kt + 2 < nk) gload(ldset, kt + 2);
;         const bf16_t* Ab = As + (buf * 128 + 64 * wr + li) * LS + 8 * lh;
;         const bf16_t* Bb = Bs + (buf * 128 + 64 * wc + li) * LS + 8 * lh;
;         bf16x8 fa[2][2], fb[2][2], ga[2][2], gb[2][2];
; #pragma unroll
;         for (int k2 = 0; k2 < 2; ++k2) { fa[k2][0] = ld8(Ab + 16 * k2); fa[k2][1] = ld8(Ab + 32 * LS + 16 * k2); fb[k2][0] = ld8(Bb + 16 * k2); fb[k2][1] = ld8(Bb + 32 * LS + 16 * k2); }
;         __builtin_amdgcn_sched_barrier(0);
; #pragma unroll
;         for (int k2 = 0; k2 < 2; ++k2) {
;             acc[0][0] = MFMA(fa[k2][0], fb[k2][0], acc[0][0]); acc[0][1] = MFMA(fa[k2][0], fb[k2][1], acc[0][1]);
;             acc[1][0] = MFMA(fa[k2][1], fb[k2][0], acc[1][0]); acc[1][1] = MFMA(fa[k2][1], fb[k2][1], acc[1][1]);
;         }
; #pragma unroll
	ds_read_b128 v[202:205], v194
	ds_read_b128 v[206:209], v194 offset:32
	ds_read_b128 v[210:213], v194 offset:4608
	ds_read_b128 v[214:217], v194 offset:4640
	ds_read_b128 v[218:221], v195 offset:36864
	ds_read_b128 v[222:225], v195 offset:36896
	ds_read_b128 v[226:229], v195 offset:41472
	ds_read_b128 v[230:233], v195 offset:41504
	s_waitcnt lgkmcnt(3)
	v_mfma_f32_32x32x16_bf16 v[52:67], v[202:205], v[218:221], v[52:67]
	global_load_dwordx4 v[96:99], v[164:165], off offset:896
	s_waitcnt lgkmcnt(1)
	v_mfma_f32_32x32x16_bf16 v[36:51], v[202:205], v[226:229], v[36:51]
	global_load_dwordx4 v[100:103], v[162:163], off offset:896
	v_mfma_f32_32x32x16_bf16 v[4:19], v[210:213], v[226:229], v[4:19]
	global_load_dwordx4 v[108:111], v[160:161], off offset:896
	s_waitcnt lgkmcnt(0)
	v_mfma_f32_32x32x16_bf16 v[36:51], v[206:209], v[230:233], v[36:51]
	global_load_dwordx4 v[112:115], v[158:159], off offset:896
	v_mfma_f32_32x32x16_bf16 v[4:19], v[214:217], v[230:233], v[4:19]
	global_load_dwordx4 v[116:119], v[156:157], off offset:896
	ds_read_b128 v[230:233], v195 offset:41568
	ds_read_b128 v[202:205], v194 offset:4672
	v_mfma_f32_32x32x16_bf16 v[20:35], v[210:213], v[218:221], v[20:35]
	global_load_dwordx4 v[120:123], v[154:155], off offset:896
	ds_read_b128 v[218:221], v194 offset:4704
	ds_read_b128 v[210:213], v194 offset:64
	v_mfma_f32_32x32x16_bf16 v[52:67], v[206:209], v[222:225], v[52:67]
	global_load_dwordx4 v[124:127], v[152:153], off offset:896
	ds_read_b128 v[226:229], v195 offset:36960
	ds_read_b128 v[206:209], v195 offset:41536
	v_mfma_f32_32x32x16_bf16 v[20:35], v[214:217], v[222:225], v[20:35]
	global_load_dwordx4 v[128:131], v[146:147], off offset:896
	ds_read_b128 v[222:225], v195 offset:36928
	ds_read_b128 v[214:217], v194 offset:96
	s_waitcnt lgkmcnt(1)
	v_mfma_f32_32x32x16_bf16 v[52:67], v[210:213], v[222:225], v[52:67]
	s_waitcnt vmcnt(23)
	ds_write_b128 v167, v[132:135] offset:18432
	v_mfma_f32_32x32x16_bf16 v[36:51], v[210:213], v[206:209], v[36:51]
	s_waitcnt vmcnt(22)
	ds_write_b128 v167, v[136:139] offset:55296
	v_mfma_f32_32x32x16_bf16 v[20:35], v[202:205], v[222:225], v[20:35]
	s_waitcnt vmcnt(21)
	ds_write_b128 v190, v[140:143] offset:18432
	v_mfma_f32_32x32x16_bf16 v[4:19], v[202:205], v[206:209], v[4:19]
	s_waitcnt vmcnt(20)
	ds_write_b128 v190, v[198:201] offset:55296
	s_waitcnt lgkmcnt(4)
	v_mfma_f32_32x32x16_bf16 v[52:67], v[214:217], v[226:229], v[52:67]
	s_waitcnt vmcnt(19)
	ds_write_b128 v191, v[174:177] offset:18432
	v_mfma_f32_32x32x16_bf16 v[36:51], v[214:217], v[230:233], v[36:51]
	s_waitcnt vmcnt(18)
	ds_write_b128 v191, v[178:181] offset:55296
	v_mfma_f32_32x32x16_bf16 v[20:35], v[218:221], v[226:229], v[20:35]
	s_waitcnt vmcnt(17)
	ds_write_b128 v192, v[242:245] offset:18432
	v_mfma_f32_32x32x16_bf16 v[4:19], v[218:221], v[230:233], v[4:19]
	s_waitcnt vmcnt(16)
	ds_write_b128 v192, v[246:249] offset:55296
	s_waitcnt lgkmcnt(0)
	s_barrier
	ds_read_b128 v[202:205], v196
	ds_read_b128 v[206:209], v196 offset:32
	ds_read_b128 v[210:213], v196 offset:4608
	ds_read_b128 v[214:217], v196 offset:4640
	ds_read_b128 v[218:221], v197 offset:36864
	ds_read_b128 v[222:225], v197 offset:36896
	ds_read_b128 v[226:229], v197 offset:41472
	ds_read_b128 v[230:233], v197 offset:41504
	s_waitcnt lgkmcnt(3)
	v_mfma_f32_32x32x16_bf16 v[52:67], v[202:205], v[218:221], v[52:67]
	global_load_dwordx4 v[132:135], v[164:165], off offset:1024
	s_waitcnt lgkmcnt(1)
	v_mfma_f32_32x32x16_bf16 v[36:51], v[202:205], v[226:229], v[36:51]
	global_load_dwordx4 v[136:139], v[162:163], off offset:1024
	v_mfma_f32_32x32x16_bf16 v[4:19], v[210:213], v[226:229], v[4:19]
	global_load_dwordx4 v[140:143], v[160:161], off offset:1024
	s_waitcnt lgkmcnt(0)
	v_mfma_f32_32x32x16_bf16 v[36:51], v[206:209], v[230:233], v[36:51]
	global_load_dwordx4 v[198:201], v[158:159], off offset:1024
	v_mfma_f32_32x32x16_bf16 v[4:19], v[214:217], v[230:233], v[4:19]
	global_load_dwordx4 v[174:177], v[156:157], off offset:1024
	ds_read_b128 v[230:233], v197 offset:41568
	ds_read_b128 v[202:205], v196 offset:4672
	v_mfma_f32_32x32x16_bf16 v[20:35], v[210:213], v[218:221], v[20:35]
	global_load_dwordx4 v[178:181], v[154:155], off offset:1024
	ds_read_b128 v[218:221], v196 offset:4704
	ds_read_b128 v[210:213], v196 offset:64
	v_mfma_f32_32x32x16_bf16 v[52:67], v[206:209], v[222:225], v[52:67]
	global_load_dwordx4 v[242:245], v[152:153], off offset:1024
	ds_read_b128 v[226:229], v197 offset:36960
	ds_read_b128 v[206:209], v197 offset:41536
	v_mfma_f32_32x32x16_bf16 v[20:35], v[214:217], v[222:225], v[20:35]
	global_load_dwordx4 v[246:249], v[146:147], off offset:1024
	ds_read_b128 v[222:225], v197 offset:36928
	ds_read_b128 v[214:217], v196 offset:96
	s_waitcnt lgkmcnt(1)
	v_mfma_f32_32x32x16_bf16 v[52:67], v[210:213], v[222:225], v[52:67]
	s_waitcnt vmcnt(23)
	ds_write_b128 v167, v[68:71]
	v_mfma_f32_32x32x16_bf16 v[36:51], v[210:213], v[206:209], v[36:51]
	s_waitcnt vmcnt(22)
	ds_write_b128 v167, v[72:75] offset:36864
	v_mfma_f32_32x32x16_bf16 v[20:35], v[202:205], v[222:225], v[20:35]
	s_waitcnt vmcnt(21)
	ds_write_b128 v190, v[76:79]
	v_mfma_f32_32x32x16_bf16 v[4:19], v[202:205], v[206:209], v[4:19]
	s_waitcnt vmcnt(20)
	ds_write_b128 v190, v[80:83] offset:36864
	s_waitcnt lgkmcnt(4)
	v_mfma_f32_32x32x16_bf16 v[52:67], v[214:217], v[226:229], v[52:67]
	s_waitcnt vmcnt(19)
	ds_write_b128 v191, v[84:87]
	v_mfma_f32_32x32x16_bf16 v[36:51], v[214:217], v[230:233], v[36:51]
	s_waitcnt vmcnt(18)
	ds_write_b128 v191, v[88:91] offset:36864
	v_mfma_f32_32x32x16_bf16 v[20:35], v[218:221], v[226:229], v[20:35]
	s_waitcnt vmcnt(17)
	ds_write_b128 v192, v[92:95]
	v_mfma_f32_32x32x16_bf16 v[4:19], v[218:221], v[230:233], v[4:19]
	s_waitcnt vmcnt(16)
	ds_write_b128 v192, v[104:107] offset:36864
	s_waitcnt lgkmcnt(0)
	s_barrier
; #define MFMA(a, b, c) __builtin_amdgcn_mfma_f32_32x32x16_bf16((a), (b), (c), 0, 0, 0)
; template <class Epi, class ColV>
; DI void gemm_tile(const bf16_t* __restrict__ A, int lda, const bf16_t* __restrict__ Bt, int ldb, int K, int m0, int n0, unsigned char* smem, Epi epi, ColV colv, const bf16_t* __restrict__ HYT = nullptr) {
;     ...
;     auto gload = [&](u32x4 (&r)[8], int kt) {
; #pragma unroll
;         for (int i = 0; i < 4; ++i) { int id = tid + 256 * i, row = id >> 3, kc = id & 7;
;             if (HYT && kt >= 12) r[i] = *(const u32x4*)(HYT + (size_t)((kt - 12) * 64 + (id >> 4)) * NT + m0 + (id & 15) * 8);
;             else r[i] = *(const u32x4*)(A + (size_t)(m0 + row) * lda + kt * 64 + kc * 8);
;             r[4 + i] = *(const u32x4*)(Bt + (size_t)(n0 + row) * ldb + kt * 64 + kc * 8); }
;     };
;     auto sstore = [&](const u32x4 (&r)[8], int buf, int kt) {
; #pragma unroll
;         for (int i = 0; i < 4; ++i) { int id = tid + 256 * i, row = id >> 3, kc = id & 7;
;             if (HYT && kt >= 12) { const int kk = id >> 4, rr = (id & 15) * 8; bf16_t* d = As + (buf * 128 + rr) * LS + kk; const bf16x8 v = __builtin_bit_cast(bf16x8, r[i]);
; #pragma unroll
;                 for (int e = 0; e < 8; ++e) d[e * LS] = (bf16_t)v[e]; }
;             else *(u32x4*)(As + (buf * 128 + row) * LS + kc * 8) = r[i];
;             *(u32x4*)(Bs + (buf * 128 + row) * LS + kc * 8) = r[4 + i]; }
;     };
;     auto step = [&](int kt, u32x4 (&ldset)[8], const u32x4 (&stset)[8]) {
;         const int buf = kt & 1;
;         if (kt + 2 < nk) gload(ldset, kt + 2);
;         const bf16_t* Ab = As + (buf * 128 + 64 * wr + li) * LS + 8 * lh;
;         const bf16_t* Bb = Bs + (buf * 128 + 64 * wc + li) * LS + 8 * lh;
;         bf16x8 fa[2][2], fb[2][2], ga[2][2], gb[2][2];
; #pragma unroll
;         for (int k2 = 0; k2 < 2; ++k2) { fa[k2][0] = ld8(Ab + 16 * k2); fa[k2][1] = ld8(Ab + 32 * LS + 16 * k2); fb[k2][0] = ld8(Bb + 16 * k2); fb[k2][1] = ld8(Bb + 32 * LS + 16 * k2); }
;         __builtin_amdgcn_sched_barrier(0);
; #pragma unroll
;         for (int k2 = 0; k2 < 2; ++k2) {
;             acc[0][0] = MFMA(fa[k2][0], fb[k2][0], acc[0][0]); acc[0][1] = MFMA(fa[k2][0], fb[k2][1], acc[0][1]);
;             acc[1][0] = MFMA(fa[k2][1], fb[k2][0], acc[1][0]); acc[1][1] = MFMA(fa[k2][1], fb[k2][1], acc[1][1]);
;         }
; #pragma unroll
	ds_read_b128 v[202:205], v194
	ds_read_b128 v[206:209], v194 offset:32
	ds_read_b128 v[210:213], v194 offset:4608
	ds_read_b128 v[214:217], v194 offset:4640
	ds_read_b128 v[218:221], v195 offset:36864
	ds_read_b128 v[222:225], v195 offset:36896
	ds_read_b128 v[226:229], v195 offset:41472
	ds_read_b128 v[230:233], v195 offset:41504
	s_waitcnt lgkmcnt(3)
	v_mfma_f32_32x32x16_bf16 v[52:67], v[202:205], v[218:221], v[52:67]
	global_load_dwordx4 v[68:71], v[164:165], off offset:1152
	s_waitcnt lgkmcnt(1)
	v_mfma_f32_32x32x16_bf16 v[36:51], v[202:205], v[226:229], v[36:51]
	global_load_dwordx4 v[72:75], v[162:163], off offset:1152
	v_mfma_f32_32x32x16_bf16 v[4:19], v[210:213], v[226:229], v[4:19]
	global_load_dwordx4 v[76:79], v[160:161], off offset:1152
	s_waitcnt lgkmcnt(0)
	v_mfma_f32_32x32x16_bf16 v[36:51], v[206:209], v[230:233], v[36:51]
	global_load_dwordx4 v[80:83], v[158:159], off offset:1152
	v_mfma_f32_32x32x16_bf16 v[4:19], v[214:217], v[230:233], v[4:19]
	global_load_dwordx4 v[84:87], v[156:157], off offset:1152
	ds_read_b128 v[230:233], v195 offset:41568
	ds_read_b128 v[202:205], v194 offset:4672
	v_mfma_f32_32x32x16_bf16 v[20:35], v[210:213], v[218:221], v[20:35]
	global_load_dwordx4 v[88:91], v[154:155], off offset:1152
	ds_read_b128 v[218:221], v194 offset:4704
	ds_read_b128 v[210:213], v194 offset:64
	v_mfma_f32_32x32x16_bf16 v[52:67], v[206:209], v[222:225], v[52:67]
	global_load_dwordx4 v[92:95], v[152:153], off offset:1152
	ds_read_b128 v[226:229], v195 offset:36960
	ds_read_b128 v[206:209], v195 offset:41536
	v_mfma_f32_32x32x16_bf16 v[20:35], v[214:217], v[222:225], v[20:35]
	global_load_dwordx4 v[104:107], v[146:147], off offset:1152
	ds_read_b128 v[222:225], v195 offset:36928
	ds_read_b128 v[214:217], v194 offset:96
	s_waitcnt lgkmcnt(1)
	v_mfma_f32_32x32x16_bf16 v[52:67], v[210:213], v[222:225], v[52:67]
	s_waitcnt vmcnt(23)
	ds_write_b128 v167, v[96:99] offset:18432
	v_mfma_f32_32x32x16_bf16 v[36:51], v[210:213], v[206:209], v[36:51]
	s_waitcnt vmcnt(22)
	ds_write_b128 v167, v[100:103] offset:55296
	v_mfma_f32_32x32x16_bf16 v[20:35], v[202:205], v[222:225], v[20:35]
	s_waitcnt vmcnt(21)
	ds_write_b128 v190, v[108:111] offset:18432
	v_mfma_f32_32x32x16_bf16 v[4:19], v[202:205], v[206:209], v[4:19]
	s_waitcnt vmcnt(20)
	ds_write_b128 v190, v[112:115] offset:55296
	s_waitcnt lgkmcnt(4)
	v_mfma_f32_32x32x16_bf16 v[52:67], v[214:217], v[226:229], v[52:67]
	s_waitcnt vmcnt(19)
	ds_write_b128 v191, v[116:119] offset:18432
	v_mfma_f32_32x32x16_bf16 v[36:51], v[214:217], v[230:233], v[36:51]
	s_waitcnt vmcnt(18)
	ds_write_b128 v191, v[120:123] offset:55296
	v_mfma_f32_32x32x16_bf16 v[20:35], v[218:221], v[226:229], v[20:35]
	s_waitcnt vmcnt(17)
	ds_write_b128 v192, v[124:127] offset:18432
	v_mfma_f32_32x32x16_bf16 v[4:19], v[218:221], v[230:233], v[4:19]
	s_waitcnt vmcnt(16)
	ds_write_b128 v192, v[128:131] offset:55296
	s_waitcnt lgkmcnt(0)
	s_barrier
	ds_read_b128 v[202:205], v196
	ds_read_b128 v[206:209], v196 offset:32
	ds_read_b128 v[210:213], v196 offset:4608
	ds_read_b128 v[214:217], v196 offset:4640
	ds_read_b128 v[218:221], v197 offset:36864
	ds_read_b128 v[222:225], v197 offset:36896
	ds_read_b128 v[226:229], v197 offset:41472
	ds_read_b128 v[230:233], v197 offset:41504
	s_waitcnt lgkmcnt(3)
	v_mfma_f32_32x32x16_bf16 v[52:67], v[202:205], v[218:221], v[52:67]
	global_load_dwordx4 v[96:99], v[164:165], off offset:1280
	s_waitcnt lgkmcnt(1)
	v_mfma_f32_32x32x16_bf16 v[36:51], v[202:205], v[226:229], v[36:51]
	global_load_dwordx4 v[100:103], v[162:163], off offset:1280
	v_mfma_f32_32x32x16_bf16 v[4:19], v[210:213], v[226:229], v[4:19]
	global_load_dwordx4 v[108:111], v[160:161], off offset:1280
	s_waitcnt lgkmcnt(0)
	v_mfma_f32_32x32x16_bf16 v[36:51], v[206:209], v[230:233], v[36:51]
	global_load_dwordx4 v[112:115], v[158:159], off offset:1280
	v_mfma_f32_32x32x16_bf16 v[4:19], v[214:217], v[230:233], v[4:19]
	global_load_dwordx4 v[116:119], v[156:157], off offset:1280
	ds_read_b128 v[230:233], v197 offset:41568
	ds_read_b128 v[202:205], v196 offset:4672
	v_mfma_f32_32x32x16_bf16 v[20:35], v[210:213], v[218:221], v[20:35]
	global_load_dwordx4 v[120:123], v[154:155], off offset:1280
	ds_read_b128 v[218:221], v196 offset:4704
	ds_read_b128 v[210:213], v196 offset:64
	v_mfma_f32_32x32x16_bf16 v[52:67], v[206:209], v[222:225], v[52:67]
	global_load_dwordx4 v[124:127], v[152:153], off offset:1280
	ds_read_b128 v[226:229], v197 offset:36960
	ds_read_b128 v[206:209], v197 offset:41536
	v_mfma_f32_32x32x16_bf16 v[20:35], v[214:217], v[222:225], v[20:35]
	global_load_dwordx4 v[128:131], v[146:147], off offset:1280
	ds_read_b128 v[222:225], v197 offset:36928
	ds_read_b128 v[214:217], v196 offset:96
	s_waitcnt lgkmcnt(1)
	v_mfma_f32_32x32x16_bf16 v[52:67], v[210:213], v[222:225], v[52:67]
	s_waitcnt vmcnt(23)
	ds_write_b128 v167, v[132:135]
	v_mfma_f32_32x32x16_bf16 v[36:51], v[210:213], v[206:209], v[36:51]
	s_waitcnt vmcnt(22)
	ds_write_b128 v167, v[136:139] offset:36864
	v_mfma_f32_32x32x16_bf16 v[20:35], v[202:205], v[222:225], v[20:35]
	s_waitcnt vmcnt(21)
	ds_write_b128 v190, v[140:143]
	v_mfma_f32_32x32x16_bf16 v[4:19], v[202:205], v[206:209], v[4:19]
	s_waitcnt vmcnt(20)
	ds_write_b128 v190, v[198:201] offset:36864
	s_waitcnt lgkmcnt(4)
	v_mfma_f32_32x32x16_bf16 v[52:67], v[214:217], v[226:229], v[52:67]
	s_waitcnt vmcnt(19)
	ds_write_b128 v191, v[174:177]
	v_mfma_f32_32x32x16_bf16 v[36:51], v[214:217], v[230:233], v[36:51]
	s_waitcnt vmcnt(18)
	ds_write_b128 v191, v[178:181] offset:36864
	v_mfma_f32_32x32x16_bf16 v[20:35], v[218:221], v[226:229], v[20:35]
	s_waitcnt vmcnt(17)
	ds_write_b128 v192, v[242:245]
	v_mfma_f32_32x32x16_bf16 v[4:19], v[218:221], v[230:233], v[4:19]
	s_waitcnt vmcnt(16)
	ds_write_b128 v192, v[246:249] offset:36864
	s_waitcnt lgkmcnt(0)
	s_barrier
; #define MFMA(a, b, c) __builtin_amdgcn_mfma_f32_32x32x16_bf16((a), (b), (c), 0, 0, 0)
; template <class Epi, class ColV>
; DI void gemm_tile(const bf16_t* __restrict__ A, int lda, const bf16_t* __restrict__ Bt, int ldb, int K, int m0, int n0, unsigned char* smem, Epi epi, ColV colv, const bf16_t* __restrict__ HYT = nullptr) {
;     ...
;     auto gload = [&](u32x4 (&r)[8], int kt) {
; #pragma unroll
;         for (int i = 0; i < 4; ++i) { int id = tid + 256 * i, row = id >> 3, kc = id & 7;
;             if (HYT && kt >= 12) r[i] = *(const u32x4*)(HYT + (size_t)((kt - 12) * 64 + (id >> 4)) * NT + m0 + (id & 15) * 8);
;             else r[i] = *(const u32x4*)(A + (size_t)(m0 + row) * lda + kt * 64 + kc * 8);
;             r[4 + i] = *(const u32x4*)(Bt + (size_t)(n0 + row) * ldb + kt * 64 + kc * 8); }
;     };
;     auto sstore = [&](const u32x4 (&r)[8], int buf, int kt) {
; #pragma unroll
;         for (int i = 0; i < 4; ++i) { int id = tid + 256 * i, row = id >> 3, kc = id & 7;
;             if (HYT && kt >= 12) { const int kk = id >> 4, rr = (id & 15) * 8; bf16_t* d = As + (buf * 128 + rr) * LS + kk; const bf16x8 v = __builtin_bit_cast(bf16x8, r[i]);
; #pragma unroll
;                 for (int e = 0; e < 8; ++e) d[e * LS] = (bf16_t)v[e]; }
;             else *(u32x4*)(As + (buf * 128 + row) * LS + kc * 8) = r[i];
;             *(u32x4*)(Bs + (buf * 128 + row) * LS + kc * 8) = r[4 + i]; }
;     };
;     auto step = [&](int kt, u32x4 (&ldset)[8], const u32x4 (&stset)[8]) {
;         const int buf = kt & 1;
;         if (kt + 2 < nk) gload(ldset, kt + 2);
;         const bf16_t* Ab = As + (buf * 128 + 64 * wr + li) * LS + 8 * lh;
;         const bf16_t* Bb = Bs + (buf * 128 + 64 * wc + li) * LS + 8 * lh;
;         bf16x8 fa[2][2], fb[2][2], ga[2][2], gb[2][2];
; #pragma unroll
;         for (int k2 = 0; k2 < 2; ++k2) { fa[k2][0] = ld8(Ab + 16 * k2); fa[k2][1] = ld8(Ab + 32 * LS + 16 * k2); fb[k2][0] = ld8(Bb + 16 * k2); fb[k2][1] = ld8(Bb + 32 * LS + 16 * k2); }
;         __builtin_amdgcn_sched_barrier(0);
; #pragma unroll
;         for (int k2 = 0; k2 < 2; ++k2) {
;             acc[0][0] = MFMA(fa[k2][0], fb[k2][0], acc[0][0]); acc[0][1] = MFMA(fa[k2][0], fb[k2][1], acc[0][1]);
;             acc[1][0] = MFMA(fa[k2][1], fb[k2][0], acc[1][0]); acc[1][1] = MFMA(fa[k2][1], fb[k2][1], acc[1][1]);
;         }
; #pragma unroll
	ds_read_b128 v[202:205], v194
	ds_read_b128 v[206:209], v194 offset:32
	ds_read_b128 v[210:213], v194 offset:4608
	ds_read_b128 v[214:217], v194 offset:4640
	ds_read_b128 v[218:221], v195 offset:36864
	ds_read_b128 v[222:225], v195 offset:36896
	ds_read_b128 v[226:229], v195 offset:41472
	ds_read_b128 v[230:233], v195 offset:41504
	s_waitcnt lgkmcnt(3)
	v_mfma_f32_32x32x16_bf16 v[52:67], v[202:205], v[218:221], v[52:67]
	global_load_dwordx4 v[132:135], v[164:165], off offset:1408
	s_waitcnt lgkmcnt(1)
	v_mfma_f32_32x32x16_bf16 v[36:51], v[202:205], v[226:229], v[36:51]
	global_load_dwordx4 v[136:139], v[162:163], off offset:1408
	v_mfma_f32_32x32x16_bf16 v[4:19], v[210:213], v[226:229], v[4:19]
	global_load_dwordx4 v[140:143], v[160:161], off offset:1408
	s_waitcnt lgkmcnt(0)
	v_mfma_f32_32x32x16_bf16 v[36:51], v[206:209], v[230:233], v[36:51]
	global_load_dwordx4 v[198:201], v[158:159], off offset:1408
	v_mfma_f32_32x32x16_bf16 v[4:19], v[214:217], v[230:233], v[4:19]
	global_load_dwordx4 v[174:177], v[156:157], off offset:1408
	ds_read_b128 v[230:233], v195 offset:41568
	ds_read_b128 v[202:205], v194 offset:4672
	v_mfma_f32_32x32x16_bf16 v[20:35], v[210:213], v[218:221], v[20:35]
	global_load_dwordx4 v[178:181], v[154:155], off offset:1408
	ds_read_b128 v[218:221], v194 offset:4704
	ds_read_b128 v[210:213], v194 offset:64
	v_mfma_f32_32x32x16_bf16 v[52:67], v[206:209], v[222:225], v[52:67]
	global_load_dwordx4 v[242:245], v[152:153], off offset:1408
	ds_read_b128 v[226:229], v195 offset:36960
	ds_read_b128 v[206:209], v195 offset:41536
	v_mfma_f32_32x32x16_bf16 v[20:35], v[214:217], v[222:225], v[20:35]
	global_load_dwordx4 v[246:249], v[146:147], off offset:1408
	ds_read_b128 v[222:225], v195 offset:36928
	ds_read_b128 v[214:217], v194 offset:96
	s_waitcnt lgkmcnt(1)
	v_mfma_f32_32x32x16_bf16 v[52:67], v[210:213], v[222:225], v[52:67]
	s_waitcnt vmcnt(23)
	ds_write_b128 v167, v[68:71] offset:18432
	v_mfma_f32_32x32x16_bf16 v[36:51], v[210:213], v[206:209], v[36:51]
	s_waitcnt vmcnt(22)
	ds_write_b128 v167, v[72:75] offset:55296
	v_mfma_f32_32x32x16_bf16 v[20:35], v[202:205], v[222:225], v[20:35]
	s_waitcnt vmcnt(21)
	ds_write_b128 v190, v[76:79] offset:18432
	v_mfma_f32_32x32x16_bf16 v[4:19], v[202:205], v[206:209], v[4:19]
	s_waitcnt vmcnt(20)
	ds_write_b128 v190, v[80:83] offset:55296
	s_waitcnt lgkmcnt(4)
	v_mfma_f32_32x32x16_bf16 v[52:67], v[214:217], v[226:229], v[52:67]
	s_waitcnt vmcnt(19)
	ds_write_b128 v191, v[84:87] offset:18432
	v_mfma_f32_32x32x16_bf16 v[36:51], v[214:217], v[230:233], v[36:51]
	s_waitcnt vmcnt(18)
	ds_write_b128 v191, v[88:91] offset:55296
	v_mfma_f32_32x32x16_bf16 v[20:35], v[218:221], v[226:229], v[20:35]
	s_waitcnt vmcnt(17)
	ds_write_b128 v192, v[92:95] offset:18432
	v_mfma_f32_32x32x16_bf16 v[4:19], v[218:221], v[230:233], v[4:19]
	s_waitcnt vmcnt(16)
	ds_write_b128 v192, v[104:107] offset:55296
	s_waitcnt lgkmcnt(0)
	s_barrier
	ds_read_b128 v[202:205], v196
	ds_read_b128 v[206:209], v196 offset:32
	ds_read_b128 v[210:213], v196 offset:4608
	ds_read_b128 v[214:217], v196 offset:4640
	ds_read_b128 v[218:221], v197 offset:36864
	ds_read_b128 v[222:225], v197 offset:36896
	ds_read_b128 v[226:229], v197 offset:41472
	ds_read_b128 v[230:233], v197 offset:41504
	s_waitcnt lgkmcnt(3)
	v_mfma_f32_32x32x16_bf16 v[52:67], v[202:205], v[218:221], v[52:67]
	global_load_dwordx4 v[68:71], v[164:165], off offset:1536
	s_waitcnt lgkmcnt(1)
	v_mfma_f32_32x32x16_bf16 v[36:51], v[202:205], v[226:229], v[36:51]
	global_load_dwordx4 v[72:75], v[162:163], off offset:1536
	v_mfma_f32_32x32x16_bf16 v[4:19], v[210:213], v[226:229], v[4:19]
	global_load_dwordx4 v[76:79], v[160:161], off offset:1536
	s_waitcnt lgkmcnt(0)
	v_mfma_f32_32x32x16_bf16 v[36:51], v[206:209], v[230:233], v[36:51]
	global_load_dwordx4 v[80:83], v[158:159], off offset:1536
	v_mfma_f32_32x32x16_bf16 v[4:19], v[214:217], v[230:233], v[4:19]
	global_load_dwordx4 v[84:87], v[156:157], off offset:1536
	ds_read_b128 v[230:233], v197 offset:41568
	ds_read_b128 v[202:205], v196 offset:4672
	v_mfma_f32_32x32x16_bf16 v[20:35], v[210:213], v[218:221], v[20:35]
	global_load_dwordx4 v[88:91], v[154:155], off offset:1536
	ds_read_b128 v[218:221], v196 offset:4704
	ds_read_b128 v[210:213], v196 offset:64
	v_mfma_f32_32x32x16_bf16 v[52:67], v[206:209], v[222:225], v[52:67]
	global_load_dwordx4 v[92:95], v[152:153], off offset:1536
	ds_read_b128 v[226:229], v197 offset:36960
	ds_read_b128 v[206:209], v197 offset:41536
	v_mfma_f32_32x32x16_bf16 v[20:35], v[214:217], v[222:225], v[20:35]
	global_load_dwordx4 v[104:107], v[146:147], off offset:1536
	ds_read_b128 v[222:225], v197 offset:36928
	ds_read_b128 v[214:217], v196 offset:96
	s_waitcnt lgkmcnt(1)
	v_mfma_f32_32x32x16_bf16 v[52:67], v[210:213], v[222:225], v[52:67]
	s_waitcnt vmcnt(23)
	ds_write_b128 v167, v[96:99]
	v_mfma_f32_32x32x16_bf16 v[36:51], v[210:213], v[206:209], v[36:51]
	s_waitcnt vmcnt(22)
	ds_write_b128 v167, v[100:103] offset:36864
	v_mfma_f32_32x32x16_bf16 v[20:35], v[202:205], v[222:225], v[20:35]
	s_waitcnt vmcnt(21)
	ds_write_b128 v190, v[108:111]
	v_mfma_f32_32x32x16_bf16 v[4:19], v[202:205], v[206:209], v[4:19]
	s_waitcnt vmcnt(20)
	ds_write_b128 v190, v[112:115] offset:36864
	s_waitcnt lgkmcnt(4)
	v_mfma_f32_32x32x16_bf16 v[52:67], v[214:217], v[226:229], v[52:67]
	s_waitcnt vmcnt(19)
	ds_write_b128 v191, v[116:119]
	v_mfma_f32_32x32x16_bf16 v[36:51], v[214:217], v[230:233], v[36:51]
	s_waitcnt vmcnt(18)
	ds_write_b128 v191, v[120:123] offset:36864
	v_mfma_f32_32x32x16_bf16 v[20:35], v[218:221], v[226:229], v[20:35]
	s_waitcnt vmcnt(17)
	ds_write_b128 v192, v[124:127]
	v_mfma_f32_32x32x16_bf16 v[4:19], v[218:221], v[230:233], v[4:19]
	s_waitcnt vmcnt(16)
	ds_write_b128 v192, v[128:131] offset:36864
	s_waitcnt lgkmcnt(0)
	s_barrier
; #define MFMA(a, b, c) __builtin_amdgcn_mfma_f32_32x32x16_bf16((a), (b), (c), 0, 0, 0)
; template <class Epi, class ColV>
; DI void gemm_tile(const bf16_t* __restrict__ A, int lda, const bf16_t* __restrict__ Bt, int ldb, int K, int m0, int n0, unsigned char* smem, Epi epi, ColV colv, const bf16_t* __restrict__ HYT = nullptr) {
;     ...
;     auto gload = [&](u32x4 (&r)[8], int kt) {
; #pragma unroll
;         for (int i = 0; i < 4; ++i) { int id = tid + 256 * i, row = id >> 3, kc = id & 7;
;             if (HYT && kt >= 12) r[i] = *(const u32x4*)(HYT + (size_t)((kt - 12) * 64 + (id >> 4)) * NT + m0 + (id & 15) * 8);
;             else r[i] = *(const u32x4*)(A + (size_t)(m0 + row) * lda + kt * 64 + kc * 8);
;             r[4 + i] = *(const u32x4*)(Bt + (size_t)(n0 + row) * ldb + kt * 64 + kc * 8); }
;     };
;     auto sstore = [&](const u32x4 (&r)[8], int buf, int kt) {
; #pragma unroll
;         for (int i = 0; i < 4; ++i) { int id = tid + 256 * i, row = id >> 3, kc = id & 7;
;             if (HYT && kt >= 12) { const int kk = id >> 4, rr = (id & 15) * 8; bf16_t* d = As + (buf * 128 + rr) * LS + kk; const bf16x8 v = __builtin_bit_cast(bf16x8, r[i]);
; #pragma unroll
;                 for (int e = 0; e < 8; ++e) d[e * LS] = (bf16_t)v[e]; }
;             else *(u32x4*)(As + (buf * 128 + row) * LS + kc * 8) = r[i];
;             *(u32x4*)(Bs + (buf * 128 + row) * LS + kc * 8) = r[4 + i]; }
;     };
;     auto step = [&](int kt, u32x4 (&ldset)[8], const u32x4 (&stset)[8]) {
;         const int buf = kt & 1;
;         if (kt + 2 < nk) gload(ldset, kt + 2);
;         const bf16_t* Ab = As + (buf * 128 + 64 * wr + li) * LS + 8 * lh;
;         const bf16_t* Bb = Bs + (buf * 128 + 64 * wc + li) * LS + 8 * lh;
;         bf16x8 fa[2][2], fb[2][2], ga[2][2], gb[2][2];
; #pragma unroll
;         for (int k2 = 0; k2 < 2; ++k2) { fa[k2][0] = ld8(Ab + 16 * k2); fa[k2][1] = ld8(Ab + 32 * LS + 16 * k2); fb[k2][0] = ld8(Bb + 16 * k2); fb[k2][1] = ld8(Bb + 32 * LS + 16 * k2); }
;         __builtin_amdgcn_sched_barrier(0);
; #pragma unroll
;         for (int k2 = 0; k2 < 2; ++k2) {
;             acc[0][0] = MFMA(fa[k2][0], fb[k2][0], acc[0][0]); acc[0][1] = MFMA(fa[k2][0], fb[k2][1], acc[0][1]);
;             acc[1][0] = MFMA(fa[k2][1], fb[k2][0], acc[1][0]); acc[1][1] = MFMA(fa[k2][1], fb[k2][1], acc[1][1]);
;         }
; #pragma unroll
	ds_read_b128 v[202:205], v194
	ds_read_b128 v[206:209], v194 offset:32
	ds_read_b128 v[210:213], v194 offset:4608
	ds_read_b128 v[214:217], v194 offset:4640
	ds_read_b128 v[218:221], v195 offset:36864
	ds_read_b128 v[222:225], v195 offset:36896
	ds_read_b128 v[226:229], v195 offset:41472
	ds_read_b128 v[230:233], v195 offset:41504
	s_waitcnt lgkmcnt(3)
	v_mfma_f32_32x32x16_bf16 v[52:67], v[202:205], v[218:221], v[52:67]
	global_load_dwordx4 v[96:99], v[164:165], off offset:1664
	s_waitcnt lgkmcnt(1)
	v_mfma_f32_32x32x16_bf16 v[36:51], v[202:205], v[226:229], v[36:51]
	global_load_dwordx4 v[100:103], v[162:163], off offset:1664
	v_mfma_f32_32x32x16_bf16 v[4:19], v[210:213], v[226:229], v[4:19]
	global_load_dwordx4 v[108:111], v[160:161], off offset:1664
	s_waitcnt lgkmcnt(0)
	v_mfma_f32_32x32x16_bf16 v[36:51], v[206:209], v[230:233], v[36:51]
	global_load_dwordx4 v[112:115], v[158:159], off offset:1664
	v_mfma_f32_32x32x16_bf16 v[4:19], v[214:217], v[230:233], v[4:19]
	global_load_dwordx4 v[116:119], v[156:157], off offset:1664
	ds_read_b128 v[230:233], v195 offset:41568
	ds_read_b128 v[202:205], v194 offset:4672
	v_mfma_f32_32x32x16_bf16 v[20:35], v[210:213], v[218:221], v[20:35]
	global_load_dwordx4 v[120:123], v[154:155], off offset:1664
	ds_read_b128 v[218:221], v194 offset:4704
	ds_read_b128 v[210:213], v194 offset:64
	v_mfma_f32_32x32x16_bf16 v[52:67], v[206:209], v[222:225], v[52:67]
	global_load_dwordx4 v[124:127], v[152:153], off offset:1664
	ds_read_b128 v[226:229], v195 offset:36960
	ds_read_b128 v[206:209], v195 offset:41536
	v_mfma_f32_32x32x16_bf16 v[20:35], v[214:217], v[222:225], v[20:35]
	global_load_dwordx4 v[128:131], v[146:147], off offset:1664
	ds_read_b128 v[222:225], v195 offset:36928
	ds_read_b128 v[214:217], v194 offset:96
	s_waitcnt lgkmcnt(1)
	v_mfma_f32_32x32x16_bf16 v[52:67], v[210:213], v[222:225], v[52:67]
	s_waitcnt vmcnt(23)
	ds_write_b128 v167, v[132:135] offset:18432
	v_mfma_f32_32x32x16_bf16 v[36:51], v[210:213], v[206:209], v[36:51]
	s_waitcnt vmcnt(22)
	ds_write_b128 v167, v[136:139] offset:55296
	v_mfma_f32_32x32x16_bf16 v[20:35], v[202:205], v[222:225], v[20:35]
	s_waitcnt vmcnt(21)
	ds_write_b128 v190, v[140:143] offset:18432
	v_mfma_f32_32x32x16_bf16 v[4:19], v[202:205], v[206:209], v[4:19]
	s_waitcnt vmcnt(20)
	ds_write_b128 v190, v[198:201] offset:55296
	s_waitcnt lgkmcnt(4)
	v_mfma_f32_32x32x16_bf16 v[52:67], v[214:217], v[226:229], v[52:67]
	s_waitcnt vmcnt(19)
	ds_write_b128 v191, v[174:177] offset:18432
	v_mfma_f32_32x32x16_bf16 v[36:51], v[214:217], v[230:233], v[36:51]
	s_waitcnt vmcnt(18)
	ds_write_b128 v191, v[178:181] offset:55296
	v_mfma_f32_32x32x16_bf16 v[20:35], v[218:221], v[226:229], v[20:35]
	s_waitcnt vmcnt(17)
	ds_write_b128 v192, v[242:245] offset:18432
	v_mfma_f32_32x32x16_bf16 v[4:19], v[218:221], v[230:233], v[4:19]
	s_waitcnt vmcnt(16)
	ds_write_b128 v192, v[246:249] offset:55296
	s_waitcnt lgkmcnt(0)
	s_barrier
	ds_read_b128 v[202:205], v196
	ds_read_b128 v[206:209], v196 offset:32
	ds_read_b128 v[210:213], v196 offset:4608
	ds_read_b128 v[214:217], v196 offset:4640
	ds_read_b128 v[218:221], v197 offset:36864
	ds_read_b128 v[222:225], v197 offset:36896
	ds_read_b128 v[226:229], v197 offset:41472
	ds_read_b128 v[230:233], v197 offset:41504
	s_waitcnt lgkmcnt(3)
	v_mfma_f32_32x32x16_bf16 v[52:67], v[202:205], v[218:221], v[52:67]
	global_load_dwordx4 v[132:135], v[164:165], off offset:1792
	s_waitcnt lgkmcnt(1)
	v_mfma_f32_32x32x16_bf16 v[36:51], v[202:205], v[226:229], v[36:51]
	global_load_dwordx4 v[136:139], v[162:163], off offset:1792
	v_mfma_f32_32x32x16_bf16 v[4:19], v[210:213], v[226:229], v[4:19]
	global_load_dwordx4 v[140:143], v[160:161], off offset:1792
	s_waitcnt lgkmcnt(0)
	v_mfma_f32_32x32x16_bf16 v[36:51], v[206:209], v[230:233], v[36:51]
	global_load_dwordx4 v[198:201], v[158:159], off offset:1792
	v_mfma_f32_32x32x16_bf16 v[4:19], v[214:217], v[230:233], v[4:19]
	global_load_dwordx4 v[174:177], v[156:157], off offset:1792
	ds_read_b128 v[230:233], v197 offset:41568
	ds_read_b128 v[202:205], v196 offset:4672
	v_mfma_f32_32x32x16_bf16 v[20:35], v[210:213], v[218:221], v[20:35]
	global_load_dwordx4 v[178:181], v[154:155], off offset:1792
	ds_read_b128 v[218:221], v196 offset:4704
	ds_read_b128 v[210:213], v196 offset:64
	v_mfma_f32_32x32x16_bf16 v[52:67], v[206:209], v[222:225], v[52:67]
	global_load_dwordx4 v[242:245], v[152:153], off offset:1792
	ds_read_b128 v[226:229], v197 offset:36960
	ds_read_b128 v[206:209], v197 offset:41536
	v_mfma_f32_32x32x16_bf16 v[20:35], v[214:217], v[222:225], v[20:35]
	global_load_dwordx4 v[246:249], v[146:147], off offset:1792
	ds_read_b128 v[222:225], v197 offset:36928
	ds_read_b128 v[214:217], v196 offset:96
	s_waitcnt lgkmcnt(1)
	v_mfma_f32_32x32x16_bf16 v[52:67], v[210:213], v[222:225], v[52:67]
	s_waitcnt vmcnt(23)
	ds_write_b128 v167, v[68:71]
	v_mfma_f32_32x32x16_bf16 v[36:51], v[210:213], v[206:209], v[36:51]
	s_waitcnt vmcnt(22)
	ds_write_b128 v167, v[72:75] offset:36864
	v_mfma_f32_32x32x16_bf16 v[20:35], v[202:205], v[222:225], v[20:35]
	s_waitcnt vmcnt(21)
	ds_write_b128 v190, v[76:79]
	v_mfma_f32_32x32x16_bf16 v[4:19], v[202:205], v[206:209], v[4:19]
	s_waitcnt vmcnt(20)
	ds_write_b128 v190, v[80:83] offset:36864
	s_waitcnt lgkmcnt(4)
	v_mfma_f32_32x32x16_bf16 v[52:67], v[214:217], v[226:229], v[52:67]
	s_waitcnt vmcnt(19)
	ds_write_b128 v191, v[84:87]
	v_mfma_f32_32x32x16_bf16 v[36:51], v[214:217], v[230:233], v[36:51]
	s_waitcnt vmcnt(18)
	ds_write_b128 v191, v[88:91] offset:36864
	v_mfma_f32_32x32x16_bf16 v[20:35], v[218:221], v[226:229], v[20:35]
	s_waitcnt vmcnt(17)
	ds_write_b128 v192, v[92:95]
	v_mfma_f32_32x32x16_bf16 v[4:19], v[218:221], v[230:233], v[4:19]
	s_waitcnt vmcnt(16)
	ds_write_b128 v192, v[104:107] offset:36864
	s_waitcnt lgkmcnt(0)
	s_barrier
; #define MFMA(a, b, c) __builtin_amdgcn_mfma_f32_32x32x16_bf16((a), (b), (c), 0, 0, 0)
; template <class Epi, class ColV>
; DI void gemm_tile(const bf16_t* __restrict__ A, int lda, const bf16_t* __restrict__ Bt, int ldb, int K, int m0, int n0, unsigned char* smem, Epi epi, ColV colv, const bf16_t* __restrict__ HYT = nullptr) {
;     ...
;     auto step = [&](int kt, u32x4 (&ldset)[8], const u32x4 (&stset)[8]) {
;         const int buf = kt & 1;
;         if (kt + 2 < nk) gload(ldset, kt + 2);
;         const bf16_t* Ab = As + (buf * 128 + 64 * wr + li) * LS + 8 * lh;
;         const bf16_t* Bb = Bs + (buf * 128 + 64 * wc + li) * LS + 8 * lh;
;         bf16x8 fa[2][2], fb[2][2], ga[2][2], gb[2][2];
; #pragma unroll
;         for (int k2 = 0; k2 < 2; ++k2) { fa[k2][0] = ld8(Ab + 16 * k2); fa[k2][1] = ld8(Ab + 32 * LS + 16 * k2); fb[k2][0] = ld8(Bb + 16 * k2); fb[k2][1] = ld8(Bb + 32 * LS + 16 * k2); }
;         __builtin_amdgcn_sched_barrier(0);
; #pragma unroll
;         for (int k2 = 0; k2 < 2; ++k2) {
;             acc[0][0] = MFMA(fa[k2][0], fb[k2][0], acc[0][0]); acc[0][1] = MFMA(fa[k2][0], fb[k2][1], acc[0][1]);
;             acc[1][0] = MFMA(fa[k2][1], fb[k2][0], acc[1][0]); acc[1][1] = MFMA(fa[k2][1], fb[k2][1], acc[1][1]);
;         }
; #pragma unroll
;         for (int k2 = 0; k2 < 2; ++k2) { const int ks = 2 + k2; ga[k2][0] = ld8(Ab + 16 * ks); ga[k2][1] = ld8(Ab + 32 * LS + 16 * ks); gb[k2][0] = ld8(Bb + 16 * ks); gb[k2][1] = ld8(Bb + 32 * LS + 16 * ks); }
; #pragma unroll
;         for (int k2 = 0; k2 < 2; ++k2) {
;             acc[0][0] = MFMA(ga[k2][0], gb[k2][0], acc[0][0]); acc[0][1] = MFMA(ga[k2][0], gb[k2][1], acc[0][1]);
;             acc[1][0] = MFMA(ga[k2][1], gb[k2][0], acc[1][0]); acc[1][1] = MFMA(ga[k2][1], gb[k2][1], acc[1][1]);
;         }
;         if (kt + 1 < nk) sstore(stset, buf ^ 1, kt + 1);
; #pragma unroll
;         for (int i = 0; i < 8; ++i) { __builtin_amdgcn_sched_group_barrier(0x008, 1, 0); __builtin_amdgcn_sched_group_barrier(0x100, 1, 0); }
; #pragma unroll
;         for (int i = 0; i < 8; ++i) { __builtin_amdgcn_sched_group_barrier(0x008, 1, 0); __builtin_amdgcn_sched_group_barrier(0x200, 1, 0); }
;         __builtin_amdgcn_sched_barrier(0);
;         __syncthreads();
;     };
	ds_read_b128 v[202:205], v194
	ds_read_b128 v[206:209], v194 offset:32
	ds_read_b128 v[210:213], v194 offset:4608
	ds_read_b128 v[214:217], v194 offset:4640
	ds_read_b128 v[218:221], v195 offset:36864
	ds_read_b128 v[222:225], v195 offset:36896
	ds_read_b128 v[226:229], v195 offset:41472
	ds_read_b128 v[230:233], v195 offset:41504
	s_waitcnt lgkmcnt(3)
	v_mfma_f32_32x32x16_bf16 v[52:67], v[202:205], v[218:221], v[52:67]
	global_load_dwordx4 v[68:71], v[164:165], off offset:1920
	s_waitcnt lgkmcnt(1)
	v_mfma_f32_32x32x16_bf16 v[36:51], v[202:205], v[226:229], v[36:51]
	global_load_dwordx4 v[72:75], v[162:163], off offset:1920
	v_mfma_f32_32x32x16_bf16 v[4:19], v[210:213], v[226:229], v[4:19]
	global_load_dwordx4 v[76:79], v[160:161], off offset:1920
	s_waitcnt lgkmcnt(0)
	v_mfma_f32_32x32x16_bf16 v[36:51], v[206:209], v[230:233], v[36:51]
	global_load_dwordx4 v[80:83], v[158:159], off offset:1920
	v_mfma_f32_32x32x16_bf16 v[4:19], v[214:217], v[230:233], v[4:19]
	global_load_dwordx4 v[84:87], v[156:157], off offset:1920
	ds_read_b128 v[230:233], v195 offset:41568
	ds_read_b128 v[202:205], v194 offset:4672
	v_mfma_f32_32x32x16_bf16 v[20:35], v[210:213], v[218:221], v[20:35]
	global_load_dwordx4 v[88:91], v[154:155], off offset:1920
	ds_read_b128 v[218:221], v194 offset:4704
	ds_read_b128 v[210:213], v194 offset:64
	v_mfma_f32_32x32x16_bf16 v[52:67], v[206:209], v[222:225], v[52:67]
	global_load_dwordx4 v[92:95], v[152:153], off offset:1920
	ds_read_b128 v[226:229], v195 offset:36960
	ds_read_b128 v[206:209], v195 offset:41536
	v_mfma_f32_32x32x16_bf16 v[20:35], v[214:217], v[222:225], v[20:35]
	global_load_dwordx4 v[104:107], v[146:147], off offset:1920
	ds_read_b128 v[222:225], v195 offset:36928
	ds_read_b128 v[214:217], v194 offset:96
	s_waitcnt lgkmcnt(1)
	v_mfma_f32_32x32x16_bf16 v[52:67], v[210:213], v[222:225], v[52:67]
	s_waitcnt vmcnt(23)
	ds_write_b128 v167, v[96:99] offset:18432
	v_mfma_f32_32x32x16_bf16 v[36:51], v[210:213], v[206:209], v[36:51]
	s_waitcnt vmcnt(22)
	ds_write_b128 v167, v[100:103] offset:55296
	v_mfma_f32_32x32x16_bf16 v[20:35], v[202:205], v[222:225], v[20:35]
	s_waitcnt vmcnt(21)
	ds_write_b128 v190, v[108:111] offset:18432
	v_mfma_f32_32x32x16_bf16 v[4:19], v[202:205], v[206:209], v[4:19]
	s_waitcnt vmcnt(20)
	ds_write_b128 v190, v[112:115] offset:55296
	s_waitcnt lgkmcnt(4)
	v_mfma_f32_32x32x16_bf16 v[52:67], v[214:217], v[226:229], v[52:67]
	s_waitcnt vmcnt(19)
	ds_write_b128 v191, v[116:119] offset:18432
	v_mfma_f32_32x32x16_bf16 v[36:51], v[214:217], v[230:233], v[36:51]
	s_waitcnt vmcnt(18)
	ds_write_b128 v191, v[120:123] offset:55296
	v_mfma_f32_32x32x16_bf16 v[20:35], v[218:221], v[226:229], v[20:35]
	s_waitcnt vmcnt(17)
	ds_write_b128 v192, v[124:127] offset:18432
	v_mfma_f32_32x32x16_bf16 v[4:19], v[218:221], v[230:233], v[4:19]
	s_waitcnt vmcnt(16)
	ds_write_b128 v192, v[128:131] offset:55296
	s_waitcnt lgkmcnt(0)
	s_barrier
	ds_read_b128 v[202:205], v196
	ds_read_b128 v[206:209], v196 offset:32
	ds_read_b128 v[210:213], v196 offset:4608
	ds_read_b128 v[214:217], v196 offset:4640
	ds_read_b128 v[218:221], v197 offset:36864
	ds_read_b128 v[222:225], v197 offset:36896
	ds_read_b128 v[226:229], v197 offset:41472
	ds_read_b128 v[230:233], v197 offset:41504
	s_waitcnt lgkmcnt(3)
	v_mfma_f32_32x32x16_bf16 v[52:67], v[202:205], v[218:221], v[52:67]
	s_waitcnt lgkmcnt(1)
	v_mfma_f32_32x32x16_bf16 v[36:51], v[202:205], v[226:229], v[36:51]
	v_mfma_f32_32x32x16_bf16 v[4:19], v[210:213], v[226:229], v[4:19]
	s_waitcnt lgkmcnt(0)
	v_mfma_f32_32x32x16_bf16 v[36:51], v[206:209], v[230:233], v[36:51]
	v_mfma_f32_32x32x16_bf16 v[4:19], v[214:217], v[230:233], v[4:19]
	ds_read_b128 v[230:233], v197 offset:41568
	ds_read_b128 v[202:205], v196 offset:4672
	v_mfma_f32_32x32x16_bf16 v[20:35], v[210:213], v[218:221], v[20:35]
	ds_read_b128 v[218:221], v196 offset:4704
	ds_read_b128 v[210:213], v196 offset:64
	v_mfma_f32_32x32x16_bf16 v[52:67], v[206:209], v[222:225], v[52:67]
	ds_read_b128 v[226:229], v197 offset:36960
	ds_read_b128 v[206:209], v197 offset:41536
	v_mfma_f32_32x32x16_bf16 v[20:35], v[214:217], v[222:225], v[20:35]
	ds_read_b128 v[222:225], v197 offset:36928
	ds_read_b128 v[214:217], v196 offset:96
	s_waitcnt lgkmcnt(1)
	v_mfma_f32_32x32x16_bf16 v[52:67], v[210:213], v[222:225], v[52:67]
	s_waitcnt vmcnt(15)
	ds_write_b128 v167, v[132:135]
	v_mfma_f32_32x32x16_bf16 v[36:51], v[210:213], v[206:209], v[36:51]
	s_waitcnt vmcnt(14)
	ds_write_b128 v167, v[136:139] offset:36864
	v_mfma_f32_32x32x16_bf16 v[20:35], v[202:205], v[222:225], v[20:35]
	s_waitcnt vmcnt(13)
	ds_write_b128 v190, v[140:143]
	v_mfma_f32_32x32x16_bf16 v[4:19], v[202:205], v[206:209], v[4:19]
	s_waitcnt vmcnt(12)
	ds_write_b128 v190, v[198:201] offset:36864
	s_waitcnt lgkmcnt(4)
	v_mfma_f32_32x32x16_bf16 v[52:67], v[214:217], v[226:229], v[52:67]
	s_waitcnt vmcnt(11)
	ds_write_b128 v191, v[174:177]
	v_mfma_f32_32x32x16_bf16 v[36:51], v[214:217], v[230:233], v[36:51]
	s_waitcnt vmcnt(10)
	ds_write_b128 v191, v[178:181] offset:36864
	v_mfma_f32_32x32x16_bf16 v[20:35], v[218:221], v[226:229], v[20:35]
	s_waitcnt vmcnt(9)
	ds_write_b128 v192, v[242:245]
	v_mfma_f32_32x32x16_bf16 v[4:19], v[218:221], v[230:233], v[4:19]
	s_waitcnt vmcnt(8)
	ds_write_b128 v192, v[246:249] offset:36864
	s_waitcnt lgkmcnt(0)
	s_barrier
; template <class Epi, class ColV>
; DI void gemm_tile(const bf16_t* __restrict__ A, int lda, const bf16_t* __restrict__ Bt, int ldb, int K, int m0, int n0, unsigned char* smem, Epi epi, ColV colv, const bf16_t* __restrict__ HYT = nullptr) {
;     ...
;         if (kt + 1 < nk) sstore(stset, buf ^ 1, kt + 1);
; #pragma unroll
;         for (int i = 0; i < 8; ++i) { __builtin_amdgcn_sched_group_barrier(0x008, 1, 0); __builtin_amdgcn_sched_group_barrier(0x100, 1, 0); }
; #pragma unroll
;         for (int i = 0; i < 8; ++i) { __builtin_amdgcn_sched_group_barrier(0x008, 1, 0); __builtin_amdgcn_sched_group_barrier(0x200, 1, 0); }
;         __builtin_amdgcn_sched_barrier(0);
;         __syncthreads();
;     };
;     gload(R0, 0); gload(R1, 1);
;     sstore(R0, 0, 0); __syncthreads();
;     for (int kt = 0; kt < nk; kt += 2) {
;         step(kt, R0, R1);
;         if (kt + 1 < nk) step(kt + 1, R1, R0);
;     }
	ds_read_b128 v[202:205], v194
	ds_read_b128 v[206:209], v194 offset:32
	ds_read_b128 v[210:213], v194 offset:4608
	ds_read_b128 v[214:217], v194 offset:4640
	ds_read_b128 v[218:221], v195 offset:36864
	ds_read_b128 v[222:225], v195 offset:36896
	ds_read_b128 v[226:229], v195 offset:41472
	ds_read_b128 v[230:233], v195 offset:41504
	s_waitcnt lgkmcnt(3)
	v_mfma_f32_32x32x16_bf16 v[52:67], v[202:205], v[218:221], v[52:67]
	s_waitcnt lgkmcnt(1)
	v_mfma_f32_32x32x16_bf16 v[36:51], v[202:205], v[226:229], v[36:51]
	v_mfma_f32_32x32x16_bf16 v[4:19], v[210:213], v[226:229], v[4:19]
	s_waitcnt lgkmcnt(0)
	v_mfma_f32_32x32x16_bf16 v[36:51], v[206:209], v[230:233], v[36:51]
	v_mfma_f32_32x32x16_bf16 v[4:19], v[214:217], v[230:233], v[4:19]
	ds_read_b128 v[230:233], v195 offset:41568
	ds_read_b128 v[202:205], v194 offset:4672
	v_mfma_f32_32x32x16_bf16 v[20:35], v[210:213], v[218:221], v[20:35]
	ds_read_b128 v[218:221], v194 offset:4704
	ds_read_b128 v[210:213], v194 offset:64
	v_mfma_f32_32x32x16_bf16 v[52:67], v[206:209], v[222:225], v[52:67]
	ds_read_b128 v[226:229], v195 offset:36960
	ds_read_b128 v[206:209], v195 offset:41536
	v_mfma_f32_32x32x16_bf16 v[20:35], v[214:217], v[222:225], v[20:35]
	ds_read_b128 v[222:225], v195 offset:36928
	ds_read_b128 v[214:217], v194 offset:96
	s_waitcnt lgkmcnt(1)
	v_mfma_f32_32x32x16_bf16 v[52:67], v[210:213], v[222:225], v[52:67]
	s_waitcnt vmcnt(7)
	ds_write_b128 v167, v[68:71] offset:18432
	v_mfma_f32_32x32x16_bf16 v[36:51], v[210:213], v[206:209], v[36:51]
	s_waitcnt vmcnt(6)
	ds_write_b128 v167, v[72:75] offset:55296
	v_mfma_f32_32x32x16_bf16 v[20:35], v[202:205], v[222:225], v[20:35]
	s_waitcnt vmcnt(5)
	ds_write_b128 v190, v[76:79] offset:18432
	v_mfma_f32_32x32x16_bf16 v[4:19], v[202:205], v[206:209], v[4:19]
	s_waitcnt vmcnt(4)
	ds_write_b128 v190, v[80:83] offset:55296
	s_waitcnt lgkmcnt(4)
	v_mfma_f32_32x32x16_bf16 v[52:67], v[214:217], v[226:229], v[52:67]
	s_waitcnt vmcnt(3)
	ds_write_b128 v191, v[84:87] offset:18432
	v_mfma_f32_32x32x16_bf16 v[36:51], v[214:217], v[230:233], v[36:51]
	s_waitcnt vmcnt(2)
	ds_write_b128 v191, v[88:91] offset:55296
	v_mfma_f32_32x32x16_bf16 v[20:35], v[218:221], v[226:229], v[20:35]
	s_waitcnt vmcnt(1)
	ds_write_b128 v192, v[92:95] offset:18432
	v_mfma_f32_32x32x16_bf16 v[4:19], v[218:221], v[230:233], v[4:19]
	s_waitcnt vmcnt(0)
	ds_write_b128 v192, v[104:107] offset:55296
	s_waitcnt lgkmcnt(0)
	s_barrier
	ds_read_b128 v[202:205], v196
	ds_read_b128 v[206:209], v196 offset:32
	ds_read_b128 v[210:213], v196 offset:4608
	ds_read_b128 v[214:217], v196 offset:4640
	ds_read_b128 v[218:221], v197 offset:36864
	ds_read_b128 v[222:225], v197 offset:36896
	ds_read_b128 v[226:229], v197 offset:41472
	ds_read_b128 v[230:233], v197 offset:41504
	s_waitcnt lgkmcnt(3)
	v_mfma_f32_32x32x16_bf16 v[52:67], v[202:205], v[218:221], v[52:67]
	s_waitcnt lgkmcnt(1)
	v_mfma_f32_32x32x16_bf16 v[36:51], v[202:205], v[226:229], v[36:51]
	v_mfma_f32_32x32x16_bf16 v[4:19], v[210:213], v[226:229], v[4:19]
	s_waitcnt lgkmcnt(0)
	v_mfma_f32_32x32x16_bf16 v[36:51], v[206:209], v[230:233], v[36:51]
	v_mfma_f32_32x32x16_bf16 v[4:19], v[214:217], v[230:233], v[4:19]
	ds_read_b128 v[230:233], v197 offset:41568
	ds_read_b128 v[202:205], v196 offset:4672
	v_mfma_f32_32x32x16_bf16 v[20:35], v[210:213], v[218:221], v[20:35]
	ds_read_b128 v[218:221], v196 offset:4704
	ds_read_b128 v[210:213], v196 offset:64
	v_mfma_f32_32x32x16_bf16 v[52:67], v[206:209], v[222:225], v[52:67]
	ds_read_b128 v[226:229], v197 offset:36960
	ds_read_b128 v[206:209], v197 offset:41536
	v_mfma_f32_32x32x16_bf16 v[20:35], v[214:217], v[222:225], v[20:35]
	ds_read_b128 v[222:225], v197 offset:36928
	ds_read_b128 v[214:217], v196 offset:96
	s_waitcnt lgkmcnt(1)
	v_mfma_f32_32x32x16_bf16 v[52:67], v[210:213], v[222:225], v[52:67]
	v_mfma_f32_32x32x16_bf16 v[36:51], v[210:213], v[206:209], v[36:51]
	v_mfma_f32_32x32x16_bf16 v[20:35], v[202:205], v[222:225], v[20:35]
	v_mfma_f32_32x32x16_bf16 v[4:19], v[202:205], v[206:209], v[4:19]
	s_waitcnt lgkmcnt(0)
	v_mfma_f32_32x32x16_bf16 v[52:67], v[214:217], v[226:229], v[52:67]
	v_mfma_f32_32x32x16_bf16 v[36:51], v[214:217], v[230:233], v[36:51]
	v_mfma_f32_32x32x16_bf16 v[20:35], v[218:221], v[226:229], v[20:35]
	v_mfma_f32_32x32x16_bf16 v[4:19], v[218:221], v[230:233], v[4:19]
	s_waitcnt lgkmcnt(0)
	s_barrier
	s_nop 7
	s_nop 3
	s_branch .LBB0_1555
